# hand-written row phases: 3-buffer row pipeline (loads never queue behind stores), x1 no longer stored after the mixer (recomputed bit-identically in the FFN row phase from T1), T2 in the upper half of
# speedup vs baseline: 1.0356x; 1.0356x over previous
; DI int obid() { int b = blockIdx.x; asm volatile("" : "+s"(b)); return b; }
; __global__ void __launch_bounds__(NTHREADS) fwd_kernel(Params p) {
;     ...
;         if (ph < NPRE) {
;             prep_phase(q, lds);
;         } else {
;             const int L = (ph - NPRE) / NST, st = (int)((SEQ64 >> (4 * ((ph - NPRE) % NST))) & 15ull), j = L >> 1;
;             const float* gains = q.norm_gains + (size_t)L * 4 * DM;
;             const bf16_t* HB = (const bf16_t*)(ws + OFF_HB);
;             switch (st) {
;             case 0:
;                 if ((L & 1) == 0) gemm_phase<EPI_ATT_IN>(HB, (const bf16_t*)(ws + OFF_ATT_IN_T) + (size_t)j * ATT_IN * DM, DM, ATT_IN, q, j, lds);
;                 else gemm_phase<EPI_REC_IN>(HB, (const bf16_t*)(ws + OFF_REC_IN_T) + (size_t)j * REC_IN * DM, DM, REC_IN, q, j, lds);
;                 break;
;             case 1:
;                 if ((L & 1) == 0) attn_phase(q, j, lds, ph); else { hgrn_pass<false>(q, j, lds); XBAR(); hgrn_pass<true>(q, j, lds); }
;                 break;
;             case 2: case 5: {
;                 const bf16_t* Ap = (st == 2) ? HB : (const bf16_t*)(ws + OFF_P);
;                 const bf16_t* Bp = (st == 2) ? (((L & 1) == 0) ? (const bf16_t*)(ws + OFF_ATT_OUT_T) + (size_t)j * DM * DM : (const bf16_t*)(ws + OFF_REC_OUT_T) + (size_t)j * DM * DM)
;                                              : (const bf16_t*)(ws + OFF_FFN_OUT_T) + (size_t)L * DM * FFN_H;
;                 gemm_phase<EPI_F32>(Ap, Bp, (st == 2) ? DM : FFN_H, DM, q, j, lds);
;                 break; }
;             case 3:
;                 row_phase((const bf16_t*)(ws + OFF_T), L == 0 ? q.x : q.out, q.out, gains + DM, gains + 2 * DM, (bf16_t*)(ws + OFF_HB), q.wave);
;                 break;
;             case 4:
;                 gemm_phase<EPI_FFN_IN>(HB, (const bf16_t*)(ws + OFF_FFN_IN_T) + (size_t)L * FFN_IN * DM, DM, FFN_IN, q, j, lds);
;                 if (L < 3) { const int rem_ = ((M_TOK / 256) * (FFN_IN / 256)) % ogrid();
;                     if (obid() >= rem_) convert_layer_weights(q, L + 1, obid() - rem_, ogrid() - rem_, lds, 2); }
;                 break;
;             default:
;                 row_phase((const bf16_t*)(ws + OFF_T), q.out, q.out, gains + 3 * DM, L < 3 ? gains + 4 * DM : nullptr, L < 3 ? (bf16_t*)(ws + OFF_HB) : nullptr, q.wave);
;                 break;
.LBB0_16:
	s_mov_b32 s4, s36
	v_writelane_b32 v255, s4, 4
	s_mov_b32 s7, s89
	s_mov_b64 s[34:35], 0
	v_writelane_b32 v255, s5, 5
	s_add_i32 s4, s36, -1
	s_mul_hi_u32 s5, s4, 0x24924925
	s_sub_i32 s6, s4, s5
	s_lshr_b32 s6, s6, 1
	s_add_i32 s31, s6, s5
	s_lshr_b32 s6, s31, 2
	s_mul_i32 s5, s6, 7
	s_sub_i32 s4, s4, s5
	s_lshl_b32 s4, s4, 2
	s_lshr_b32 s4, 0x6543210, s4
	s_and_b32 s36, s4, 7
	v_writelane_b32 v255, s6, 6
	s_add_u32 s82, s68, 0x6681000
	s_addc_u32 s83, s69, 0
	v_writelane_b32 v255, s7, 7
	s_mov_b64 s[6:7], 0
	v_writelane_b32 v255, s6, 8
	s_mov_b64 s[4:5], -1
	s_cmp_lt_i32 s36, 3
	v_writelane_b32 v255, s7, 9
	s_movk_i32 s28, 0x2000
	s_movk_i32 s29, 0x3000
	s_cbranch_scc1 .LBB0_27
	v_readlane_b32 s4, v255, 6
	v_readlane_b32 s5, v255, 7
	s_lshl_b64 s[4:5], s[4:5], 14
	v_readlane_b32 s6, v255, 0
	v_readlane_b32 s7, v255, 1
	s_add_u32 s4, s6, s4
	s_addc_u32 s5, s7, s5
	v_writelane_b32 v255, s4, 10
	s_cmp_gt_i32 s36, 3
	s_nop 0
	v_writelane_b32 v255, s5, 11
	s_cbranch_scc0 .LBB0_25
	s_cmp_gt_i32 s36, 4
	s_cbranch_scc0 .LBB0_31
	s_cmp_lg_u32 s36, 5
	s_mov_b64 s[34:35], -1
	s_cbranch_scc0 .LBB0_33
	v_readlane_b32 s4, v255, 6
	s_nop 3
	s_cmp_eq_u32 s4, 3
	s_cbranch_scc1 .Lrow_r2
	s_branch .Lrow_r2h

; DI int obid() { int b = blockIdx.x; asm volatile("" : "+s"(b)); return b; }
; DI int ogrid() { int g = gridDim.x; asm volatile("" : "+s"(g)); return g; }
; DI int otid_w(int gw) { return (gw << 6) | olane(); }
; DI float shx(float v, int mask) { const int l = olane(); return __builtin_bit_cast(float, __builtin_amdgcn_ds_bpermute(((l ^ mask) & 63) << 2, __builtin_bit_cast(int, v))); }
; DI void row_phase(const bf16_t* msrc, const float* xsrc, float* xdst, const float* g_post, const float* g_next, bf16_t* hdst, const int gw) {
;     ...
;     const int tid = otid_w(gw); const int lane = tid & 63, w = tid >> 6;
;     const int wg = obid() * 8 + w, nw = ogrid() * 8;
;     for (int rowb = wg * RB; rowb < M_TOK; rowb += nw * RB) {
;         f32x4 xv[RB][4], mv[RB][4];
; #pragma unroll
;         for (int r = 0; r < RB; ++r)
; #pragma unroll
;             for (int j = 0; j < 4; ++j) xv[r][j] = *(const f32x4*)(xsrc + (size_t)(rowb + r) * DM + lane * 4 + 256 * j);
;         if (msrc) {
; #pragma unroll
;             for (int r = 0; r < RB; ++r)
; #pragma unroll
;                 for (int j = 0; j < 4; ++j) { const u32x2 mw = *(const u32x2*)(msrc + (size_t)(rowb + r) * DM + lane * 4 + 256 * j);
;                     mv[r][j] = (f32x4){__uint_as_float(mw[0] << 16), __uint_as_float(mw[0] & 0xffff0000u), __uint_as_float(mw[1] << 16), __uint_as_float(mw[1] & 0xffff0000u)}; }
;             float ss[RB];
; #pragma unroll
;             for (int r = 0; r < RB; ++r) { ss[r] = 0.f;
; #pragma unroll
;                 for (int j = 0; j < 4; ++j) ss[r] += mv[r][j][0] * mv[r][j][0] + mv[r][j][1] * mv[r][j][1] + mv[r][j][2] * mv[r][j][2] + mv[r][j][3] * mv[r][j][3]; }
; #pragma unroll
;             for (int o = 32; o >= 1; o >>= 1)
; #pragma unroll
;                 for (int r = 0; r < RB; ++r) ss[r] += shx(ss[r], o);
; #pragma unroll
;             for (int j = 0; j < 4; ++j) { const f32x4 g = *(const f32x4*)(g_post + lane * 4 + 256 * j);
; #pragma unroll
;                 for (int r = 0; r < RB; ++r) { const float r1 = rsqrtf(ss[r] * (1.f / DM) + EPS); xv[r][j] = xv[r][j] + mv[r][j] * r1 * g; *(f32x4*)(xdst + (size_t)(rowb + r) * DM + lane * 4 + 256 * j) = xv[r][j]; } }
.Lrow_r1:
	v_writelane_b32 v3, s4, 0
	v_writelane_b32 v3, s5, 1
	v_writelane_b32 v3, s6, 2
	v_writelane_b32 v3, s7, 3
	v_writelane_b32 v3, s8, 4
	v_writelane_b32 v3, s9, 5
	v_writelane_b32 v3, s10, 6
	v_writelane_b32 v3, s11, 7
	v_writelane_b32 v3, s12, 8
	v_writelane_b32 v3, s13, 9
	v_writelane_b32 v3, s14, 10
	v_writelane_b32 v3, s15, 11
	v_writelane_b32 v3, s16, 12
	v_writelane_b32 v3, s17, 13
	v_writelane_b32 v3, s18, 14
	v_writelane_b32 v3, s19, 15
	v_writelane_b32 v3, s20, 16
	v_writelane_b32 v3, s21, 17
	v_writelane_b32 v3, s22, 18
	v_writelane_b32 v3, s23, 19
	v_writelane_b32 v3, s24, 20
	v_writelane_b32 v3, s25, 21
	s_waitcnt vmcnt(0) lgkmcnt(0)
	v_mbcnt_lo_u32_b32 v0, -1, 0
	v_mbcnt_hi_u32_b32 v0, -1, v0
	v_lshlrev_b32_e32 v1, 5, v0
	v_lshlrev_b32_e32 v2, 4, v0
	s_lshr_b32 s4, s71, 6
	s_lshl_b32 s5, s2, 3
	s_add_i32 s5, s5, s4
	s_lshl_b32 s24, s5, 15
	s_lshl_b32 s25, s5, 14
	v_readlane_b32 s8, v254, 62
	v_readlane_b32 s9, v254, 63
	v_readlane_b32 s6, v255, 2
	v_readlane_b32 s7, v255, 3
	v_readlane_b32 s4, v255, 6
	v_readlane_b32 s16, v255, 10
	v_readlane_b32 s17, v255, 11
	s_nop 1
	s_cmp_eq_u32 s4, 0
	s_cselect_b32 s6, s6, s8
	s_cselect_b32 s7, s7, s9
	s_add_u32 s6, s6, s24
	s_addc_u32 s7, s7, 0
	s_add_u32 s8, s8, s24
	s_addc_u32 s9, s9, 0
	s_add_u32 s10, s68, 0x10681000
	s_addc_u32 s11, s69, 0
	s_add_u32 s10, s10, s25
	s_addc_u32 s11, s11, 0
	s_add_u32 s12, s10, 0x2000000
	s_addc_u32 s13, s11, 0
	s_add_u32 s14, s82, s25
	s_addc_u32 s15, s83, 0
	s_add_u32 s18, s16, 0x1000
	s_addc_u32 s19, s17, 0
	global_load_dwordx4 v[40:43], v1, s[18:19] offset:0
	global_load_dwordx4 v[44:47], v1, s[18:19] offset:16
	global_load_dwordx4 v[48:51], v1, s[18:19] offset:2048
	global_load_dwordx4 v[52:55], v1, s[18:19] offset:2064
	s_add_u32 s18, s16, 0x2000
	s_addc_u32 s19, s17, 0
	global_load_dwordx4 v[56:59], v1, s[18:19] offset:0
	global_load_dwordx4 v[60:63], v1, s[18:19] offset:16
	global_load_dwordx4 v[64:67], v1, s[18:19] offset:2048
	global_load_dwordx4 v[68:71], v1, s[18:19] offset:2064
	global_load_dwordx4 v[96:99], v1, s[6:7] offset:0
	global_load_dwordx4 v[100:103], v1, s[6:7] offset:16
	global_load_dwordx4 v[104:107], v1, s[6:7] offset:2048
	global_load_dwordx4 v[108:111], v1, s[6:7] offset:2064
	global_load_dwordx4 v[112:115], v2, s[10:11]
	global_load_dwordx4 v[116:119], v2, s[10:11] offset:1024
	s_add_u32 s6, s6, 0x1000
	s_addc_u32 s7, s7, 0
	s_add_u32 s10, s10, 0x800
	s_addc_u32 s11, s11, 0
	global_load_dwordx4 v[128:131], v1, s[6:7] offset:0
	global_load_dwordx4 v[132:135], v1, s[6:7] offset:16
	global_load_dwordx4 v[136:139], v1, s[6:7] offset:2048
	global_load_dwordx4 v[140:143], v1, s[6:7] offset:2064
	global_load_dwordx4 v[144:147], v2, s[10:11]
	global_load_dwordx4 v[148:151], v2, s[10:11] offset:1024
	s_add_u32 s6, s6, 0x1000
	s_addc_u32 s7, s7, 0
	s_add_u32 s10, s10, 0x800
	s_addc_u32 s11, s11, 0
	global_load_dwordx4 v[160:163], v1, s[6:7] offset:0
	global_load_dwordx4 v[164:167], v1, s[6:7] offset:16
	global_load_dwordx4 v[168:171], v1, s[6:7] offset:2048
	global_load_dwordx4 v[172:175], v1, s[6:7] offset:2064
	global_load_dwordx4 v[176:179], v2, s[10:11]
	global_load_dwordx4 v[180:183], v2, s[10:11] offset:1024
	s_add_u32 s6, s6, 0x1000
	s_addc_u32 s7, s7, 0
	s_add_u32 s10, s10, 0x800
	s_addc_u32 s11, s11, 0
	s_waitcnt vmcnt(12)
	v_lshlrev_b32_e32 v208, 16, v112
	v_and_b32_e32 v209, 0xffff0000, v112
	v_lshlrev_b32_e32 v210, 16, v113
	v_and_b32_e32 v211, 0xffff0000, v113
	v_lshlrev_b32_e32 v212, 16, v114
	v_and_b32_e32 v213, 0xffff0000, v114
	v_lshlrev_b32_e32 v214, 16, v115
	v_and_b32_e32 v215, 0xffff0000, v115
	v_lshlrev_b32_e32 v216, 16, v116
	v_and_b32_e32 v217, 0xffff0000, v116
	v_lshlrev_b32_e32 v218, 16, v117
	v_and_b32_e32 v219, 0xffff0000, v117
	v_lshlrev_b32_e32 v220, 16, v118
	v_and_b32_e32 v221, 0xffff0000, v118
	v_lshlrev_b32_e32 v222, 16, v119
	v_and_b32_e32 v223, 0xffff0000, v119
	v_mul_f32_e32 v224, v208, v208
	v_fmac_f32_e32 v224, v209, v209
	v_fmac_f32_e32 v224, v210, v210
	v_fmac_f32_e32 v224, v211, v211
	v_fmac_f32_e32 v224, v212, v212
	v_fmac_f32_e32 v224, v213, v213
	v_fmac_f32_e32 v224, v214, v214
	v_fmac_f32_e32 v224, v215, v215
	v_fmac_f32_e32 v224, v216, v216
	v_fmac_f32_e32 v224, v217, v217
	v_fmac_f32_e32 v224, v218, v218
	v_fmac_f32_e32 v224, v219, v219
	v_fmac_f32_e32 v224, v220, v220
	v_fmac_f32_e32 v224, v221, v221
	v_fmac_f32_e32 v224, v222, v222
	v_fmac_f32_e32 v224, v223, v223
	s_nop 1
	v_add_f32_dpp v224, v224, v224 quad_perm:[1,0,3,2] row_mask:0xf bank_mask:0xf
	s_nop 1
	v_add_f32_dpp v224, v224, v224 quad_perm:[2,3,0,1] row_mask:0xf bank_mask:0xf
	s_nop 1
	v_add_f32_dpp v224, v224, v224 row_ror:4 row_mask:0xf bank_mask:0xf
	s_nop 1
	v_add_f32_dpp v224, v224, v224 row_ror:8 row_mask:0xf bank_mask:0xf
	s_nop 1
	v_readlane_b32 s20, v224, 0
	v_readlane_b32 s21, v224, 16
	v_readlane_b32 s22, v224, 32
	v_readlane_b32 s23, v224, 48
	s_nop 1
	v_mov_b32_e32 v225, s20
	v_add_f32_e32 v225, s21, v225
	v_add_f32_e32 v225, s22, v225
	v_add_f32_e32 v225, s23, v225
	v_mov_b32_e32 v226, 0x358637bd
	v_fmac_f32_e32 v226, 0x3a800000, v225
	v_rsq_f32_e32 v226, v226
	s_nop 0
	v_mul_f32_e32 v208, v208, v226
	v_mul_f32_e32 v209, v209, v226
	v_mul_f32_e32 v210, v210, v226
	v_mul_f32_e32 v211, v211, v226
	v_mul_f32_e32 v212, v212, v226
	v_mul_f32_e32 v213, v213, v226
	v_mul_f32_e32 v214, v214, v226
	v_mul_f32_e32 v215, v215, v226
	v_mul_f32_e32 v216, v216, v226
	v_mul_f32_e32 v217, v217, v226
	v_mul_f32_e32 v218, v218, v226
	v_mul_f32_e32 v219, v219, v226
	v_mul_f32_e32 v220, v220, v226
	v_mul_f32_e32 v221, v221, v226
	v_mul_f32_e32 v222, v222, v226
	v_mul_f32_e32 v223, v223, v226
	v_fmac_f32_e32 v96, v208, v40
; DI unsigned pk_bf16(float a, float b) { f32x2_t v = {a, b}; bf16x2_t r = __builtin_convertvector(v, bf16x2_t); return __builtin_bit_cast(unsigned, r); }
; DI float shx(float v, int mask) { const int l = olane(); return __builtin_bit_cast(float, __builtin_amdgcn_ds_bpermute(((l ^ mask) & 63) << 2, __builtin_bit_cast(int, v))); }
; DI void row_phase(const bf16_t* msrc, const float* xsrc, float* xdst, const float* g_post, const float* g_next, bf16_t* hdst, const int gw) {
;     ...
;                 for (int r = 0; r < RB; ++r) { const float r1 = rsqrtf(ss[r] * (1.f / DM) + EPS); xv[r][j] = xv[r][j] + mv[r][j] * r1 * g; *(f32x4*)(xdst + (size_t)(rowb + r) * DM + lane * 4 + 256 * j) = xv[r][j]; } }
;         }
;         if (hdst) {
;             float ss[RB];
; #pragma unroll
;             for (int r = 0; r < RB; ++r) { ss[r] = 0.f;
; #pragma unroll
;                 for (int j = 0; j < 4; ++j) ss[r] += xv[r][j][0] * xv[r][j][0] + xv[r][j][1] * xv[r][j][1] + xv[r][j][2] * xv[r][j][2] + xv[r][j][3] * xv[r][j][3]; }
; #pragma unroll
;             for (int o = 32; o >= 1; o >>= 1)
; #pragma unroll
;                 for (int r = 0; r < RB; ++r) ss[r] += shx(ss[r], o);
; #pragma unroll
;             for (int j = 0; j < 4; ++j) { const f32x4 g = *(const f32x4*)(g_next + lane * 4 + 256 * j);
; #pragma unroll
;                 for (int r = 0; r < RB; ++r) { const float r2 = rsqrtf(ss[r] * (1.f / DM) + EPS); const f32x4 hv = xv[r][j] * r2 * g;
;                     u32x2 o; o[0] = pk_bf16(hv[0], hv[1]); o[1] = pk_bf16(hv[2], hv[3]); *(u32x2*)(hdst + (size_t)(rowb + r) * DM + lane * 4 + 256 * j) = o; } }
	v_fmac_f32_e32 v97, v209, v41
	v_fmac_f32_e32 v98, v210, v42
	v_fmac_f32_e32 v99, v211, v43
	v_fmac_f32_e32 v100, v212, v44
	v_fmac_f32_e32 v101, v213, v45
	v_fmac_f32_e32 v102, v214, v46
	v_fmac_f32_e32 v103, v215, v47
	v_fmac_f32_e32 v104, v216, v48
	v_fmac_f32_e32 v105, v217, v49
	v_fmac_f32_e32 v106, v218, v50
	v_fmac_f32_e32 v107, v219, v51
	v_fmac_f32_e32 v108, v220, v52
	v_fmac_f32_e32 v109, v221, v53
	v_fmac_f32_e32 v110, v222, v54
	v_fmac_f32_e32 v111, v223, v55
	v_mul_f32_e32 v224, v96, v96
	v_fmac_f32_e32 v224, v97, v97
	v_fmac_f32_e32 v224, v98, v98
	v_fmac_f32_e32 v224, v99, v99
	v_fmac_f32_e32 v224, v100, v100
	v_fmac_f32_e32 v224, v101, v101
	v_fmac_f32_e32 v224, v102, v102
	v_fmac_f32_e32 v224, v103, v103
	v_fmac_f32_e32 v224, v104, v104
	v_fmac_f32_e32 v224, v105, v105
	v_fmac_f32_e32 v224, v106, v106
	v_fmac_f32_e32 v224, v107, v107
	v_fmac_f32_e32 v224, v108, v108
	v_fmac_f32_e32 v224, v109, v109
	v_fmac_f32_e32 v224, v110, v110
	v_fmac_f32_e32 v224, v111, v111
	s_nop 1
	v_add_f32_dpp v224, v224, v224 quad_perm:[1,0,3,2] row_mask:0xf bank_mask:0xf
	s_nop 1
	v_add_f32_dpp v224, v224, v224 quad_perm:[2,3,0,1] row_mask:0xf bank_mask:0xf
	s_nop 1
	v_add_f32_dpp v224, v224, v224 row_ror:4 row_mask:0xf bank_mask:0xf
	s_nop 1
	v_add_f32_dpp v224, v224, v224 row_ror:8 row_mask:0xf bank_mask:0xf
	s_nop 1
	v_readlane_b32 s20, v224, 0
	v_readlane_b32 s21, v224, 16
	v_readlane_b32 s22, v224, 32
	v_readlane_b32 s23, v224, 48
	s_nop 1
	v_mov_b32_e32 v225, s20
	v_add_f32_e32 v225, s21, v225
	v_add_f32_e32 v225, s22, v225
	v_add_f32_e32 v225, s23, v225
	v_mov_b32_e32 v226, 0x358637bd
	v_fmac_f32_e32 v226, 0x3a800000, v225
	v_rsq_f32_e32 v226, v226
	s_nop 0
	v_mul_f32_e32 v208, v96, v226
	v_mul_f32_e32 v209, v97, v226
	v_mul_f32_e32 v210, v98, v226
	v_mul_f32_e32 v211, v99, v226
	v_mul_f32_e32 v212, v100, v226
	v_mul_f32_e32 v213, v101, v226
	v_mul_f32_e32 v214, v102, v226
	v_mul_f32_e32 v215, v103, v226
	v_mul_f32_e32 v216, v104, v226
	v_mul_f32_e32 v217, v105, v226
	v_mul_f32_e32 v218, v106, v226
	v_mul_f32_e32 v219, v107, v226
	v_mul_f32_e32 v220, v108, v226
	v_mul_f32_e32 v221, v109, v226
	v_mul_f32_e32 v222, v110, v226
	v_mul_f32_e32 v223, v111, v226
	v_mul_f32_e32 v208, v208, v56
	v_mul_f32_e32 v209, v209, v57
	v_mul_f32_e32 v210, v210, v58
	v_mul_f32_e32 v211, v211, v59
	v_mul_f32_e32 v212, v212, v60
	v_mul_f32_e32 v213, v213, v61
	v_mul_f32_e32 v214, v214, v62
	v_mul_f32_e32 v215, v215, v63
	v_mul_f32_e32 v216, v216, v64
	v_mul_f32_e32 v217, v217, v65
	v_mul_f32_e32 v218, v218, v66
	v_mul_f32_e32 v219, v219, v67
	v_mul_f32_e32 v220, v220, v68
	v_mul_f32_e32 v221, v221, v69
	v_mul_f32_e32 v222, v222, v70
	v_mul_f32_e32 v223, v223, v71
	v_cvt_pk_bf16_f32 v112, v208, v209
	v_cvt_pk_bf16_f32 v113, v210, v211
	v_cvt_pk_bf16_f32 v114, v212, v213
	v_cvt_pk_bf16_f32 v115, v214, v215
	v_cvt_pk_bf16_f32 v116, v216, v217
	v_cvt_pk_bf16_f32 v117, v218, v219
	v_cvt_pk_bf16_f32 v118, v220, v221
	v_cvt_pk_bf16_f32 v119, v222, v223
	global_store_dwordx4 v2, v[112:115], s[14:15]
	global_store_dwordx4 v2, v[116:119], s[14:15] offset:1024
	s_add_u32 s14, s14, 0x800
	s_addc_u32 s15, s15, 0
	global_load_dwordx4 v[96:99], v1, s[6:7] offset:0
	global_load_dwordx4 v[100:103], v1, s[6:7] offset:16
	global_load_dwordx4 v[104:107], v1, s[6:7] offset:2048
	global_load_dwordx4 v[108:111], v1, s[6:7] offset:2064
	global_load_dwordx4 v[112:115], v2, s[10:11]
	global_load_dwordx4 v[116:119], v2, s[10:11] offset:1024
	s_add_u32 s6, s6, 0x1000
	s_addc_u32 s7, s7, 0
	s_add_u32 s10, s10, 0x800
	s_addc_u32 s11, s11, 0
	s_waitcnt vmcnt(14)
	v_lshlrev_b32_e32 v208, 16, v144
	v_and_b32_e32 v209, 0xffff0000, v144
	v_lshlrev_b32_e32 v210, 16, v145
	v_and_b32_e32 v211, 0xffff0000, v145
	v_lshlrev_b32_e32 v212, 16, v146
	v_and_b32_e32 v213, 0xffff0000, v146
	v_lshlrev_b32_e32 v214, 16, v147
	v_and_b32_e32 v215, 0xffff0000, v147
	v_lshlrev_b32_e32 v216, 16, v148
	v_and_b32_e32 v217, 0xffff0000, v148
	v_lshlrev_b32_e32 v218, 16, v149
	v_and_b32_e32 v219, 0xffff0000, v149
	v_lshlrev_b32_e32 v220, 16, v150
	v_and_b32_e32 v221, 0xffff0000, v150
	v_lshlrev_b32_e32 v222, 16, v151
	v_and_b32_e32 v223, 0xffff0000, v151
	v_mul_f32_e32 v224, v208, v208
	v_fmac_f32_e32 v224, v209, v209
	v_fmac_f32_e32 v224, v210, v210
	v_fmac_f32_e32 v224, v211, v211
	v_fmac_f32_e32 v224, v212, v212
	v_fmac_f32_e32 v224, v213, v213
	v_fmac_f32_e32 v224, v214, v214
	v_fmac_f32_e32 v224, v215, v215
	v_fmac_f32_e32 v224, v216, v216
	v_fmac_f32_e32 v224, v217, v217
	v_fmac_f32_e32 v224, v218, v218
	v_fmac_f32_e32 v224, v219, v219
	v_fmac_f32_e32 v224, v220, v220
	v_fmac_f32_e32 v224, v221, v221
	v_fmac_f32_e32 v224, v222, v222
	v_fmac_f32_e32 v224, v223, v223
	s_nop 1
	v_add_f32_dpp v224, v224, v224 quad_perm:[1,0,3,2] row_mask:0xf bank_mask:0xf
	s_nop 1
	v_add_f32_dpp v224, v224, v224 quad_perm:[2,3,0,1] row_mask:0xf bank_mask:0xf
	s_nop 1
	v_add_f32_dpp v224, v224, v224 row_ror:4 row_mask:0xf bank_mask:0xf
	s_nop 1
	v_add_f32_dpp v224, v224, v224 row_ror:8 row_mask:0xf bank_mask:0xf
	s_nop 1
	v_readlane_b32 s20, v224, 0
	v_readlane_b32 s21, v224, 16
	v_readlane_b32 s22, v224, 32
	v_readlane_b32 s23, v224, 48
	s_nop 1
	v_mov_b32_e32 v225, s20
	v_add_f32_e32 v225, s21, v225
	v_add_f32_e32 v225, s22, v225
	v_add_f32_e32 v225, s23, v225
	v_mov_b32_e32 v226, 0x358637bd
	v_fmac_f32_e32 v226, 0x3a800000, v225
	v_rsq_f32_e32 v226, v226
	s_nop 0
	v_mul_f32_e32 v208, v208, v226
	v_mul_f32_e32 v209, v209, v226
	v_mul_f32_e32 v210, v210, v226
	v_mul_f32_e32 v211, v211, v226
	v_mul_f32_e32 v212, v212, v226
	v_mul_f32_e32 v213, v213, v226
	v_mul_f32_e32 v214, v214, v226
	v_mul_f32_e32 v215, v215, v226
; DI unsigned pk_bf16(float a, float b) { f32x2_t v = {a, b}; bf16x2_t r = __builtin_convertvector(v, bf16x2_t); return __builtin_bit_cast(unsigned, r); }
; DI float shx(float v, int mask) { const int l = olane(); return __builtin_bit_cast(float, __builtin_amdgcn_ds_bpermute(((l ^ mask) & 63) << 2, __builtin_bit_cast(int, v))); }
; DI void row_phase(const bf16_t* msrc, const float* xsrc, float* xdst, const float* g_post, const float* g_next, bf16_t* hdst, const int gw) {
;     ...
;                 for (int r = 0; r < RB; ++r) { const float r1 = rsqrtf(ss[r] * (1.f / DM) + EPS); xv[r][j] = xv[r][j] + mv[r][j] * r1 * g; *(f32x4*)(xdst + (size_t)(rowb + r) * DM + lane * 4 + 256 * j) = xv[r][j]; } }
;         }
;         if (hdst) {
;             float ss[RB];
; #pragma unroll
;             for (int r = 0; r < RB; ++r) { ss[r] = 0.f;
; #pragma unroll
;                 for (int j = 0; j < 4; ++j) ss[r] += xv[r][j][0] * xv[r][j][0] + xv[r][j][1] * xv[r][j][1] + xv[r][j][2] * xv[r][j][2] + xv[r][j][3] * xv[r][j][3]; }
; #pragma unroll
;             for (int o = 32; o >= 1; o >>= 1)
; #pragma unroll
;                 for (int r = 0; r < RB; ++r) ss[r] += shx(ss[r], o);
; #pragma unroll
;             for (int j = 0; j < 4; ++j) { const f32x4 g = *(const f32x4*)(g_next + lane * 4 + 256 * j);
; #pragma unroll
;                 for (int r = 0; r < RB; ++r) { const float r2 = rsqrtf(ss[r] * (1.f / DM) + EPS); const f32x4 hv = xv[r][j] * r2 * g;
;                     u32x2 o; o[0] = pk_bf16(hv[0], hv[1]); o[1] = pk_bf16(hv[2], hv[3]); *(u32x2*)(hdst + (size_t)(rowb + r) * DM + lane * 4 + 256 * j) = o; } }
	v_mul_f32_e32 v216, v216, v226
	v_mul_f32_e32 v217, v217, v226
	v_mul_f32_e32 v218, v218, v226
	v_mul_f32_e32 v219, v219, v226
	v_mul_f32_e32 v220, v220, v226
	v_mul_f32_e32 v221, v221, v226
	v_mul_f32_e32 v222, v222, v226
	v_mul_f32_e32 v223, v223, v226
	v_fmac_f32_e32 v128, v208, v40
	v_fmac_f32_e32 v129, v209, v41
	v_fmac_f32_e32 v130, v210, v42
	v_fmac_f32_e32 v131, v211, v43
	v_fmac_f32_e32 v132, v212, v44
	v_fmac_f32_e32 v133, v213, v45
	v_fmac_f32_e32 v134, v214, v46
	v_fmac_f32_e32 v135, v215, v47
	v_fmac_f32_e32 v136, v216, v48
	v_fmac_f32_e32 v137, v217, v49
	v_fmac_f32_e32 v138, v218, v50
	v_fmac_f32_e32 v139, v219, v51
	v_fmac_f32_e32 v140, v220, v52
	v_fmac_f32_e32 v141, v221, v53
	v_fmac_f32_e32 v142, v222, v54
	v_fmac_f32_e32 v143, v223, v55
	v_mul_f32_e32 v224, v128, v128
	v_fmac_f32_e32 v224, v129, v129
	v_fmac_f32_e32 v224, v130, v130
	v_fmac_f32_e32 v224, v131, v131
	v_fmac_f32_e32 v224, v132, v132
	v_fmac_f32_e32 v224, v133, v133
	v_fmac_f32_e32 v224, v134, v134
	v_fmac_f32_e32 v224, v135, v135
	v_fmac_f32_e32 v224, v136, v136
	v_fmac_f32_e32 v224, v137, v137
	v_fmac_f32_e32 v224, v138, v138
	v_fmac_f32_e32 v224, v139, v139
	v_fmac_f32_e32 v224, v140, v140
	v_fmac_f32_e32 v224, v141, v141
	v_fmac_f32_e32 v224, v142, v142
	v_fmac_f32_e32 v224, v143, v143
	s_nop 1
	v_add_f32_dpp v224, v224, v224 quad_perm:[1,0,3,2] row_mask:0xf bank_mask:0xf
	s_nop 1
	v_add_f32_dpp v224, v224, v224 quad_perm:[2,3,0,1] row_mask:0xf bank_mask:0xf
	s_nop 1
	v_add_f32_dpp v224, v224, v224 row_ror:4 row_mask:0xf bank_mask:0xf
	s_nop 1
	v_add_f32_dpp v224, v224, v224 row_ror:8 row_mask:0xf bank_mask:0xf
	s_nop 1
	v_readlane_b32 s20, v224, 0
	v_readlane_b32 s21, v224, 16
	v_readlane_b32 s22, v224, 32
	v_readlane_b32 s23, v224, 48
	s_nop 1
	v_mov_b32_e32 v225, s20
	v_add_f32_e32 v225, s21, v225
	v_add_f32_e32 v225, s22, v225
	v_add_f32_e32 v225, s23, v225
	v_mov_b32_e32 v226, 0x358637bd
	v_fmac_f32_e32 v226, 0x3a800000, v225
	v_rsq_f32_e32 v226, v226
	s_nop 0
	v_mul_f32_e32 v208, v128, v226
	v_mul_f32_e32 v209, v129, v226
	v_mul_f32_e32 v210, v130, v226
	v_mul_f32_e32 v211, v131, v226
	v_mul_f32_e32 v212, v132, v226
	v_mul_f32_e32 v213, v133, v226
	v_mul_f32_e32 v214, v134, v226
	v_mul_f32_e32 v215, v135, v226
	v_mul_f32_e32 v216, v136, v226
	v_mul_f32_e32 v217, v137, v226
	v_mul_f32_e32 v218, v138, v226
	v_mul_f32_e32 v219, v139, v226
	v_mul_f32_e32 v220, v140, v226
	v_mul_f32_e32 v221, v141, v226
	v_mul_f32_e32 v222, v142, v226
	v_mul_f32_e32 v223, v143, v226
	v_mul_f32_e32 v208, v208, v56
	v_mul_f32_e32 v209, v209, v57
	v_mul_f32_e32 v210, v210, v58
	v_mul_f32_e32 v211, v211, v59
	v_mul_f32_e32 v212, v212, v60
	v_mul_f32_e32 v213, v213, v61
	v_mul_f32_e32 v214, v214, v62
	v_mul_f32_e32 v215, v215, v63
	v_mul_f32_e32 v216, v216, v64
	v_mul_f32_e32 v217, v217, v65
	v_mul_f32_e32 v218, v218, v66
	v_mul_f32_e32 v219, v219, v67
	v_mul_f32_e32 v220, v220, v68
	v_mul_f32_e32 v221, v221, v69
	v_mul_f32_e32 v222, v222, v70
	v_mul_f32_e32 v223, v223, v71
	v_cvt_pk_bf16_f32 v144, v208, v209
	v_cvt_pk_bf16_f32 v145, v210, v211
	v_cvt_pk_bf16_f32 v146, v212, v213
	v_cvt_pk_bf16_f32 v147, v214, v215
	v_cvt_pk_bf16_f32 v148, v216, v217
	v_cvt_pk_bf16_f32 v149, v218, v219
	v_cvt_pk_bf16_f32 v150, v220, v221
	v_cvt_pk_bf16_f32 v151, v222, v223
	global_store_dwordx4 v2, v[144:147], s[14:15]
	global_store_dwordx4 v2, v[148:151], s[14:15] offset:1024
	s_add_u32 s14, s14, 0x800
	s_addc_u32 s15, s15, 0
	global_load_dwordx4 v[128:131], v1, s[6:7] offset:0
	global_load_dwordx4 v[132:135], v1, s[6:7] offset:16
	global_load_dwordx4 v[136:139], v1, s[6:7] offset:2048
	global_load_dwordx4 v[140:143], v1, s[6:7] offset:2064
	global_load_dwordx4 v[144:147], v2, s[10:11]
	global_load_dwordx4 v[148:151], v2, s[10:11] offset:1024
	s_add_u32 s6, s6, 0x1000
	s_addc_u32 s7, s7, 0
	s_add_u32 s10, s10, 0x800
	s_addc_u32 s11, s11, 0
	s_waitcnt vmcnt(16)
	v_lshlrev_b32_e32 v208, 16, v176
	v_and_b32_e32 v209, 0xffff0000, v176
	v_lshlrev_b32_e32 v210, 16, v177
	v_and_b32_e32 v211, 0xffff0000, v177
	v_lshlrev_b32_e32 v212, 16, v178
	v_and_b32_e32 v213, 0xffff0000, v178
	v_lshlrev_b32_e32 v214, 16, v179
	v_and_b32_e32 v215, 0xffff0000, v179
	v_lshlrev_b32_e32 v216, 16, v180
	v_and_b32_e32 v217, 0xffff0000, v180
	v_lshlrev_b32_e32 v218, 16, v181
	v_and_b32_e32 v219, 0xffff0000, v181
	v_lshlrev_b32_e32 v220, 16, v182
	v_and_b32_e32 v221, 0xffff0000, v182
	v_lshlrev_b32_e32 v222, 16, v183
	v_and_b32_e32 v223, 0xffff0000, v183
	v_mul_f32_e32 v224, v208, v208
	v_fmac_f32_e32 v224, v209, v209
	v_fmac_f32_e32 v224, v210, v210
	v_fmac_f32_e32 v224, v211, v211
	v_fmac_f32_e32 v224, v212, v212
	v_fmac_f32_e32 v224, v213, v213
	v_fmac_f32_e32 v224, v214, v214
	v_fmac_f32_e32 v224, v215, v215
	v_fmac_f32_e32 v224, v216, v216
	v_fmac_f32_e32 v224, v217, v217
	v_fmac_f32_e32 v224, v218, v218
	v_fmac_f32_e32 v224, v219, v219
	v_fmac_f32_e32 v224, v220, v220
	v_fmac_f32_e32 v224, v221, v221
	v_fmac_f32_e32 v224, v222, v222
	v_fmac_f32_e32 v224, v223, v223
	s_nop 1
	v_add_f32_dpp v224, v224, v224 quad_perm:[1,0,3,2] row_mask:0xf bank_mask:0xf
	s_nop 1
	v_add_f32_dpp v224, v224, v224 quad_perm:[2,3,0,1] row_mask:0xf bank_mask:0xf
	s_nop 1
	v_add_f32_dpp v224, v224, v224 row_ror:4 row_mask:0xf bank_mask:0xf
	s_nop 1
	v_add_f32_dpp v224, v224, v224 row_ror:8 row_mask:0xf bank_mask:0xf
	s_nop 1
	v_readlane_b32 s20, v224, 0
	v_readlane_b32 s21, v224, 16
	v_readlane_b32 s22, v224, 32
	v_readlane_b32 s23, v224, 48
	s_nop 1
	v_mov_b32_e32 v225, s20
	v_add_f32_e32 v225, s21, v225
	v_add_f32_e32 v225, s22, v225
	v_add_f32_e32 v225, s23, v225
	v_mov_b32_e32 v226, 0x358637bd
	v_fmac_f32_e32 v226, 0x3a800000, v225
; DI unsigned pk_bf16(float a, float b) { f32x2_t v = {a, b}; bf16x2_t r = __builtin_convertvector(v, bf16x2_t); return __builtin_bit_cast(unsigned, r); }
; DI float shx(float v, int mask) { const int l = olane(); return __builtin_bit_cast(float, __builtin_amdgcn_ds_bpermute(((l ^ mask) & 63) << 2, __builtin_bit_cast(int, v))); }
; DI void row_phase(const bf16_t* msrc, const float* xsrc, float* xdst, const float* g_post, const float* g_next, bf16_t* hdst, const int gw) {
;     ...
;                 for (int r = 0; r < RB; ++r) { const float r1 = rsqrtf(ss[r] * (1.f / DM) + EPS); xv[r][j] = xv[r][j] + mv[r][j] * r1 * g; *(f32x4*)(xdst + (size_t)(rowb + r) * DM + lane * 4 + 256 * j) = xv[r][j]; } }
;         }
;         if (hdst) {
;             float ss[RB];
; #pragma unroll
;             for (int r = 0; r < RB; ++r) { ss[r] = 0.f;
; #pragma unroll
;                 for (int j = 0; j < 4; ++j) ss[r] += xv[r][j][0] * xv[r][j][0] + xv[r][j][1] * xv[r][j][1] + xv[r][j][2] * xv[r][j][2] + xv[r][j][3] * xv[r][j][3]; }
; #pragma unroll
;             for (int o = 32; o >= 1; o >>= 1)
; #pragma unroll
;                 for (int r = 0; r < RB; ++r) ss[r] += shx(ss[r], o);
; #pragma unroll
;             for (int j = 0; j < 4; ++j) { const f32x4 g = *(const f32x4*)(g_next + lane * 4 + 256 * j);
; #pragma unroll
;                 for (int r = 0; r < RB; ++r) { const float r2 = rsqrtf(ss[r] * (1.f / DM) + EPS); const f32x4 hv = xv[r][j] * r2 * g;
;                     u32x2 o; o[0] = pk_bf16(hv[0], hv[1]); o[1] = pk_bf16(hv[2], hv[3]); *(u32x2*)(hdst + (size_t)(rowb + r) * DM + lane * 4 + 256 * j) = o; } }
	v_rsq_f32_e32 v226, v226
	s_nop 0
	v_mul_f32_e32 v208, v208, v226
	v_mul_f32_e32 v209, v209, v226
	v_mul_f32_e32 v210, v210, v226
	v_mul_f32_e32 v211, v211, v226
	v_mul_f32_e32 v212, v212, v226
	v_mul_f32_e32 v213, v213, v226
	v_mul_f32_e32 v214, v214, v226
	v_mul_f32_e32 v215, v215, v226
	v_mul_f32_e32 v216, v216, v226
	v_mul_f32_e32 v217, v217, v226
	v_mul_f32_e32 v218, v218, v226
	v_mul_f32_e32 v219, v219, v226
	v_mul_f32_e32 v220, v220, v226
	v_mul_f32_e32 v221, v221, v226
	v_mul_f32_e32 v222, v222, v226
	v_mul_f32_e32 v223, v223, v226
	v_fmac_f32_e32 v160, v208, v40
	v_fmac_f32_e32 v161, v209, v41
	v_fmac_f32_e32 v162, v210, v42
	v_fmac_f32_e32 v163, v211, v43
	v_fmac_f32_e32 v164, v212, v44
	v_fmac_f32_e32 v165, v213, v45
	v_fmac_f32_e32 v166, v214, v46
	v_fmac_f32_e32 v167, v215, v47
	v_fmac_f32_e32 v168, v216, v48
	v_fmac_f32_e32 v169, v217, v49
	v_fmac_f32_e32 v170, v218, v50
	v_fmac_f32_e32 v171, v219, v51
	v_fmac_f32_e32 v172, v220, v52
	v_fmac_f32_e32 v173, v221, v53
	v_fmac_f32_e32 v174, v222, v54
	v_fmac_f32_e32 v175, v223, v55
	v_mul_f32_e32 v224, v160, v160
	v_fmac_f32_e32 v224, v161, v161
	v_fmac_f32_e32 v224, v162, v162
	v_fmac_f32_e32 v224, v163, v163
	v_fmac_f32_e32 v224, v164, v164
	v_fmac_f32_e32 v224, v165, v165
	v_fmac_f32_e32 v224, v166, v166
	v_fmac_f32_e32 v224, v167, v167
	v_fmac_f32_e32 v224, v168, v168
	v_fmac_f32_e32 v224, v169, v169
	v_fmac_f32_e32 v224, v170, v170
	v_fmac_f32_e32 v224, v171, v171
	v_fmac_f32_e32 v224, v172, v172
	v_fmac_f32_e32 v224, v173, v173
	v_fmac_f32_e32 v224, v174, v174
	v_fmac_f32_e32 v224, v175, v175
	s_nop 1
	v_add_f32_dpp v224, v224, v224 quad_perm:[1,0,3,2] row_mask:0xf bank_mask:0xf
	s_nop 1
	v_add_f32_dpp v224, v224, v224 quad_perm:[2,3,0,1] row_mask:0xf bank_mask:0xf
	s_nop 1
	v_add_f32_dpp v224, v224, v224 row_ror:4 row_mask:0xf bank_mask:0xf
	s_nop 1
	v_add_f32_dpp v224, v224, v224 row_ror:8 row_mask:0xf bank_mask:0xf
	s_nop 1
	v_readlane_b32 s20, v224, 0
	v_readlane_b32 s21, v224, 16
	v_readlane_b32 s22, v224, 32
	v_readlane_b32 s23, v224, 48
	s_nop 1
	v_mov_b32_e32 v225, s20
	v_add_f32_e32 v225, s21, v225
	v_add_f32_e32 v225, s22, v225
	v_add_f32_e32 v225, s23, v225
	v_mov_b32_e32 v226, 0x358637bd
	v_fmac_f32_e32 v226, 0x3a800000, v225
	v_rsq_f32_e32 v226, v226
	s_nop 0
	v_mul_f32_e32 v208, v160, v226
	v_mul_f32_e32 v209, v161, v226
	v_mul_f32_e32 v210, v162, v226
	v_mul_f32_e32 v211, v163, v226
	v_mul_f32_e32 v212, v164, v226
	v_mul_f32_e32 v213, v165, v226
	v_mul_f32_e32 v214, v166, v226
	v_mul_f32_e32 v215, v167, v226
	v_mul_f32_e32 v216, v168, v226
	v_mul_f32_e32 v217, v169, v226
	v_mul_f32_e32 v218, v170, v226
	v_mul_f32_e32 v219, v171, v226
	v_mul_f32_e32 v220, v172, v226
	v_mul_f32_e32 v221, v173, v226
	v_mul_f32_e32 v222, v174, v226
	v_mul_f32_e32 v223, v175, v226
	v_mul_f32_e32 v208, v208, v56
	v_mul_f32_e32 v209, v209, v57
	v_mul_f32_e32 v210, v210, v58
	v_mul_f32_e32 v211, v211, v59
	v_mul_f32_e32 v212, v212, v60
	v_mul_f32_e32 v213, v213, v61
	v_mul_f32_e32 v214, v214, v62
	v_mul_f32_e32 v215, v215, v63
	v_mul_f32_e32 v216, v216, v64
	v_mul_f32_e32 v217, v217, v65
	v_mul_f32_e32 v218, v218, v66
	v_mul_f32_e32 v219, v219, v67
	v_mul_f32_e32 v220, v220, v68
	v_mul_f32_e32 v221, v221, v69
	v_mul_f32_e32 v222, v222, v70
	v_mul_f32_e32 v223, v223, v71
	v_cvt_pk_bf16_f32 v176, v208, v209
	v_cvt_pk_bf16_f32 v177, v210, v211
	v_cvt_pk_bf16_f32 v178, v212, v213
	v_cvt_pk_bf16_f32 v179, v214, v215
	v_cvt_pk_bf16_f32 v180, v216, v217
	v_cvt_pk_bf16_f32 v181, v218, v219
	v_cvt_pk_bf16_f32 v182, v220, v221
	v_cvt_pk_bf16_f32 v183, v222, v223
	global_store_dwordx4 v2, v[176:179], s[14:15]
	global_store_dwordx4 v2, v[180:183], s[14:15] offset:1024
	s_add_u32 s14, s14, 0x800
	s_addc_u32 s15, s15, 0
	global_load_dwordx4 v[160:163], v1, s[6:7] offset:0
	global_load_dwordx4 v[164:167], v1, s[6:7] offset:16
	global_load_dwordx4 v[168:171], v1, s[6:7] offset:2048
	global_load_dwordx4 v[172:175], v1, s[6:7] offset:2064
	global_load_dwordx4 v[176:179], v2, s[10:11]
	global_load_dwordx4 v[180:183], v2, s[10:11] offset:1024
	s_add_u32 s6, s6, 0x1000
	s_addc_u32 s7, s7, 0
	s_add_u32 s10, s10, 0x800
	s_addc_u32 s11, s11, 0
	s_waitcnt vmcnt(16)
	v_lshlrev_b32_e32 v208, 16, v112
	v_and_b32_e32 v209, 0xffff0000, v112
	v_lshlrev_b32_e32 v210, 16, v113
	v_and_b32_e32 v211, 0xffff0000, v113
	v_lshlrev_b32_e32 v212, 16, v114
	v_and_b32_e32 v213, 0xffff0000, v114
	v_lshlrev_b32_e32 v214, 16, v115
	v_and_b32_e32 v215, 0xffff0000, v115
	v_lshlrev_b32_e32 v216, 16, v116
	v_and_b32_e32 v217, 0xffff0000, v116
	v_lshlrev_b32_e32 v218, 16, v117
	v_and_b32_e32 v219, 0xffff0000, v117
	v_lshlrev_b32_e32 v220, 16, v118
	v_and_b32_e32 v221, 0xffff0000, v118
	v_lshlrev_b32_e32 v222, 16, v119
	v_and_b32_e32 v223, 0xffff0000, v119
	v_mul_f32_e32 v224, v208, v208
	v_fmac_f32_e32 v224, v209, v209
	v_fmac_f32_e32 v224, v210, v210
	v_fmac_f32_e32 v224, v211, v211
	v_fmac_f32_e32 v224, v212, v212
	v_fmac_f32_e32 v224, v213, v213
	v_fmac_f32_e32 v224, v214, v214
	v_fmac_f32_e32 v224, v215, v215
	v_fmac_f32_e32 v224, v216, v216
	v_fmac_f32_e32 v224, v217, v217
	v_fmac_f32_e32 v224, v218, v218
	v_fmac_f32_e32 v224, v219, v219
	v_fmac_f32_e32 v224, v220, v220
	v_fmac_f32_e32 v224, v221, v221
	v_fmac_f32_e32 v224, v222, v222
	v_fmac_f32_e32 v224, v223, v223
	s_nop 1
	v_add_f32_dpp v224, v224, v224 quad_perm:[1,0,3,2] row_mask:0xf bank_mask:0xf
	s_nop 1
	v_add_f32_dpp v224, v224, v224 quad_perm:[2,3,0,1] row_mask:0xf bank_mask:0xf
	s_nop 1
	v_add_f32_dpp v224, v224, v224 row_ror:4 row_mask:0xf bank_mask:0xf
	s_nop 1
	v_add_f32_dpp v224, v224, v224 row_ror:8 row_mask:0xf bank_mask:0xf
	s_nop 1
	v_readlane_b32 s20, v224, 0
; DI unsigned pk_bf16(float a, float b) { f32x2_t v = {a, b}; bf16x2_t r = __builtin_convertvector(v, bf16x2_t); return __builtin_bit_cast(unsigned, r); }
; DI float shx(float v, int mask) { const int l = olane(); return __builtin_bit_cast(float, __builtin_amdgcn_ds_bpermute(((l ^ mask) & 63) << 2, __builtin_bit_cast(int, v))); }
; DI void row_phase(const bf16_t* msrc, const float* xsrc, float* xdst, const float* g_post, const float* g_next, bf16_t* hdst, const int gw) {
;     ...
;                 for (int r = 0; r < RB; ++r) { const float r1 = rsqrtf(ss[r] * (1.f / DM) + EPS); xv[r][j] = xv[r][j] + mv[r][j] * r1 * g; *(f32x4*)(xdst + (size_t)(rowb + r) * DM + lane * 4 + 256 * j) = xv[r][j]; } }
;         }
;         if (hdst) {
;             float ss[RB];
; #pragma unroll
;             for (int r = 0; r < RB; ++r) { ss[r] = 0.f;
; #pragma unroll
;                 for (int j = 0; j < 4; ++j) ss[r] += xv[r][j][0] * xv[r][j][0] + xv[r][j][1] * xv[r][j][1] + xv[r][j][2] * xv[r][j][2] + xv[r][j][3] * xv[r][j][3]; }
; #pragma unroll
;             for (int o = 32; o >= 1; o >>= 1)
; #pragma unroll
;                 for (int r = 0; r < RB; ++r) ss[r] += shx(ss[r], o);
; #pragma unroll
;             for (int j = 0; j < 4; ++j) { const f32x4 g = *(const f32x4*)(g_next + lane * 4 + 256 * j);
; #pragma unroll
;                 for (int r = 0; r < RB; ++r) { const float r2 = rsqrtf(ss[r] * (1.f / DM) + EPS); const f32x4 hv = xv[r][j] * r2 * g;
;                     u32x2 o; o[0] = pk_bf16(hv[0], hv[1]); o[1] = pk_bf16(hv[2], hv[3]); *(u32x2*)(hdst + (size_t)(rowb + r) * DM + lane * 4 + 256 * j) = o; } }
	v_readlane_b32 s21, v224, 16
	v_readlane_b32 s22, v224, 32
	v_readlane_b32 s23, v224, 48
	s_nop 1
	v_mov_b32_e32 v225, s20
	v_add_f32_e32 v225, s21, v225
	v_add_f32_e32 v225, s22, v225
	v_add_f32_e32 v225, s23, v225
	v_mov_b32_e32 v226, 0x358637bd
	v_fmac_f32_e32 v226, 0x3a800000, v225
	v_rsq_f32_e32 v226, v226
	s_nop 0
	v_mul_f32_e32 v208, v208, v226
	v_mul_f32_e32 v209, v209, v226
	v_mul_f32_e32 v210, v210, v226
	v_mul_f32_e32 v211, v211, v226
	v_mul_f32_e32 v212, v212, v226
	v_mul_f32_e32 v213, v213, v226
	v_mul_f32_e32 v214, v214, v226
	v_mul_f32_e32 v215, v215, v226
	v_mul_f32_e32 v216, v216, v226
	v_mul_f32_e32 v217, v217, v226
	v_mul_f32_e32 v218, v218, v226
	v_mul_f32_e32 v219, v219, v226
	v_mul_f32_e32 v220, v220, v226
	v_mul_f32_e32 v221, v221, v226
	v_mul_f32_e32 v222, v222, v226
	v_mul_f32_e32 v223, v223, v226
	v_fmac_f32_e32 v96, v208, v40
	v_fmac_f32_e32 v97, v209, v41
	v_fmac_f32_e32 v98, v210, v42
	v_fmac_f32_e32 v99, v211, v43
	v_fmac_f32_e32 v100, v212, v44
	v_fmac_f32_e32 v101, v213, v45
	v_fmac_f32_e32 v102, v214, v46
	v_fmac_f32_e32 v103, v215, v47
	v_fmac_f32_e32 v104, v216, v48
	v_fmac_f32_e32 v105, v217, v49
	v_fmac_f32_e32 v106, v218, v50
	v_fmac_f32_e32 v107, v219, v51
	v_fmac_f32_e32 v108, v220, v52
	v_fmac_f32_e32 v109, v221, v53
	v_fmac_f32_e32 v110, v222, v54
	v_fmac_f32_e32 v111, v223, v55
	v_mul_f32_e32 v224, v96, v96
	v_fmac_f32_e32 v224, v97, v97
	v_fmac_f32_e32 v224, v98, v98
	v_fmac_f32_e32 v224, v99, v99
	v_fmac_f32_e32 v224, v100, v100
	v_fmac_f32_e32 v224, v101, v101
	v_fmac_f32_e32 v224, v102, v102
	v_fmac_f32_e32 v224, v103, v103
	v_fmac_f32_e32 v224, v104, v104
	v_fmac_f32_e32 v224, v105, v105
	v_fmac_f32_e32 v224, v106, v106
	v_fmac_f32_e32 v224, v107, v107
	v_fmac_f32_e32 v224, v108, v108
	v_fmac_f32_e32 v224, v109, v109
	v_fmac_f32_e32 v224, v110, v110
	v_fmac_f32_e32 v224, v111, v111
	s_nop 1
	v_add_f32_dpp v224, v224, v224 quad_perm:[1,0,3,2] row_mask:0xf bank_mask:0xf
	s_nop 1
	v_add_f32_dpp v224, v224, v224 quad_perm:[2,3,0,1] row_mask:0xf bank_mask:0xf
	s_nop 1
	v_add_f32_dpp v224, v224, v224 row_ror:4 row_mask:0xf bank_mask:0xf
	s_nop 1
	v_add_f32_dpp v224, v224, v224 row_ror:8 row_mask:0xf bank_mask:0xf
	s_nop 1
	v_readlane_b32 s20, v224, 0
	v_readlane_b32 s21, v224, 16
	v_readlane_b32 s22, v224, 32
	v_readlane_b32 s23, v224, 48
	s_nop 1
	v_mov_b32_e32 v225, s20
	v_add_f32_e32 v225, s21, v225
	v_add_f32_e32 v225, s22, v225
	v_add_f32_e32 v225, s23, v225
	v_mov_b32_e32 v226, 0x358637bd
	v_fmac_f32_e32 v226, 0x3a800000, v225
	v_rsq_f32_e32 v226, v226
	s_nop 0
	v_mul_f32_e32 v208, v96, v226
	v_mul_f32_e32 v209, v97, v226
	v_mul_f32_e32 v210, v98, v226
	v_mul_f32_e32 v211, v99, v226
	v_mul_f32_e32 v212, v100, v226
	v_mul_f32_e32 v213, v101, v226
	v_mul_f32_e32 v214, v102, v226
	v_mul_f32_e32 v215, v103, v226
	v_mul_f32_e32 v216, v104, v226
	v_mul_f32_e32 v217, v105, v226
	v_mul_f32_e32 v218, v106, v226
	v_mul_f32_e32 v219, v107, v226
	v_mul_f32_e32 v220, v108, v226
	v_mul_f32_e32 v221, v109, v226
	v_mul_f32_e32 v222, v110, v226
	v_mul_f32_e32 v223, v111, v226
	v_mul_f32_e32 v208, v208, v56
	v_mul_f32_e32 v209, v209, v57
	v_mul_f32_e32 v210, v210, v58
	v_mul_f32_e32 v211, v211, v59
	v_mul_f32_e32 v212, v212, v60
	v_mul_f32_e32 v213, v213, v61
	v_mul_f32_e32 v214, v214, v62
	v_mul_f32_e32 v215, v215, v63
	v_mul_f32_e32 v216, v216, v64
	v_mul_f32_e32 v217, v217, v65
	v_mul_f32_e32 v218, v218, v66
	v_mul_f32_e32 v219, v219, v67
	v_mul_f32_e32 v220, v220, v68
	v_mul_f32_e32 v221, v221, v69
	v_mul_f32_e32 v222, v222, v70
	v_mul_f32_e32 v223, v223, v71
	v_cvt_pk_bf16_f32 v112, v208, v209
	v_cvt_pk_bf16_f32 v113, v210, v211
	v_cvt_pk_bf16_f32 v114, v212, v213
	v_cvt_pk_bf16_f32 v115, v214, v215
	v_cvt_pk_bf16_f32 v116, v216, v217
	v_cvt_pk_bf16_f32 v117, v218, v219
	v_cvt_pk_bf16_f32 v118, v220, v221
	v_cvt_pk_bf16_f32 v119, v222, v223
	global_store_dwordx4 v2, v[112:115], s[14:15]
	global_store_dwordx4 v2, v[116:119], s[14:15] offset:1024
	s_add_u32 s14, s14, 0x800
	s_addc_u32 s15, s15, 0
	global_load_dwordx4 v[96:99], v1, s[6:7] offset:0
	global_load_dwordx4 v[100:103], v1, s[6:7] offset:16
	global_load_dwordx4 v[104:107], v1, s[6:7] offset:2048
	global_load_dwordx4 v[108:111], v1, s[6:7] offset:2064
	global_load_dwordx4 v[112:115], v2, s[10:11]
	global_load_dwordx4 v[116:119], v2, s[10:11] offset:1024
	s_add_u32 s6, s6, 0x1000
	s_addc_u32 s7, s7, 0
	s_add_u32 s10, s10, 0x800
	s_addc_u32 s11, s11, 0
	s_waitcnt vmcnt(16)
; DI unsigned pk_bf16(float a, float b) { f32x2_t v = {a, b}; bf16x2_t r = __builtin_convertvector(v, bf16x2_t); return __builtin_bit_cast(unsigned, r); }
; DI void row_phase(const bf16_t* msrc, const float* xsrc, float* xdst, const float* g_post, const float* g_next, bf16_t* hdst, const int gw) {
;     ...
;                 for (int j = 0; j < 4; ++j) { const u32x2 mw = *(const u32x2*)(msrc + (size_t)(rowb + r) * DM + lane * 4 + 256 * j);
;                     mv[r][j] = (f32x4){__uint_as_float(mw[0] << 16), __uint_as_float(mw[0] & 0xffff0000u), __uint_as_float(mw[1] << 16), __uint_as_float(mw[1] & 0xffff0000u)}; }
;             float ss[RB];
; #pragma unroll
;             for (int r = 0; r < RB; ++r) { ss[r] = 0.f;
; #pragma unroll
;                 for (int j = 0; j < 4; ++j) ss[r] += mv[r][j][0] * mv[r][j][0] + mv[r][j][1] * mv[r][j][1] + mv[r][j][2] * mv[r][j][2] + mv[r][j][3] * mv[r][j][3]; }
; #pragma unroll
;             for (int o = 32; o >= 1; o >>= 1)
; #pragma unroll
;                 for (int r = 0; r < RB; ++r) ss[r] += shx(ss[r], o);
; #pragma unroll
;             for (int j = 0; j < 4; ++j) { const f32x4 g = *(const f32x4*)(g_post + lane * 4 + 256 * j);
; #pragma unroll
;                 for (int r = 0; r < RB; ++r) { const float r1 = rsqrtf(ss[r] * (1.f / DM) + EPS); xv[r][j] = xv[r][j] + mv[r][j] * r1 * g; *(f32x4*)(xdst + (size_t)(rowb + r) * DM + lane * 4 + 256 * j) = xv[r][j]; } }
;         }
;         if (hdst) {
;             float ss[RB];
; #pragma unroll
;             for (int r = 0; r < RB; ++r) { ss[r] = 0.f;
; #pragma unroll
;                 for (int j = 0; j < 4; ++j) ss[r] += xv[r][j][0] * xv[r][j][0] + xv[r][j][1] * xv[r][j][1] + xv[r][j][2] * xv[r][j][2] + xv[r][j][3] * xv[r][j][3]; }
; #pragma unroll
;             for (int o = 32; o >= 1; o >>= 1)
; #pragma unroll
;                 for (int r = 0; r < RB; ++r) ss[r] += shx(ss[r], o);
; #pragma unroll
;             for (int j = 0; j < 4; ++j) { const f32x4 g = *(const f32x4*)(g_next + lane * 4 + 256 * j);
; #pragma unroll
;                 for (int r = 0; r < RB; ++r) { const float r2 = rsqrtf(ss[r] * (1.f / DM) + EPS); const f32x4 hv = xv[r][j] * r2 * g;
;                     u32x2 o; o[0] = pk_bf16(hv[0], hv[1]); o[1] = pk_bf16(hv[2], hv[3]); *(u32x2*)(hdst + (size_t)(rowb + r) * DM + lane * 4 + 256 * j) = o; } }
	v_lshlrev_b32_e32 v208, 16, v144
	v_and_b32_e32 v209, 0xffff0000, v144
	v_lshlrev_b32_e32 v210, 16, v145
	v_and_b32_e32 v211, 0xffff0000, v145
	v_lshlrev_b32_e32 v212, 16, v146
	v_and_b32_e32 v213, 0xffff0000, v146
	v_lshlrev_b32_e32 v214, 16, v147
	v_and_b32_e32 v215, 0xffff0000, v147
	v_lshlrev_b32_e32 v216, 16, v148
	v_and_b32_e32 v217, 0xffff0000, v148
	v_lshlrev_b32_e32 v218, 16, v149
	v_and_b32_e32 v219, 0xffff0000, v149
	v_lshlrev_b32_e32 v220, 16, v150
	v_and_b32_e32 v221, 0xffff0000, v150
	v_lshlrev_b32_e32 v222, 16, v151
	v_and_b32_e32 v223, 0xffff0000, v151
	v_mul_f32_e32 v224, v208, v208
	v_fmac_f32_e32 v224, v209, v209
	v_fmac_f32_e32 v224, v210, v210
	v_fmac_f32_e32 v224, v211, v211
	v_fmac_f32_e32 v224, v212, v212
	v_fmac_f32_e32 v224, v213, v213
	v_fmac_f32_e32 v224, v214, v214
	v_fmac_f32_e32 v224, v215, v215
	v_fmac_f32_e32 v224, v216, v216
	v_fmac_f32_e32 v224, v217, v217
	v_fmac_f32_e32 v224, v218, v218
	v_fmac_f32_e32 v224, v219, v219
	v_fmac_f32_e32 v224, v220, v220
	v_fmac_f32_e32 v224, v221, v221
	v_fmac_f32_e32 v224, v222, v222
	v_fmac_f32_e32 v224, v223, v223
	s_nop 1
	v_add_f32_dpp v224, v224, v224 quad_perm:[1,0,3,2] row_mask:0xf bank_mask:0xf
	s_nop 1
	v_add_f32_dpp v224, v224, v224 quad_perm:[2,3,0,1] row_mask:0xf bank_mask:0xf
	s_nop 1
	v_add_f32_dpp v224, v224, v224 row_ror:4 row_mask:0xf bank_mask:0xf
	s_nop 1
	v_add_f32_dpp v224, v224, v224 row_ror:8 row_mask:0xf bank_mask:0xf
	s_nop 1
	v_readlane_b32 s20, v224, 0
	v_readlane_b32 s21, v224, 16
	v_readlane_b32 s22, v224, 32
	v_readlane_b32 s23, v224, 48
	s_nop 1
	v_mov_b32_e32 v225, s20
	v_add_f32_e32 v225, s21, v225
	v_add_f32_e32 v225, s22, v225
	v_add_f32_e32 v225, s23, v225
	v_mov_b32_e32 v226, 0x358637bd
	v_fmac_f32_e32 v226, 0x3a800000, v225
	v_rsq_f32_e32 v226, v226
	s_nop 0
	v_mul_f32_e32 v208, v208, v226
	v_mul_f32_e32 v209, v209, v226
	v_mul_f32_e32 v210, v210, v226
	v_mul_f32_e32 v211, v211, v226
	v_mul_f32_e32 v212, v212, v226
	v_mul_f32_e32 v213, v213, v226
	v_mul_f32_e32 v214, v214, v226
	v_mul_f32_e32 v215, v215, v226
	v_mul_f32_e32 v216, v216, v226
	v_mul_f32_e32 v217, v217, v226
	v_mul_f32_e32 v218, v218, v226
	v_mul_f32_e32 v219, v219, v226
	v_mul_f32_e32 v220, v220, v226
	v_mul_f32_e32 v221, v221, v226
	v_mul_f32_e32 v222, v222, v226
	v_mul_f32_e32 v223, v223, v226
	v_fmac_f32_e32 v128, v208, v40
	v_fmac_f32_e32 v129, v209, v41
	v_fmac_f32_e32 v130, v210, v42
	v_fmac_f32_e32 v131, v211, v43
	v_fmac_f32_e32 v132, v212, v44
	v_fmac_f32_e32 v133, v213, v45
	v_fmac_f32_e32 v134, v214, v46
	v_fmac_f32_e32 v135, v215, v47
	v_fmac_f32_e32 v136, v216, v48
	v_fmac_f32_e32 v137, v217, v49
	v_fmac_f32_e32 v138, v218, v50
	v_fmac_f32_e32 v139, v219, v51
	v_fmac_f32_e32 v140, v220, v52
	v_fmac_f32_e32 v141, v221, v53
	v_fmac_f32_e32 v142, v222, v54
	v_fmac_f32_e32 v143, v223, v55
	v_mul_f32_e32 v224, v128, v128
	v_fmac_f32_e32 v224, v129, v129
	v_fmac_f32_e32 v224, v130, v130
	v_fmac_f32_e32 v224, v131, v131
	v_fmac_f32_e32 v224, v132, v132
	v_fmac_f32_e32 v224, v133, v133
	v_fmac_f32_e32 v224, v134, v134
	v_fmac_f32_e32 v224, v135, v135
	v_fmac_f32_e32 v224, v136, v136
	v_fmac_f32_e32 v224, v137, v137
	v_fmac_f32_e32 v224, v138, v138
	v_fmac_f32_e32 v224, v139, v139
	v_fmac_f32_e32 v224, v140, v140
	v_fmac_f32_e32 v224, v141, v141
	v_fmac_f32_e32 v224, v142, v142
	v_fmac_f32_e32 v224, v143, v143
	s_nop 1
	v_add_f32_dpp v224, v224, v224 quad_perm:[1,0,3,2] row_mask:0xf bank_mask:0xf
	s_nop 1
	v_add_f32_dpp v224, v224, v224 quad_perm:[2,3,0,1] row_mask:0xf bank_mask:0xf
	s_nop 1
	v_add_f32_dpp v224, v224, v224 row_ror:4 row_mask:0xf bank_mask:0xf
	s_nop 1
	v_add_f32_dpp v224, v224, v224 row_ror:8 row_mask:0xf bank_mask:0xf
	s_nop 1
	v_readlane_b32 s20, v224, 0
	v_readlane_b32 s21, v224, 16
	v_readlane_b32 s22, v224, 32
	v_readlane_b32 s23, v224, 48
	s_nop 1
	v_mov_b32_e32 v225, s20
	v_add_f32_e32 v225, s21, v225
	v_add_f32_e32 v225, s22, v225
	v_add_f32_e32 v225, s23, v225
	v_mov_b32_e32 v226, 0x358637bd
	v_fmac_f32_e32 v226, 0x3a800000, v225
	v_rsq_f32_e32 v226, v226
	s_nop 0
	v_mul_f32_e32 v208, v128, v226
	v_mul_f32_e32 v209, v129, v226
	v_mul_f32_e32 v210, v130, v226
	v_mul_f32_e32 v211, v131, v226
	v_mul_f32_e32 v212, v132, v226
	v_mul_f32_e32 v213, v133, v226
	v_mul_f32_e32 v214, v134, v226
	v_mul_f32_e32 v215, v135, v226
	v_mul_f32_e32 v216, v136, v226
	v_mul_f32_e32 v217, v137, v226
	v_mul_f32_e32 v218, v138, v226
	v_mul_f32_e32 v219, v139, v226
	v_mul_f32_e32 v220, v140, v226
	v_mul_f32_e32 v221, v141, v226
	v_mul_f32_e32 v222, v142, v226
	v_mul_f32_e32 v223, v143, v226
	v_mul_f32_e32 v208, v208, v56
	v_mul_f32_e32 v209, v209, v57
	v_mul_f32_e32 v210, v210, v58
	v_mul_f32_e32 v211, v211, v59
	v_mul_f32_e32 v212, v212, v60
	v_mul_f32_e32 v213, v213, v61
	v_mul_f32_e32 v214, v214, v62
	v_mul_f32_e32 v215, v215, v63
	v_mul_f32_e32 v216, v216, v64
	v_mul_f32_e32 v217, v217, v65
	v_mul_f32_e32 v218, v218, v66
	v_mul_f32_e32 v219, v219, v67
	v_mul_f32_e32 v220, v220, v68
	v_mul_f32_e32 v221, v221, v69
	v_mul_f32_e32 v222, v222, v70
	v_mul_f32_e32 v223, v223, v71
	v_cvt_pk_bf16_f32 v144, v208, v209
	v_cvt_pk_bf16_f32 v145, v210, v211
	v_cvt_pk_bf16_f32 v146, v212, v213
	v_cvt_pk_bf16_f32 v147, v214, v215
	v_cvt_pk_bf16_f32 v148, v216, v217
	v_cvt_pk_bf16_f32 v149, v218, v219
	v_cvt_pk_bf16_f32 v150, v220, v221
	v_cvt_pk_bf16_f32 v151, v222, v223
	global_store_dwordx4 v2, v[144:147], s[14:15]
	global_store_dwordx4 v2, v[148:151], s[14:15] offset:1024
	s_add_u32 s14, s14, 0x800
	s_addc_u32 s15, s15, 0
	global_load_dwordx4 v[128:131], v1, s[6:7] offset:0
	global_load_dwordx4 v[132:135], v1, s[6:7] offset:16
	global_load_dwordx4 v[136:139], v1, s[6:7] offset:2048
	global_load_dwordx4 v[140:143], v1, s[6:7] offset:2064
	global_load_dwordx4 v[144:147], v2, s[10:11]
	global_load_dwordx4 v[148:151], v2, s[10:11] offset:1024
	s_add_u32 s6, s6, 0x1000
	s_addc_u32 s7, s7, 0
	s_add_u32 s10, s10, 0x800
	s_addc_u32 s11, s11, 0
	s_waitcnt vmcnt(16)
; DI unsigned pk_bf16(float a, float b) { f32x2_t v = {a, b}; bf16x2_t r = __builtin_convertvector(v, bf16x2_t); return __builtin_bit_cast(unsigned, r); }
; DI void row_phase(const bf16_t* msrc, const float* xsrc, float* xdst, const float* g_post, const float* g_next, bf16_t* hdst, const int gw) {
;     ...
;                 for (int j = 0; j < 4; ++j) { const u32x2 mw = *(const u32x2*)(msrc + (size_t)(rowb + r) * DM + lane * 4 + 256 * j);
;                     mv[r][j] = (f32x4){__uint_as_float(mw[0] << 16), __uint_as_float(mw[0] & 0xffff0000u), __uint_as_float(mw[1] << 16), __uint_as_float(mw[1] & 0xffff0000u)}; }
;             float ss[RB];
; #pragma unroll
;             for (int r = 0; r < RB; ++r) { ss[r] = 0.f;
; #pragma unroll
;                 for (int j = 0; j < 4; ++j) ss[r] += mv[r][j][0] * mv[r][j][0] + mv[r][j][1] * mv[r][j][1] + mv[r][j][2] * mv[r][j][2] + mv[r][j][3] * mv[r][j][3]; }
; #pragma unroll
;             for (int o = 32; o >= 1; o >>= 1)
; #pragma unroll
;                 for (int r = 0; r < RB; ++r) ss[r] += shx(ss[r], o);
; #pragma unroll
;             for (int j = 0; j < 4; ++j) { const f32x4 g = *(const f32x4*)(g_post + lane * 4 + 256 * j);
; #pragma unroll
;                 for (int r = 0; r < RB; ++r) { const float r1 = rsqrtf(ss[r] * (1.f / DM) + EPS); xv[r][j] = xv[r][j] + mv[r][j] * r1 * g; *(f32x4*)(xdst + (size_t)(rowb + r) * DM + lane * 4 + 256 * j) = xv[r][j]; } }
;         }
;         if (hdst) {
;             float ss[RB];
; #pragma unroll
;             for (int r = 0; r < RB; ++r) { ss[r] = 0.f;
; #pragma unroll
;                 for (int j = 0; j < 4; ++j) ss[r] += xv[r][j][0] * xv[r][j][0] + xv[r][j][1] * xv[r][j][1] + xv[r][j][2] * xv[r][j][2] + xv[r][j][3] * xv[r][j][3]; }
; #pragma unroll
;             for (int o = 32; o >= 1; o >>= 1)
; #pragma unroll
;                 for (int r = 0; r < RB; ++r) ss[r] += shx(ss[r], o);
; #pragma unroll
;             for (int j = 0; j < 4; ++j) { const f32x4 g = *(const f32x4*)(g_next + lane * 4 + 256 * j);
; #pragma unroll
;                 for (int r = 0; r < RB; ++r) { const float r2 = rsqrtf(ss[r] * (1.f / DM) + EPS); const f32x4 hv = xv[r][j] * r2 * g;
;                     u32x2 o; o[0] = pk_bf16(hv[0], hv[1]); o[1] = pk_bf16(hv[2], hv[3]); *(u32x2*)(hdst + (size_t)(rowb + r) * DM + lane * 4 + 256 * j) = o; } }
	v_lshlrev_b32_e32 v208, 16, v176
	v_and_b32_e32 v209, 0xffff0000, v176
	v_lshlrev_b32_e32 v210, 16, v177
	v_and_b32_e32 v211, 0xffff0000, v177
	v_lshlrev_b32_e32 v212, 16, v178
	v_and_b32_e32 v213, 0xffff0000, v178
	v_lshlrev_b32_e32 v214, 16, v179
	v_and_b32_e32 v215, 0xffff0000, v179
	v_lshlrev_b32_e32 v216, 16, v180
	v_and_b32_e32 v217, 0xffff0000, v180
	v_lshlrev_b32_e32 v218, 16, v181
	v_and_b32_e32 v219, 0xffff0000, v181
	v_lshlrev_b32_e32 v220, 16, v182
	v_and_b32_e32 v221, 0xffff0000, v182
	v_lshlrev_b32_e32 v222, 16, v183
	v_and_b32_e32 v223, 0xffff0000, v183
	v_mul_f32_e32 v224, v208, v208
	v_fmac_f32_e32 v224, v209, v209
	v_fmac_f32_e32 v224, v210, v210
	v_fmac_f32_e32 v224, v211, v211
	v_fmac_f32_e32 v224, v212, v212
	v_fmac_f32_e32 v224, v213, v213
	v_fmac_f32_e32 v224, v214, v214
	v_fmac_f32_e32 v224, v215, v215
	v_fmac_f32_e32 v224, v216, v216
	v_fmac_f32_e32 v224, v217, v217
	v_fmac_f32_e32 v224, v218, v218
	v_fmac_f32_e32 v224, v219, v219
	v_fmac_f32_e32 v224, v220, v220
	v_fmac_f32_e32 v224, v221, v221
	v_fmac_f32_e32 v224, v222, v222
	v_fmac_f32_e32 v224, v223, v223
	s_nop 1
	v_add_f32_dpp v224, v224, v224 quad_perm:[1,0,3,2] row_mask:0xf bank_mask:0xf
	s_nop 1
	v_add_f32_dpp v224, v224, v224 quad_perm:[2,3,0,1] row_mask:0xf bank_mask:0xf
	s_nop 1
	v_add_f32_dpp v224, v224, v224 row_ror:4 row_mask:0xf bank_mask:0xf
	s_nop 1
	v_add_f32_dpp v224, v224, v224 row_ror:8 row_mask:0xf bank_mask:0xf
	s_nop 1
	v_readlane_b32 s20, v224, 0
	v_readlane_b32 s21, v224, 16
	v_readlane_b32 s22, v224, 32
	v_readlane_b32 s23, v224, 48
	s_nop 1
	v_mov_b32_e32 v225, s20
	v_add_f32_e32 v225, s21, v225
	v_add_f32_e32 v225, s22, v225
	v_add_f32_e32 v225, s23, v225
	v_mov_b32_e32 v226, 0x358637bd
	v_fmac_f32_e32 v226, 0x3a800000, v225
	v_rsq_f32_e32 v226, v226
	s_nop 0
	v_mul_f32_e32 v208, v208, v226
	v_mul_f32_e32 v209, v209, v226
	v_mul_f32_e32 v210, v210, v226
	v_mul_f32_e32 v211, v211, v226
	v_mul_f32_e32 v212, v212, v226
	v_mul_f32_e32 v213, v213, v226
	v_mul_f32_e32 v214, v214, v226
	v_mul_f32_e32 v215, v215, v226
	v_mul_f32_e32 v216, v216, v226
	v_mul_f32_e32 v217, v217, v226
	v_mul_f32_e32 v218, v218, v226
	v_mul_f32_e32 v219, v219, v226
	v_mul_f32_e32 v220, v220, v226
	v_mul_f32_e32 v221, v221, v226
	v_mul_f32_e32 v222, v222, v226
	v_mul_f32_e32 v223, v223, v226
	v_fmac_f32_e32 v160, v208, v40
	v_fmac_f32_e32 v161, v209, v41
	v_fmac_f32_e32 v162, v210, v42
	v_fmac_f32_e32 v163, v211, v43
	v_fmac_f32_e32 v164, v212, v44
	v_fmac_f32_e32 v165, v213, v45
	v_fmac_f32_e32 v166, v214, v46
	v_fmac_f32_e32 v167, v215, v47
	v_fmac_f32_e32 v168, v216, v48
	v_fmac_f32_e32 v169, v217, v49
	v_fmac_f32_e32 v170, v218, v50
	v_fmac_f32_e32 v171, v219, v51
	v_fmac_f32_e32 v172, v220, v52
	v_fmac_f32_e32 v173, v221, v53
	v_fmac_f32_e32 v174, v222, v54
	v_fmac_f32_e32 v175, v223, v55
	v_mul_f32_e32 v224, v160, v160
	v_fmac_f32_e32 v224, v161, v161
	v_fmac_f32_e32 v224, v162, v162
	v_fmac_f32_e32 v224, v163, v163
	v_fmac_f32_e32 v224, v164, v164
	v_fmac_f32_e32 v224, v165, v165
	v_fmac_f32_e32 v224, v166, v166
	v_fmac_f32_e32 v224, v167, v167
	v_fmac_f32_e32 v224, v168, v168
	v_fmac_f32_e32 v224, v169, v169
	v_fmac_f32_e32 v224, v170, v170
	v_fmac_f32_e32 v224, v171, v171
	v_fmac_f32_e32 v224, v172, v172
	v_fmac_f32_e32 v224, v173, v173
	v_fmac_f32_e32 v224, v174, v174
	v_fmac_f32_e32 v224, v175, v175
	s_nop 1
	v_add_f32_dpp v224, v224, v224 quad_perm:[1,0,3,2] row_mask:0xf bank_mask:0xf
	s_nop 1
	v_add_f32_dpp v224, v224, v224 quad_perm:[2,3,0,1] row_mask:0xf bank_mask:0xf
	s_nop 1
	v_add_f32_dpp v224, v224, v224 row_ror:4 row_mask:0xf bank_mask:0xf
	s_nop 1
	v_add_f32_dpp v224, v224, v224 row_ror:8 row_mask:0xf bank_mask:0xf
	s_nop 1
	v_readlane_b32 s20, v224, 0
	v_readlane_b32 s21, v224, 16
	v_readlane_b32 s22, v224, 32
	v_readlane_b32 s23, v224, 48
	s_nop 1
	v_mov_b32_e32 v225, s20
	v_add_f32_e32 v225, s21, v225
	v_add_f32_e32 v225, s22, v225
	v_add_f32_e32 v225, s23, v225
	v_mov_b32_e32 v226, 0x358637bd
	v_fmac_f32_e32 v226, 0x3a800000, v225
	v_rsq_f32_e32 v226, v226
	s_nop 0
	v_mul_f32_e32 v208, v160, v226
	v_mul_f32_e32 v209, v161, v226
	v_mul_f32_e32 v210, v162, v226
	v_mul_f32_e32 v211, v163, v226
	v_mul_f32_e32 v212, v164, v226
	v_mul_f32_e32 v213, v165, v226
	v_mul_f32_e32 v214, v166, v226
	v_mul_f32_e32 v215, v167, v226
	v_mul_f32_e32 v216, v168, v226
	v_mul_f32_e32 v217, v169, v226
	v_mul_f32_e32 v218, v170, v226
	v_mul_f32_e32 v219, v171, v226
	v_mul_f32_e32 v220, v172, v226
	v_mul_f32_e32 v221, v173, v226
	v_mul_f32_e32 v222, v174, v226
	v_mul_f32_e32 v223, v175, v226
	v_mul_f32_e32 v208, v208, v56
	v_mul_f32_e32 v209, v209, v57
	v_mul_f32_e32 v210, v210, v58
	v_mul_f32_e32 v211, v211, v59
	v_mul_f32_e32 v212, v212, v60
	v_mul_f32_e32 v213, v213, v61
	v_mul_f32_e32 v214, v214, v62
	v_mul_f32_e32 v215, v215, v63
	v_mul_f32_e32 v216, v216, v64
	v_mul_f32_e32 v217, v217, v65
	v_mul_f32_e32 v218, v218, v66
	v_mul_f32_e32 v219, v219, v67
	v_mul_f32_e32 v220, v220, v68
	v_mul_f32_e32 v221, v221, v69
	v_mul_f32_e32 v222, v222, v70
	v_mul_f32_e32 v223, v223, v71
	v_cvt_pk_bf16_f32 v176, v208, v209
	v_cvt_pk_bf16_f32 v177, v210, v211
	v_cvt_pk_bf16_f32 v178, v212, v213
	v_cvt_pk_bf16_f32 v179, v214, v215
	v_cvt_pk_bf16_f32 v180, v216, v217
	v_cvt_pk_bf16_f32 v181, v218, v219
	v_cvt_pk_bf16_f32 v182, v220, v221
	v_cvt_pk_bf16_f32 v183, v222, v223
	global_store_dwordx4 v2, v[176:179], s[14:15]
	global_store_dwordx4 v2, v[180:183], s[14:15] offset:1024
	s_add_u32 s14, s14, 0x800
	s_addc_u32 s15, s15, 0
	s_waitcnt vmcnt(10)
; DI unsigned pk_bf16(float a, float b) { f32x2_t v = {a, b}; bf16x2_t r = __builtin_convertvector(v, bf16x2_t); return __builtin_bit_cast(unsigned, r); }
; DI void row_phase(const bf16_t* msrc, const float* xsrc, float* xdst, const float* g_post, const float* g_next, bf16_t* hdst, const int gw) {
;     ...
;                 for (int j = 0; j < 4; ++j) { const u32x2 mw = *(const u32x2*)(msrc + (size_t)(rowb + r) * DM + lane * 4 + 256 * j);
;                     mv[r][j] = (f32x4){__uint_as_float(mw[0] << 16), __uint_as_float(mw[0] & 0xffff0000u), __uint_as_float(mw[1] << 16), __uint_as_float(mw[1] & 0xffff0000u)}; }
;             float ss[RB];
; #pragma unroll
;             for (int r = 0; r < RB; ++r) { ss[r] = 0.f;
; #pragma unroll
;                 for (int j = 0; j < 4; ++j) ss[r] += mv[r][j][0] * mv[r][j][0] + mv[r][j][1] * mv[r][j][1] + mv[r][j][2] * mv[r][j][2] + mv[r][j][3] * mv[r][j][3]; }
; #pragma unroll
;             for (int o = 32; o >= 1; o >>= 1)
; #pragma unroll
;                 for (int r = 0; r < RB; ++r) ss[r] += shx(ss[r], o);
; #pragma unroll
;             for (int j = 0; j < 4; ++j) { const f32x4 g = *(const f32x4*)(g_post + lane * 4 + 256 * j);
; #pragma unroll
;                 for (int r = 0; r < RB; ++r) { const float r1 = rsqrtf(ss[r] * (1.f / DM) + EPS); xv[r][j] = xv[r][j] + mv[r][j] * r1 * g; *(f32x4*)(xdst + (size_t)(rowb + r) * DM + lane * 4 + 256 * j) = xv[r][j]; } }
;         }
;         if (hdst) {
;             float ss[RB];
; #pragma unroll
;             for (int r = 0; r < RB; ++r) { ss[r] = 0.f;
; #pragma unroll
;                 for (int j = 0; j < 4; ++j) ss[r] += xv[r][j][0] * xv[r][j][0] + xv[r][j][1] * xv[r][j][1] + xv[r][j][2] * xv[r][j][2] + xv[r][j][3] * xv[r][j][3]; }
; #pragma unroll
;             for (int o = 32; o >= 1; o >>= 1)
; #pragma unroll
;                 for (int r = 0; r < RB; ++r) ss[r] += shx(ss[r], o);
; #pragma unroll
;             for (int j = 0; j < 4; ++j) { const f32x4 g = *(const f32x4*)(g_next + lane * 4 + 256 * j);
; #pragma unroll
;                 for (int r = 0; r < RB; ++r) { const float r2 = rsqrtf(ss[r] * (1.f / DM) + EPS); const f32x4 hv = xv[r][j] * r2 * g;
;                     u32x2 o; o[0] = pk_bf16(hv[0], hv[1]); o[1] = pk_bf16(hv[2], hv[3]); *(u32x2*)(hdst + (size_t)(rowb + r) * DM + lane * 4 + 256 * j) = o; } }
	v_lshlrev_b32_e32 v208, 16, v112
	v_and_b32_e32 v209, 0xffff0000, v112
	v_lshlrev_b32_e32 v210, 16, v113
	v_and_b32_e32 v211, 0xffff0000, v113
	v_lshlrev_b32_e32 v212, 16, v114
	v_and_b32_e32 v213, 0xffff0000, v114
	v_lshlrev_b32_e32 v214, 16, v115
	v_and_b32_e32 v215, 0xffff0000, v115
	v_lshlrev_b32_e32 v216, 16, v116
	v_and_b32_e32 v217, 0xffff0000, v116
	v_lshlrev_b32_e32 v218, 16, v117
	v_and_b32_e32 v219, 0xffff0000, v117
	v_lshlrev_b32_e32 v220, 16, v118
	v_and_b32_e32 v221, 0xffff0000, v118
	v_lshlrev_b32_e32 v222, 16, v119
	v_and_b32_e32 v223, 0xffff0000, v119
	v_mul_f32_e32 v224, v208, v208
	v_fmac_f32_e32 v224, v209, v209
	v_fmac_f32_e32 v224, v210, v210
	v_fmac_f32_e32 v224, v211, v211
	v_fmac_f32_e32 v224, v212, v212
	v_fmac_f32_e32 v224, v213, v213
	v_fmac_f32_e32 v224, v214, v214
	v_fmac_f32_e32 v224, v215, v215
	v_fmac_f32_e32 v224, v216, v216
	v_fmac_f32_e32 v224, v217, v217
	v_fmac_f32_e32 v224, v218, v218
	v_fmac_f32_e32 v224, v219, v219
	v_fmac_f32_e32 v224, v220, v220
	v_fmac_f32_e32 v224, v221, v221
	v_fmac_f32_e32 v224, v222, v222
	v_fmac_f32_e32 v224, v223, v223
	s_nop 1
	v_add_f32_dpp v224, v224, v224 quad_perm:[1,0,3,2] row_mask:0xf bank_mask:0xf
	s_nop 1
	v_add_f32_dpp v224, v224, v224 quad_perm:[2,3,0,1] row_mask:0xf bank_mask:0xf
	s_nop 1
	v_add_f32_dpp v224, v224, v224 row_ror:4 row_mask:0xf bank_mask:0xf
	s_nop 1
	v_add_f32_dpp v224, v224, v224 row_ror:8 row_mask:0xf bank_mask:0xf
	s_nop 1
	v_readlane_b32 s20, v224, 0
	v_readlane_b32 s21, v224, 16
	v_readlane_b32 s22, v224, 32
	v_readlane_b32 s23, v224, 48
	s_nop 1
	v_mov_b32_e32 v225, s20
	v_add_f32_e32 v225, s21, v225
	v_add_f32_e32 v225, s22, v225
	v_add_f32_e32 v225, s23, v225
	v_mov_b32_e32 v226, 0x358637bd
	v_fmac_f32_e32 v226, 0x3a800000, v225
	v_rsq_f32_e32 v226, v226
	s_nop 0
	v_mul_f32_e32 v208, v208, v226
	v_mul_f32_e32 v209, v209, v226
	v_mul_f32_e32 v210, v210, v226
	v_mul_f32_e32 v211, v211, v226
	v_mul_f32_e32 v212, v212, v226
	v_mul_f32_e32 v213, v213, v226
	v_mul_f32_e32 v214, v214, v226
	v_mul_f32_e32 v215, v215, v226
	v_mul_f32_e32 v216, v216, v226
	v_mul_f32_e32 v217, v217, v226
	v_mul_f32_e32 v218, v218, v226
	v_mul_f32_e32 v219, v219, v226
	v_mul_f32_e32 v220, v220, v226
	v_mul_f32_e32 v221, v221, v226
	v_mul_f32_e32 v222, v222, v226
	v_mul_f32_e32 v223, v223, v226
	v_fmac_f32_e32 v96, v208, v40
	v_fmac_f32_e32 v97, v209, v41
	v_fmac_f32_e32 v98, v210, v42
	v_fmac_f32_e32 v99, v211, v43
	v_fmac_f32_e32 v100, v212, v44
	v_fmac_f32_e32 v101, v213, v45
	v_fmac_f32_e32 v102, v214, v46
	v_fmac_f32_e32 v103, v215, v47
	v_fmac_f32_e32 v104, v216, v48
	v_fmac_f32_e32 v105, v217, v49
	v_fmac_f32_e32 v106, v218, v50
	v_fmac_f32_e32 v107, v219, v51
	v_fmac_f32_e32 v108, v220, v52
	v_fmac_f32_e32 v109, v221, v53
	v_fmac_f32_e32 v110, v222, v54
	v_fmac_f32_e32 v111, v223, v55
	v_mul_f32_e32 v224, v96, v96
	v_fmac_f32_e32 v224, v97, v97
	v_fmac_f32_e32 v224, v98, v98
	v_fmac_f32_e32 v224, v99, v99
	v_fmac_f32_e32 v224, v100, v100
	v_fmac_f32_e32 v224, v101, v101
	v_fmac_f32_e32 v224, v102, v102
	v_fmac_f32_e32 v224, v103, v103
	v_fmac_f32_e32 v224, v104, v104
	v_fmac_f32_e32 v224, v105, v105
	v_fmac_f32_e32 v224, v106, v106
	v_fmac_f32_e32 v224, v107, v107
	v_fmac_f32_e32 v224, v108, v108
	v_fmac_f32_e32 v224, v109, v109
	v_fmac_f32_e32 v224, v110, v110
	v_fmac_f32_e32 v224, v111, v111
	s_nop 1
	v_add_f32_dpp v224, v224, v224 quad_perm:[1,0,3,2] row_mask:0xf bank_mask:0xf
	s_nop 1
	v_add_f32_dpp v224, v224, v224 quad_perm:[2,3,0,1] row_mask:0xf bank_mask:0xf
	s_nop 1
	v_add_f32_dpp v224, v224, v224 row_ror:4 row_mask:0xf bank_mask:0xf
	s_nop 1
	v_add_f32_dpp v224, v224, v224 row_ror:8 row_mask:0xf bank_mask:0xf
	s_nop 1
	v_readlane_b32 s20, v224, 0
	v_readlane_b32 s21, v224, 16
	v_readlane_b32 s22, v224, 32
	v_readlane_b32 s23, v224, 48
	s_nop 1
	v_mov_b32_e32 v225, s20
	v_add_f32_e32 v225, s21, v225
	v_add_f32_e32 v225, s22, v225
	v_add_f32_e32 v225, s23, v225
	v_mov_b32_e32 v226, 0x358637bd
	v_fmac_f32_e32 v226, 0x3a800000, v225
	v_rsq_f32_e32 v226, v226
	s_nop 0
	v_mul_f32_e32 v208, v96, v226
	v_mul_f32_e32 v209, v97, v226
	v_mul_f32_e32 v210, v98, v226
	v_mul_f32_e32 v211, v99, v226
	v_mul_f32_e32 v212, v100, v226
	v_mul_f32_e32 v213, v101, v226
	v_mul_f32_e32 v214, v102, v226
	v_mul_f32_e32 v215, v103, v226
	v_mul_f32_e32 v216, v104, v226
	v_mul_f32_e32 v217, v105, v226
	v_mul_f32_e32 v218, v106, v226
	v_mul_f32_e32 v219, v107, v226
	v_mul_f32_e32 v220, v108, v226
	v_mul_f32_e32 v221, v109, v226
	v_mul_f32_e32 v222, v110, v226
	v_mul_f32_e32 v223, v111, v226
	v_mul_f32_e32 v208, v208, v56
	v_mul_f32_e32 v209, v209, v57
	v_mul_f32_e32 v210, v210, v58
	v_mul_f32_e32 v211, v211, v59
	v_mul_f32_e32 v212, v212, v60
	v_mul_f32_e32 v213, v213, v61
	v_mul_f32_e32 v214, v214, v62
	v_mul_f32_e32 v215, v215, v63
	v_mul_f32_e32 v216, v216, v64
	v_mul_f32_e32 v217, v217, v65
	v_mul_f32_e32 v218, v218, v66
	v_mul_f32_e32 v219, v219, v67
	v_mul_f32_e32 v220, v220, v68
	v_mul_f32_e32 v221, v221, v69
	v_mul_f32_e32 v222, v222, v70
	v_mul_f32_e32 v223, v223, v71
	v_cvt_pk_bf16_f32 v112, v208, v209
	v_cvt_pk_bf16_f32 v113, v210, v211
	v_cvt_pk_bf16_f32 v114, v212, v213
	v_cvt_pk_bf16_f32 v115, v214, v215
	v_cvt_pk_bf16_f32 v116, v216, v217
	v_cvt_pk_bf16_f32 v117, v218, v219
	v_cvt_pk_bf16_f32 v118, v220, v221
	v_cvt_pk_bf16_f32 v119, v222, v223
	global_store_dwordx4 v2, v[112:115], s[14:15]
	global_store_dwordx4 v2, v[116:119], s[14:15] offset:1024
	s_add_u32 s14, s14, 0x800
	s_addc_u32 s15, s15, 0
	s_waitcnt vmcnt(4)
; DI unsigned pk_bf16(float a, float b) { f32x2_t v = {a, b}; bf16x2_t r = __builtin_convertvector(v, bf16x2_t); return __builtin_bit_cast(unsigned, r); }
; DI float shx(float v, int mask) { const int l = olane(); return __builtin_bit_cast(float, __builtin_amdgcn_ds_bpermute(((l ^ mask) & 63) << 2, __builtin_bit_cast(int, v))); }
; DI void row_phase(const bf16_t* msrc, const float* xsrc, float* xdst, const float* g_post, const float* g_next, bf16_t* hdst, const int gw) {
;     ...
;                 for (int r = 0; r < RB; ++r) { const float r1 = rsqrtf(ss[r] * (1.f / DM) + EPS); xv[r][j] = xv[r][j] + mv[r][j] * r1 * g; *(f32x4*)(xdst + (size_t)(rowb + r) * DM + lane * 4 + 256 * j) = xv[r][j]; } }
;         }
;         if (hdst) {
;             float ss[RB];
; #pragma unroll
;             for (int r = 0; r < RB; ++r) { ss[r] = 0.f;
; #pragma unroll
;                 for (int j = 0; j < 4; ++j) ss[r] += xv[r][j][0] * xv[r][j][0] + xv[r][j][1] * xv[r][j][1] + xv[r][j][2] * xv[r][j][2] + xv[r][j][3] * xv[r][j][3]; }
; #pragma unroll
;             for (int o = 32; o >= 1; o >>= 1)
; #pragma unroll
;                 for (int r = 0; r < RB; ++r) ss[r] += shx(ss[r], o);
; #pragma unroll
;             for (int j = 0; j < 4; ++j) { const f32x4 g = *(const f32x4*)(g_next + lane * 4 + 256 * j);
; #pragma unroll
;                 for (int r = 0; r < RB; ++r) { const float r2 = rsqrtf(ss[r] * (1.f / DM) + EPS); const f32x4 hv = xv[r][j] * r2 * g;
;                     u32x2 o; o[0] = pk_bf16(hv[0], hv[1]); o[1] = pk_bf16(hv[2], hv[3]); *(u32x2*)(hdst + (size_t)(rowb + r) * DM + lane * 4 + 256 * j) = o; } }
	v_lshlrev_b32_e32 v208, 16, v144
	v_and_b32_e32 v209, 0xffff0000, v144
	v_lshlrev_b32_e32 v210, 16, v145
	v_and_b32_e32 v211, 0xffff0000, v145
	v_lshlrev_b32_e32 v212, 16, v146
	v_and_b32_e32 v213, 0xffff0000, v146
	v_lshlrev_b32_e32 v214, 16, v147
	v_and_b32_e32 v215, 0xffff0000, v147
	v_lshlrev_b32_e32 v216, 16, v148
	v_and_b32_e32 v217, 0xffff0000, v148
	v_lshlrev_b32_e32 v218, 16, v149
	v_and_b32_e32 v219, 0xffff0000, v149
	v_lshlrev_b32_e32 v220, 16, v150
	v_and_b32_e32 v221, 0xffff0000, v150
	v_lshlrev_b32_e32 v222, 16, v151
	v_and_b32_e32 v223, 0xffff0000, v151
	v_mul_f32_e32 v224, v208, v208
	v_fmac_f32_e32 v224, v209, v209
	v_fmac_f32_e32 v224, v210, v210
	v_fmac_f32_e32 v224, v211, v211
	v_fmac_f32_e32 v224, v212, v212
	v_fmac_f32_e32 v224, v213, v213
	v_fmac_f32_e32 v224, v214, v214
	v_fmac_f32_e32 v224, v215, v215
	v_fmac_f32_e32 v224, v216, v216
	v_fmac_f32_e32 v224, v217, v217
	v_fmac_f32_e32 v224, v218, v218
	v_fmac_f32_e32 v224, v219, v219
	v_fmac_f32_e32 v224, v220, v220
	v_fmac_f32_e32 v224, v221, v221
	v_fmac_f32_e32 v224, v222, v222
	v_fmac_f32_e32 v224, v223, v223
	s_nop 1
	v_add_f32_dpp v224, v224, v224 quad_perm:[1,0,3,2] row_mask:0xf bank_mask:0xf
	s_nop 1
	v_add_f32_dpp v224, v224, v224 quad_perm:[2,3,0,1] row_mask:0xf bank_mask:0xf
	s_nop 1
	v_add_f32_dpp v224, v224, v224 row_ror:4 row_mask:0xf bank_mask:0xf
	s_nop 1
	v_add_f32_dpp v224, v224, v224 row_ror:8 row_mask:0xf bank_mask:0xf
	s_nop 1
	v_readlane_b32 s20, v224, 0
	v_readlane_b32 s21, v224, 16
	v_readlane_b32 s22, v224, 32
	v_readlane_b32 s23, v224, 48
	s_nop 1
	v_mov_b32_e32 v225, s20
	v_add_f32_e32 v225, s21, v225
	v_add_f32_e32 v225, s22, v225
	v_add_f32_e32 v225, s23, v225
	v_mov_b32_e32 v226, 0x358637bd
	v_fmac_f32_e32 v226, 0x3a800000, v225
	v_rsq_f32_e32 v226, v226
	s_nop 0
	v_mul_f32_e32 v208, v208, v226
	v_mul_f32_e32 v209, v209, v226
	v_mul_f32_e32 v210, v210, v226
	v_mul_f32_e32 v211, v211, v226
	v_mul_f32_e32 v212, v212, v226
	v_mul_f32_e32 v213, v213, v226
	v_mul_f32_e32 v214, v214, v226
	v_mul_f32_e32 v215, v215, v226
	v_mul_f32_e32 v216, v216, v226
	v_mul_f32_e32 v217, v217, v226
	v_mul_f32_e32 v218, v218, v226
	v_mul_f32_e32 v219, v219, v226
	v_mul_f32_e32 v220, v220, v226
	v_mul_f32_e32 v221, v221, v226
	v_mul_f32_e32 v222, v222, v226
	v_mul_f32_e32 v223, v223, v226
	v_fmac_f32_e32 v128, v208, v40
	v_fmac_f32_e32 v129, v209, v41
	v_fmac_f32_e32 v130, v210, v42
	v_fmac_f32_e32 v131, v211, v43
	v_fmac_f32_e32 v132, v212, v44
	v_fmac_f32_e32 v133, v213, v45
	v_fmac_f32_e32 v134, v214, v46
	v_fmac_f32_e32 v135, v215, v47
	v_fmac_f32_e32 v136, v216, v48
	v_fmac_f32_e32 v137, v217, v49
	v_fmac_f32_e32 v138, v218, v50
	v_fmac_f32_e32 v139, v219, v51
	v_fmac_f32_e32 v140, v220, v52
	v_fmac_f32_e32 v141, v221, v53
	v_fmac_f32_e32 v142, v222, v54
	v_fmac_f32_e32 v143, v223, v55
	v_mul_f32_e32 v224, v128, v128
	v_fmac_f32_e32 v224, v129, v129
	v_fmac_f32_e32 v224, v130, v130
	v_fmac_f32_e32 v224, v131, v131
	v_fmac_f32_e32 v224, v132, v132
	v_fmac_f32_e32 v224, v133, v133
	v_fmac_f32_e32 v224, v134, v134
	v_fmac_f32_e32 v224, v135, v135
	v_fmac_f32_e32 v224, v136, v136
	v_fmac_f32_e32 v224, v137, v137
	v_fmac_f32_e32 v224, v138, v138
	v_fmac_f32_e32 v224, v139, v139
	v_fmac_f32_e32 v224, v140, v140
	v_fmac_f32_e32 v224, v141, v141
	v_fmac_f32_e32 v224, v142, v142
	v_fmac_f32_e32 v224, v143, v143
	s_nop 1
	v_add_f32_dpp v224, v224, v224 quad_perm:[1,0,3,2] row_mask:0xf bank_mask:0xf
	s_nop 1
	v_add_f32_dpp v224, v224, v224 quad_perm:[2,3,0,1] row_mask:0xf bank_mask:0xf
	s_nop 1
	v_add_f32_dpp v224, v224, v224 row_ror:4 row_mask:0xf bank_mask:0xf
	s_nop 1
	v_add_f32_dpp v224, v224, v224 row_ror:8 row_mask:0xf bank_mask:0xf
	s_nop 1
	v_readlane_b32 s20, v224, 0
	v_readlane_b32 s21, v224, 16
	v_readlane_b32 s22, v224, 32
	v_readlane_b32 s23, v224, 48
	s_nop 1
	v_mov_b32_e32 v225, s20
	v_add_f32_e32 v225, s21, v225
	v_add_f32_e32 v225, s22, v225
	v_add_f32_e32 v225, s23, v225
	v_mov_b32_e32 v226, 0x358637bd
	v_fmac_f32_e32 v226, 0x3a800000, v225
	v_rsq_f32_e32 v226, v226
	s_nop 0
	v_mul_f32_e32 v208, v128, v226
	v_mul_f32_e32 v209, v129, v226
	v_mul_f32_e32 v210, v130, v226
	v_mul_f32_e32 v211, v131, v226
	v_mul_f32_e32 v212, v132, v226
	v_mul_f32_e32 v213, v133, v226
	v_mul_f32_e32 v214, v134, v226
	v_mul_f32_e32 v215, v135, v226
	v_mul_f32_e32 v216, v136, v226
	v_mul_f32_e32 v217, v137, v226
	v_mul_f32_e32 v218, v138, v226
	v_mul_f32_e32 v219, v139, v226
	v_mul_f32_e32 v220, v140, v226
	v_mul_f32_e32 v221, v141, v226
	v_mul_f32_e32 v222, v142, v226
	v_mul_f32_e32 v223, v143, v226
	v_mul_f32_e32 v208, v208, v56
	v_mul_f32_e32 v209, v209, v57
	v_mul_f32_e32 v210, v210, v58
	v_mul_f32_e32 v211, v211, v59
	v_mul_f32_e32 v212, v212, v60
	v_mul_f32_e32 v213, v213, v61
	v_mul_f32_e32 v214, v214, v62
	v_mul_f32_e32 v215, v215, v63
	v_mul_f32_e32 v216, v216, v64
	v_mul_f32_e32 v217, v217, v65
	v_mul_f32_e32 v218, v218, v66
	v_mul_f32_e32 v219, v219, v67
	v_mul_f32_e32 v220, v220, v68
	v_mul_f32_e32 v221, v221, v69
	v_mul_f32_e32 v222, v222, v70
	v_mul_f32_e32 v223, v223, v71
	v_cvt_pk_bf16_f32 v144, v208, v209
	v_cvt_pk_bf16_f32 v145, v210, v211
	v_cvt_pk_bf16_f32 v146, v212, v213
	v_cvt_pk_bf16_f32 v147, v214, v215
	v_cvt_pk_bf16_f32 v148, v216, v217
	v_cvt_pk_bf16_f32 v149, v218, v219
	v_cvt_pk_bf16_f32 v150, v220, v221
	v_cvt_pk_bf16_f32 v151, v222, v223
	global_store_dwordx4 v2, v[144:147], s[14:15]
	global_store_dwordx4 v2, v[148:151], s[14:15] offset:1024
	s_add_u32 s14, s14, 0x800
	s_addc_u32 s15, s15, 0
	v_readlane_b32 s4, v3, 0
	v_readlane_b32 s5, v3, 1
	v_readlane_b32 s6, v3, 2
	v_readlane_b32 s7, v3, 3
	v_readlane_b32 s8, v3, 4
	v_readlane_b32 s9, v3, 5
	v_readlane_b32 s10, v3, 6
	v_readlane_b32 s11, v3, 7
	v_readlane_b32 s12, v3, 8
	v_readlane_b32 s13, v3, 9
	v_readlane_b32 s14, v3, 10
	v_readlane_b32 s15, v3, 11
	v_readlane_b32 s16, v3, 12
	v_readlane_b32 s17, v3, 13
	v_readlane_b32 s18, v3, 14
	v_readlane_b32 s19, v3, 15
	v_readlane_b32 s20, v3, 16
	v_readlane_b32 s21, v3, 17
	v_readlane_b32 s22, v3, 18
	v_readlane_b32 s23, v3, 19
	v_readlane_b32 s24, v3, 20
	v_readlane_b32 s25, v3, 21
	s_mov_b32 s6, 0x358637bd
	s_branch .LBB0_79
; DI int obid() { int b = blockIdx.x; asm volatile("" : "+s"(b)); return b; }
; DI int ogrid() { int g = gridDim.x; asm volatile("" : "+s"(g)); return g; }
; DI int otid_w(int gw) { return (gw << 6) | olane(); }
; DI float shx(float v, int mask) { const int l = olane(); return __builtin_bit_cast(float, __builtin_amdgcn_ds_bpermute(((l ^ mask) & 63) << 2, __builtin_bit_cast(int, v))); }
; DI void row_phase(const bf16_t* msrc, const float* xsrc, float* xdst, const float* g_post, const float* g_next, bf16_t* hdst, const int gw) {
;     constexpr int RB = 4;
;     const int tid = otid_w(gw); const int lane = tid & 63, w = tid >> 6;
;     const int wg = obid() * 8 + w, nw = ogrid() * 8;
;     for (int rowb = wg * RB; rowb < M_TOK; rowb += nw * RB) {
;         f32x4 xv[RB][4], mv[RB][4];
; #pragma unroll
;         for (int r = 0; r < RB; ++r)
; #pragma unroll
;             for (int j = 0; j < 4; ++j) xv[r][j] = *(const f32x4*)(xsrc + (size_t)(rowb + r) * DM + lane * 4 + 256 * j);
;         if (msrc) {
; #pragma unroll
;             for (int r = 0; r < RB; ++r)
; #pragma unroll
;                 for (int j = 0; j < 4; ++j) { const u32x2 mw = *(const u32x2*)(msrc + (size_t)(rowb + r) * DM + lane * 4 + 256 * j);
;                     mv[r][j] = (f32x4){__uint_as_float(mw[0] << 16), __uint_as_float(mw[0] & 0xffff0000u), __uint_as_float(mw[1] << 16), __uint_as_float(mw[1] & 0xffff0000u)}; }
;             float ss[RB];
; #pragma unroll
;             for (int r = 0; r < RB; ++r) { ss[r] = 0.f;
; #pragma unroll
;                 for (int j = 0; j < 4; ++j) ss[r] += mv[r][j][0] * mv[r][j][0] + mv[r][j][1] * mv[r][j][1] + mv[r][j][2] * mv[r][j][2] + mv[r][j][3] * mv[r][j][3]; }
; #pragma unroll
;             for (int o = 32; o >= 1; o >>= 1)
; #pragma unroll
;                 for (int r = 0; r < RB; ++r) ss[r] += shx(ss[r], o);
; #pragma unroll
;             for (int j = 0; j < 4; ++j) { const f32x4 g = *(const f32x4*)(g_post + lane * 4 + 256 * j);
; #pragma unroll
;                 for (int r = 0; r < RB; ++r) { const float r1 = rsqrtf(ss[r] * (1.f / DM) + EPS); xv[r][j] = xv[r][j] + mv[r][j] * r1 * g; *(f32x4*)(xdst + (size_t)(rowb + r) * DM + lane * 4 + 256 * j) = xv[r][j]; } }
.Lrow_r2h:
	v_writelane_b32 v3, s4, 0
	v_writelane_b32 v3, s5, 1
	v_writelane_b32 v3, s6, 2
	v_writelane_b32 v3, s7, 3
	v_writelane_b32 v3, s8, 4
	v_writelane_b32 v3, s9, 5
	v_writelane_b32 v3, s10, 6
	v_writelane_b32 v3, s11, 7
	v_writelane_b32 v3, s12, 8
	v_writelane_b32 v3, s13, 9
	v_writelane_b32 v3, s14, 10
	v_writelane_b32 v3, s15, 11
	v_writelane_b32 v3, s16, 12
	v_writelane_b32 v3, s17, 13
	v_writelane_b32 v3, s18, 14
	v_writelane_b32 v3, s19, 15
	v_writelane_b32 v3, s20, 16
	v_writelane_b32 v3, s21, 17
	v_writelane_b32 v3, s22, 18
	v_writelane_b32 v3, s23, 19
	v_writelane_b32 v3, s24, 20
	v_writelane_b32 v3, s25, 21
	s_waitcnt vmcnt(0) lgkmcnt(0)
	v_mbcnt_lo_u32_b32 v0, -1, 0
	v_mbcnt_hi_u32_b32 v0, -1, v0
	v_lshlrev_b32_e32 v1, 5, v0
	v_lshlrev_b32_e32 v2, 4, v0
	s_lshr_b32 s4, s71, 6
	s_lshl_b32 s5, s2, 3
	s_add_i32 s5, s5, s4
	s_lshl_b32 s24, s5, 15
	s_lshl_b32 s25, s5, 14
	v_readlane_b32 s8, v254, 62
	v_readlane_b32 s9, v254, 63
	v_readlane_b32 s6, v255, 2
	v_readlane_b32 s7, v255, 3
	v_readlane_b32 s4, v255, 6
	v_readlane_b32 s16, v255, 10
	v_readlane_b32 s17, v255, 11
	s_nop 1
	s_cmp_eq_u32 s4, 0
	s_cselect_b32 s6, s6, s8
	s_cselect_b32 s7, s7, s9
	s_add_u32 s6, s6, s24
	s_addc_u32 s7, s7, 0
	s_add_u32 s8, s8, s24
	s_addc_u32 s9, s9, 0
	s_add_u32 s10, s68, 0x10681000
	s_addc_u32 s11, s69, 0
	s_add_u32 s10, s10, s25
	s_addc_u32 s11, s11, 0
	s_add_u32 s12, s10, 0x2000000
	s_addc_u32 s13, s11, 0
	s_add_u32 s14, s82, s25
	s_addc_u32 s15, s83, 0
	s_add_u32 s18, s16, 0x1000
	s_addc_u32 s19, s17, 0
	global_load_dwordx4 v[40:43], v1, s[18:19] offset:0
	global_load_dwordx4 v[44:47], v1, s[18:19] offset:16
	global_load_dwordx4 v[48:51], v1, s[18:19] offset:2048
	global_load_dwordx4 v[52:55], v1, s[18:19] offset:2064
	s_add_u32 s18, s16, 0x3000
	s_addc_u32 s19, s17, 0
	global_load_dwordx4 v[56:59], v1, s[18:19] offset:0
	global_load_dwordx4 v[60:63], v1, s[18:19] offset:16
	global_load_dwordx4 v[64:67], v1, s[18:19] offset:2048
	global_load_dwordx4 v[68:71], v1, s[18:19] offset:2064
	s_add_u32 s18, s16, 0x4000
	s_addc_u32 s19, s17, 0
	global_load_dwordx4 v[72:75], v1, s[18:19] offset:0
	global_load_dwordx4 v[76:79], v1, s[18:19] offset:16
	global_load_dwordx4 v[80:83], v1, s[18:19] offset:2048
	global_load_dwordx4 v[84:87], v1, s[18:19] offset:2064
	global_load_dwordx4 v[96:99], v1, s[6:7] offset:0
	global_load_dwordx4 v[100:103], v1, s[6:7] offset:16
	global_load_dwordx4 v[104:107], v1, s[6:7] offset:2048
	global_load_dwordx4 v[108:111], v1, s[6:7] offset:2064
	global_load_dwordx4 v[112:115], v2, s[10:11]
	global_load_dwordx4 v[116:119], v2, s[10:11] offset:1024
	global_load_dwordx4 v[120:123], v2, s[12:13]
	global_load_dwordx4 v[124:127], v2, s[12:13] offset:1024
	s_add_u32 s6, s6, 0x1000
	s_addc_u32 s7, s7, 0
	s_add_u32 s10, s10, 0x800
	s_addc_u32 s11, s11, 0
	s_add_u32 s12, s12, 0x800
	s_addc_u32 s13, s13, 0
	global_load_dwordx4 v[128:131], v1, s[6:7] offset:0
	global_load_dwordx4 v[132:135], v1, s[6:7] offset:16
	global_load_dwordx4 v[136:139], v1, s[6:7] offset:2048
	global_load_dwordx4 v[140:143], v1, s[6:7] offset:2064
	global_load_dwordx4 v[144:147], v2, s[10:11]
	global_load_dwordx4 v[148:151], v2, s[10:11] offset:1024
	global_load_dwordx4 v[152:155], v2, s[12:13]
	global_load_dwordx4 v[156:159], v2, s[12:13] offset:1024
	s_add_u32 s6, s6, 0x1000
	s_addc_u32 s7, s7, 0
	s_add_u32 s10, s10, 0x800
	s_addc_u32 s11, s11, 0
	s_add_u32 s12, s12, 0x800
	s_addc_u32 s13, s13, 0
	global_load_dwordx4 v[160:163], v1, s[6:7] offset:0
	global_load_dwordx4 v[164:167], v1, s[6:7] offset:16
	global_load_dwordx4 v[168:171], v1, s[6:7] offset:2048
	global_load_dwordx4 v[172:175], v1, s[6:7] offset:2064
	global_load_dwordx4 v[176:179], v2, s[10:11]
	global_load_dwordx4 v[180:183], v2, s[10:11] offset:1024
	global_load_dwordx4 v[184:187], v2, s[12:13]
	global_load_dwordx4 v[188:191], v2, s[12:13] offset:1024
	s_add_u32 s6, s6, 0x1000
	s_addc_u32 s7, s7, 0
	s_add_u32 s10, s10, 0x800
	s_addc_u32 s11, s11, 0
	s_add_u32 s12, s12, 0x800
	s_addc_u32 s13, s13, 0
	s_waitcnt vmcnt(16)
	v_lshlrev_b32_e32 v208, 16, v112
	v_and_b32_e32 v209, 0xffff0000, v112
	v_lshlrev_b32_e32 v210, 16, v113
	v_and_b32_e32 v211, 0xffff0000, v113
	v_lshlrev_b32_e32 v212, 16, v114
	v_and_b32_e32 v213, 0xffff0000, v114
	v_lshlrev_b32_e32 v214, 16, v115
	v_and_b32_e32 v215, 0xffff0000, v115
	v_lshlrev_b32_e32 v216, 16, v116
	v_and_b32_e32 v217, 0xffff0000, v116
	v_lshlrev_b32_e32 v218, 16, v117
	v_and_b32_e32 v219, 0xffff0000, v117
	v_lshlrev_b32_e32 v220, 16, v118
	v_and_b32_e32 v221, 0xffff0000, v118
	v_lshlrev_b32_e32 v222, 16, v119
	v_and_b32_e32 v223, 0xffff0000, v119
	v_mul_f32_e32 v224, v208, v208
	v_fmac_f32_e32 v224, v209, v209
	v_fmac_f32_e32 v224, v210, v210
	v_fmac_f32_e32 v224, v211, v211
	v_fmac_f32_e32 v224, v212, v212
	v_fmac_f32_e32 v224, v213, v213
	v_fmac_f32_e32 v224, v214, v214
	v_fmac_f32_e32 v224, v215, v215
	v_fmac_f32_e32 v224, v216, v216
	v_fmac_f32_e32 v224, v217, v217
	v_fmac_f32_e32 v224, v218, v218
	v_fmac_f32_e32 v224, v219, v219
	v_fmac_f32_e32 v224, v220, v220
	v_fmac_f32_e32 v224, v221, v221
	v_fmac_f32_e32 v224, v222, v222
	v_fmac_f32_e32 v224, v223, v223
	s_nop 1
	v_add_f32_dpp v224, v224, v224 quad_perm:[1,0,3,2] row_mask:0xf bank_mask:0xf
	s_nop 1
	v_add_f32_dpp v224, v224, v224 quad_perm:[2,3,0,1] row_mask:0xf bank_mask:0xf
	s_nop 1
	v_add_f32_dpp v224, v224, v224 row_ror:4 row_mask:0xf bank_mask:0xf
	s_nop 1
	v_add_f32_dpp v224, v224, v224 row_ror:8 row_mask:0xf bank_mask:0xf
	s_nop 1
	v_readlane_b32 s20, v224, 0
	v_readlane_b32 s21, v224, 16
	v_readlane_b32 s22, v224, 32
	v_readlane_b32 s23, v224, 48
	s_nop 1
	v_mov_b32_e32 v225, s20
; DI unsigned pk_bf16(float a, float b) { f32x2_t v = {a, b}; bf16x2_t r = __builtin_convertvector(v, bf16x2_t); return __builtin_bit_cast(unsigned, r); }
; DI void row_phase(const bf16_t* msrc, const float* xsrc, float* xdst, const float* g_post, const float* g_next, bf16_t* hdst, const int gw) {
;     ...
;                 for (int j = 0; j < 4; ++j) { const u32x2 mw = *(const u32x2*)(msrc + (size_t)(rowb + r) * DM + lane * 4 + 256 * j);
;                     mv[r][j] = (f32x4){__uint_as_float(mw[0] << 16), __uint_as_float(mw[0] & 0xffff0000u), __uint_as_float(mw[1] << 16), __uint_as_float(mw[1] & 0xffff0000u)}; }
;             float ss[RB];
; #pragma unroll
;             for (int r = 0; r < RB; ++r) { ss[r] = 0.f;
; #pragma unroll
;                 for (int j = 0; j < 4; ++j) ss[r] += mv[r][j][0] * mv[r][j][0] + mv[r][j][1] * mv[r][j][1] + mv[r][j][2] * mv[r][j][2] + mv[r][j][3] * mv[r][j][3]; }
; #pragma unroll
;             for (int o = 32; o >= 1; o >>= 1)
; #pragma unroll
;                 for (int r = 0; r < RB; ++r) ss[r] += shx(ss[r], o);
; #pragma unroll
;             for (int j = 0; j < 4; ++j) { const f32x4 g = *(const f32x4*)(g_post + lane * 4 + 256 * j);
; #pragma unroll
;                 for (int r = 0; r < RB; ++r) { const float r1 = rsqrtf(ss[r] * (1.f / DM) + EPS); xv[r][j] = xv[r][j] + mv[r][j] * r1 * g; *(f32x4*)(xdst + (size_t)(rowb + r) * DM + lane * 4 + 256 * j) = xv[r][j]; } }
;         }
;         if (hdst) {
;             float ss[RB];
; #pragma unroll
;             for (int r = 0; r < RB; ++r) { ss[r] = 0.f;
; #pragma unroll
;                 for (int j = 0; j < 4; ++j) ss[r] += xv[r][j][0] * xv[r][j][0] + xv[r][j][1] * xv[r][j][1] + xv[r][j][2] * xv[r][j][2] + xv[r][j][3] * xv[r][j][3]; }
; #pragma unroll
;             for (int o = 32; o >= 1; o >>= 1)
; #pragma unroll
;                 for (int r = 0; r < RB; ++r) ss[r] += shx(ss[r], o);
; #pragma unroll
;             for (int j = 0; j < 4; ++j) { const f32x4 g = *(const f32x4*)(g_next + lane * 4 + 256 * j);
; #pragma unroll
;                 for (int r = 0; r < RB; ++r) { const float r2 = rsqrtf(ss[r] * (1.f / DM) + EPS); const f32x4 hv = xv[r][j] * r2 * g;
;                     u32x2 o; o[0] = pk_bf16(hv[0], hv[1]); o[1] = pk_bf16(hv[2], hv[3]); *(u32x2*)(hdst + (size_t)(rowb + r) * DM + lane * 4 + 256 * j) = o; } }
	v_add_f32_e32 v225, s21, v225
	v_add_f32_e32 v225, s22, v225
	v_add_f32_e32 v225, s23, v225
	v_mov_b32_e32 v226, 0x358637bd
	v_fmac_f32_e32 v226, 0x3a800000, v225
	v_rsq_f32_e32 v226, v226
	s_nop 0
	v_mul_f32_e32 v208, v208, v226
	v_mul_f32_e32 v209, v209, v226
	v_mul_f32_e32 v210, v210, v226
	v_mul_f32_e32 v211, v211, v226
	v_mul_f32_e32 v212, v212, v226
	v_mul_f32_e32 v213, v213, v226
	v_mul_f32_e32 v214, v214, v226
	v_mul_f32_e32 v215, v215, v226
	v_mul_f32_e32 v216, v216, v226
	v_mul_f32_e32 v217, v217, v226
	v_mul_f32_e32 v218, v218, v226
	v_mul_f32_e32 v219, v219, v226
	v_mul_f32_e32 v220, v220, v226
	v_mul_f32_e32 v221, v221, v226
	v_mul_f32_e32 v222, v222, v226
	v_mul_f32_e32 v223, v223, v226
	v_fmac_f32_e32 v96, v208, v40
	v_fmac_f32_e32 v97, v209, v41
	v_fmac_f32_e32 v98, v210, v42
	v_fmac_f32_e32 v99, v211, v43
	v_fmac_f32_e32 v100, v212, v44
	v_fmac_f32_e32 v101, v213, v45
	v_fmac_f32_e32 v102, v214, v46
	v_fmac_f32_e32 v103, v215, v47
	v_fmac_f32_e32 v104, v216, v48
	v_fmac_f32_e32 v105, v217, v49
	v_fmac_f32_e32 v106, v218, v50
	v_fmac_f32_e32 v107, v219, v51
	v_fmac_f32_e32 v108, v220, v52
	v_fmac_f32_e32 v109, v221, v53
	v_fmac_f32_e32 v110, v222, v54
	v_fmac_f32_e32 v111, v223, v55
	v_lshlrev_b32_e32 v208, 16, v120
	v_and_b32_e32 v209, 0xffff0000, v120
	v_lshlrev_b32_e32 v210, 16, v121
	v_and_b32_e32 v211, 0xffff0000, v121
	v_lshlrev_b32_e32 v212, 16, v122
	v_and_b32_e32 v213, 0xffff0000, v122
	v_lshlrev_b32_e32 v214, 16, v123
	v_and_b32_e32 v215, 0xffff0000, v123
	v_lshlrev_b32_e32 v216, 16, v124
	v_and_b32_e32 v217, 0xffff0000, v124
	v_lshlrev_b32_e32 v218, 16, v125
	v_and_b32_e32 v219, 0xffff0000, v125
	v_lshlrev_b32_e32 v220, 16, v126
	v_and_b32_e32 v221, 0xffff0000, v126
	v_lshlrev_b32_e32 v222, 16, v127
	v_and_b32_e32 v223, 0xffff0000, v127
	v_mul_f32_e32 v224, v208, v208
	v_fmac_f32_e32 v224, v209, v209
	v_fmac_f32_e32 v224, v210, v210
	v_fmac_f32_e32 v224, v211, v211
	v_fmac_f32_e32 v224, v212, v212
	v_fmac_f32_e32 v224, v213, v213
	v_fmac_f32_e32 v224, v214, v214
	v_fmac_f32_e32 v224, v215, v215
	v_fmac_f32_e32 v224, v216, v216
	v_fmac_f32_e32 v224, v217, v217
	v_fmac_f32_e32 v224, v218, v218
	v_fmac_f32_e32 v224, v219, v219
	v_fmac_f32_e32 v224, v220, v220
	v_fmac_f32_e32 v224, v221, v221
	v_fmac_f32_e32 v224, v222, v222
	v_fmac_f32_e32 v224, v223, v223
	s_nop 1
	v_add_f32_dpp v224, v224, v224 quad_perm:[1,0,3,2] row_mask:0xf bank_mask:0xf
	s_nop 1
	v_add_f32_dpp v224, v224, v224 quad_perm:[2,3,0,1] row_mask:0xf bank_mask:0xf
	s_nop 1
	v_add_f32_dpp v224, v224, v224 row_ror:4 row_mask:0xf bank_mask:0xf
	s_nop 1
	v_add_f32_dpp v224, v224, v224 row_ror:8 row_mask:0xf bank_mask:0xf
	s_nop 1
	v_readlane_b32 s20, v224, 0
	v_readlane_b32 s21, v224, 16
	v_readlane_b32 s22, v224, 32
	v_readlane_b32 s23, v224, 48
	s_nop 1
	v_mov_b32_e32 v225, s20
	v_add_f32_e32 v225, s21, v225
	v_add_f32_e32 v225, s22, v225
	v_add_f32_e32 v225, s23, v225
	v_mov_b32_e32 v226, 0x358637bd
	v_fmac_f32_e32 v226, 0x3a800000, v225
	v_rsq_f32_e32 v226, v226
	s_nop 0
	v_mul_f32_e32 v208, v208, v226
	v_mul_f32_e32 v209, v209, v226
	v_mul_f32_e32 v210, v210, v226
	v_mul_f32_e32 v211, v211, v226
	v_mul_f32_e32 v212, v212, v226
	v_mul_f32_e32 v213, v213, v226
	v_mul_f32_e32 v214, v214, v226
	v_mul_f32_e32 v215, v215, v226
	v_mul_f32_e32 v216, v216, v226
	v_mul_f32_e32 v217, v217, v226
	v_mul_f32_e32 v218, v218, v226
	v_mul_f32_e32 v219, v219, v226
	v_mul_f32_e32 v220, v220, v226
	v_mul_f32_e32 v221, v221, v226
	v_mul_f32_e32 v222, v222, v226
	v_mul_f32_e32 v223, v223, v226
	v_fmac_f32_e32 v96, v208, v56
	v_fmac_f32_e32 v97, v209, v57
	v_fmac_f32_e32 v98, v210, v58
	v_fmac_f32_e32 v99, v211, v59
	v_fmac_f32_e32 v100, v212, v60
	v_fmac_f32_e32 v101, v213, v61
	v_fmac_f32_e32 v102, v214, v62
	v_fmac_f32_e32 v103, v215, v63
	v_fmac_f32_e32 v104, v216, v64
	v_fmac_f32_e32 v105, v217, v65
	v_fmac_f32_e32 v106, v218, v66
	v_fmac_f32_e32 v107, v219, v67
	v_fmac_f32_e32 v108, v220, v68
	v_fmac_f32_e32 v109, v221, v69
	v_fmac_f32_e32 v110, v222, v70
	v_fmac_f32_e32 v111, v223, v71
	global_store_dwordx4 v1, v[96:99], s[8:9] offset:0
	global_store_dwordx4 v1, v[100:103], s[8:9] offset:16
	global_store_dwordx4 v1, v[104:107], s[8:9] offset:2048
	global_store_dwordx4 v1, v[108:111], s[8:9] offset:2064
	s_add_u32 s8, s8, 0x1000
	s_addc_u32 s9, s9, 0
	v_mul_f32_e32 v224, v96, v96
	v_fmac_f32_e32 v224, v97, v97
	v_fmac_f32_e32 v224, v98, v98
	v_fmac_f32_e32 v224, v99, v99
	v_fmac_f32_e32 v224, v100, v100
	v_fmac_f32_e32 v224, v101, v101
	v_fmac_f32_e32 v224, v102, v102
	v_fmac_f32_e32 v224, v103, v103
	v_fmac_f32_e32 v224, v104, v104
	v_fmac_f32_e32 v224, v105, v105
	v_fmac_f32_e32 v224, v106, v106
	v_fmac_f32_e32 v224, v107, v107
	v_fmac_f32_e32 v224, v108, v108
	v_fmac_f32_e32 v224, v109, v109
	v_fmac_f32_e32 v224, v110, v110
	v_fmac_f32_e32 v224, v111, v111
	s_nop 1
	v_add_f32_dpp v224, v224, v224 quad_perm:[1,0,3,2] row_mask:0xf bank_mask:0xf
	s_nop 1
	v_add_f32_dpp v224, v224, v224 quad_perm:[2,3,0,1] row_mask:0xf bank_mask:0xf
	s_nop 1
	v_add_f32_dpp v224, v224, v224 row_ror:4 row_mask:0xf bank_mask:0xf
	s_nop 1
	v_add_f32_dpp v224, v224, v224 row_ror:8 row_mask:0xf bank_mask:0xf
	s_nop 1
	v_readlane_b32 s20, v224, 0
	v_readlane_b32 s21, v224, 16
	v_readlane_b32 s22, v224, 32
	v_readlane_b32 s23, v224, 48
	s_nop 1
	v_mov_b32_e32 v225, s20
	v_add_f32_e32 v225, s21, v225
	v_add_f32_e32 v225, s22, v225
	v_add_f32_e32 v225, s23, v225
	v_mov_b32_e32 v226, 0x358637bd
	v_fmac_f32_e32 v226, 0x3a800000, v225
	v_rsq_f32_e32 v226, v226
	s_nop 0
	v_mul_f32_e32 v208, v96, v226
	v_mul_f32_e32 v209, v97, v226
	v_mul_f32_e32 v210, v98, v226
	v_mul_f32_e32 v211, v99, v226
; DI void row_phase(const bf16_t* msrc, const float* xsrc, float* xdst, const float* g_post, const float* g_next, bf16_t* hdst, const int gw) {
;     ...
;             for (int j = 0; j < 4; ++j) xv[r][j] = *(const f32x4*)(xsrc + (size_t)(rowb + r) * DM + lane * 4 + 256 * j);
;         if (msrc) {
; #pragma unroll
;             for (int r = 0; r < RB; ++r)
; #pragma unroll
;                 for (int j = 0; j < 4; ++j) { const u32x2 mw = *(const u32x2*)(msrc + (size_t)(rowb + r) * DM + lane * 4 + 256 * j);
;                     mv[r][j] = (f32x4){__uint_as_float(mw[0] << 16), __uint_as_float(mw[0] & 0xffff0000u), __uint_as_float(mw[1] << 16), __uint_as_float(mw[1] & 0xffff0000u)}; }
;             float ss[RB];
; #pragma unroll
;             for (int r = 0; r < RB; ++r) { ss[r] = 0.f;
; #pragma unroll
;                 for (int j = 0; j < 4; ++j) ss[r] += mv[r][j][0] * mv[r][j][0] + mv[r][j][1] * mv[r][j][1] + mv[r][j][2] * mv[r][j][2] + mv[r][j][3] * mv[r][j][3]; }
; #pragma unroll
;             for (int o = 32; o >= 1; o >>= 1)
; #pragma unroll
;                 for (int r = 0; r < RB; ++r) ss[r] += shx(ss[r], o);
; #pragma unroll
;             for (int j = 0; j < 4; ++j) { const f32x4 g = *(const f32x4*)(g_post + lane * 4 + 256 * j);
; #pragma unroll
;                 for (int r = 0; r < RB; ++r) { const float r1 = rsqrtf(ss[r] * (1.f / DM) + EPS); xv[r][j] = xv[r][j] + mv[r][j] * r1 * g; *(f32x4*)(xdst + (size_t)(rowb + r) * DM + lane * 4 + 256 * j) = xv[r][j]; } }
;         }
;         if (hdst) {
;             float ss[RB];
; #pragma unroll
;             for (int r = 0; r < RB; ++r) { ss[r] = 0.f;
; #pragma unroll
;                 for (int j = 0; j < 4; ++j) ss[r] += xv[r][j][0] * xv[r][j][0] + xv[r][j][1] * xv[r][j][1] + xv[r][j][2] * xv[r][j][2] + xv[r][j][3] * xv[r][j][3]; }
; #pragma unroll
;             for (int o = 32; o >= 1; o >>= 1)
; #pragma unroll
;                 for (int r = 0; r < RB; ++r) ss[r] += shx(ss[r], o);
; #pragma unroll
;             for (int j = 0; j < 4; ++j) { const f32x4 g = *(const f32x4*)(g_next + lane * 4 + 256 * j);
; #pragma unroll
;                 for (int r = 0; r < RB; ++r) { const float r2 = rsqrtf(ss[r] * (1.f / DM) + EPS); const f32x4 hv = xv[r][j] * r2 * g;
;                     u32x2 o; o[0] = pk_bf16(hv[0], hv[1]); o[1] = pk_bf16(hv[2], hv[3]); *(u32x2*)(hdst + (size_t)(rowb + r) * DM + lane * 4 + 256 * j) = o; } }
	v_mul_f32_e32 v212, v100, v226
	v_mul_f32_e32 v213, v101, v226
	v_mul_f32_e32 v214, v102, v226
	v_mul_f32_e32 v215, v103, v226
	v_mul_f32_e32 v216, v104, v226
	v_mul_f32_e32 v217, v105, v226
	v_mul_f32_e32 v218, v106, v226
	v_mul_f32_e32 v219, v107, v226
	v_mul_f32_e32 v220, v108, v226
	v_mul_f32_e32 v221, v109, v226
	v_mul_f32_e32 v222, v110, v226
	v_mul_f32_e32 v223, v111, v226
	v_mul_f32_e32 v208, v208, v72
	v_mul_f32_e32 v209, v209, v73
	v_mul_f32_e32 v210, v210, v74
	v_mul_f32_e32 v211, v211, v75
	v_mul_f32_e32 v212, v212, v76
	v_mul_f32_e32 v213, v213, v77
	v_mul_f32_e32 v214, v214, v78
	v_mul_f32_e32 v215, v215, v79
	v_mul_f32_e32 v216, v216, v80
	v_mul_f32_e32 v217, v217, v81
	v_mul_f32_e32 v218, v218, v82
	v_mul_f32_e32 v219, v219, v83
	v_mul_f32_e32 v220, v220, v84
	v_mul_f32_e32 v221, v221, v85
	v_mul_f32_e32 v222, v222, v86
	v_mul_f32_e32 v223, v223, v87
	v_cvt_pk_bf16_f32 v112, v208, v209
	v_cvt_pk_bf16_f32 v113, v210, v211
	v_cvt_pk_bf16_f32 v114, v212, v213
	v_cvt_pk_bf16_f32 v115, v214, v215
	v_cvt_pk_bf16_f32 v116, v216, v217
	v_cvt_pk_bf16_f32 v117, v218, v219
	v_cvt_pk_bf16_f32 v118, v220, v221
	v_cvt_pk_bf16_f32 v119, v222, v223
	global_store_dwordx4 v2, v[112:115], s[14:15]
	global_store_dwordx4 v2, v[116:119], s[14:15] offset:1024
	s_add_u32 s14, s14, 0x800
	s_addc_u32 s15, s15, 0
	global_load_dwordx4 v[96:99], v1, s[6:7] offset:0
	global_load_dwordx4 v[100:103], v1, s[6:7] offset:16
	global_load_dwordx4 v[104:107], v1, s[6:7] offset:2048
	global_load_dwordx4 v[108:111], v1, s[6:7] offset:2064
	global_load_dwordx4 v[112:115], v2, s[10:11]
	global_load_dwordx4 v[116:119], v2, s[10:11] offset:1024
	global_load_dwordx4 v[120:123], v2, s[12:13]
	global_load_dwordx4 v[124:127], v2, s[12:13] offset:1024
	s_add_u32 s6, s6, 0x1000
	s_addc_u32 s7, s7, 0
	s_add_u32 s10, s10, 0x800
	s_addc_u32 s11, s11, 0
	s_add_u32 s12, s12, 0x800
	s_addc_u32 s13, s13, 0
	s_waitcnt vmcnt(22)
	v_lshlrev_b32_e32 v208, 16, v144
	v_and_b32_e32 v209, 0xffff0000, v144
	v_lshlrev_b32_e32 v210, 16, v145
	v_and_b32_e32 v211, 0xffff0000, v145
	v_lshlrev_b32_e32 v212, 16, v146
	v_and_b32_e32 v213, 0xffff0000, v146
	v_lshlrev_b32_e32 v214, 16, v147
	v_and_b32_e32 v215, 0xffff0000, v147
	v_lshlrev_b32_e32 v216, 16, v148
	v_and_b32_e32 v217, 0xffff0000, v148
	v_lshlrev_b32_e32 v218, 16, v149
	v_and_b32_e32 v219, 0xffff0000, v149
	v_lshlrev_b32_e32 v220, 16, v150
	v_and_b32_e32 v221, 0xffff0000, v150
	v_lshlrev_b32_e32 v222, 16, v151
	v_and_b32_e32 v223, 0xffff0000, v151
	v_mul_f32_e32 v224, v208, v208
	v_fmac_f32_e32 v224, v209, v209
	v_fmac_f32_e32 v224, v210, v210
	v_fmac_f32_e32 v224, v211, v211
	v_fmac_f32_e32 v224, v212, v212
	v_fmac_f32_e32 v224, v213, v213
	v_fmac_f32_e32 v224, v214, v214
	v_fmac_f32_e32 v224, v215, v215
	v_fmac_f32_e32 v224, v216, v216
	v_fmac_f32_e32 v224, v217, v217
	v_fmac_f32_e32 v224, v218, v218
	v_fmac_f32_e32 v224, v219, v219
	v_fmac_f32_e32 v224, v220, v220
	v_fmac_f32_e32 v224, v221, v221
	v_fmac_f32_e32 v224, v222, v222
	v_fmac_f32_e32 v224, v223, v223
	s_nop 1
	v_add_f32_dpp v224, v224, v224 quad_perm:[1,0,3,2] row_mask:0xf bank_mask:0xf
	s_nop 1
	v_add_f32_dpp v224, v224, v224 quad_perm:[2,3,0,1] row_mask:0xf bank_mask:0xf
	s_nop 1
	v_add_f32_dpp v224, v224, v224 row_ror:4 row_mask:0xf bank_mask:0xf
	s_nop 1
	v_add_f32_dpp v224, v224, v224 row_ror:8 row_mask:0xf bank_mask:0xf
	s_nop 1
	v_readlane_b32 s20, v224, 0
	v_readlane_b32 s21, v224, 16
	v_readlane_b32 s22, v224, 32
	v_readlane_b32 s23, v224, 48
	s_nop 1
	v_mov_b32_e32 v225, s20
	v_add_f32_e32 v225, s21, v225
	v_add_f32_e32 v225, s22, v225
	v_add_f32_e32 v225, s23, v225
	v_mov_b32_e32 v226, 0x358637bd
	v_fmac_f32_e32 v226, 0x3a800000, v225
	v_rsq_f32_e32 v226, v226
	s_nop 0
	v_mul_f32_e32 v208, v208, v226
	v_mul_f32_e32 v209, v209, v226
	v_mul_f32_e32 v210, v210, v226
	v_mul_f32_e32 v211, v211, v226
	v_mul_f32_e32 v212, v212, v226
	v_mul_f32_e32 v213, v213, v226
	v_mul_f32_e32 v214, v214, v226
	v_mul_f32_e32 v215, v215, v226
	v_mul_f32_e32 v216, v216, v226
	v_mul_f32_e32 v217, v217, v226
	v_mul_f32_e32 v218, v218, v226
	v_mul_f32_e32 v219, v219, v226
	v_mul_f32_e32 v220, v220, v226
	v_mul_f32_e32 v221, v221, v226
	v_mul_f32_e32 v222, v222, v226
	v_mul_f32_e32 v223, v223, v226
	v_fmac_f32_e32 v128, v208, v40
	v_fmac_f32_e32 v129, v209, v41
	v_fmac_f32_e32 v130, v210, v42
	v_fmac_f32_e32 v131, v211, v43
	v_fmac_f32_e32 v132, v212, v44
	v_fmac_f32_e32 v133, v213, v45
	v_fmac_f32_e32 v134, v214, v46
	v_fmac_f32_e32 v135, v215, v47
	v_fmac_f32_e32 v136, v216, v48
	v_fmac_f32_e32 v137, v217, v49
	v_fmac_f32_e32 v138, v218, v50
	v_fmac_f32_e32 v139, v219, v51
	v_fmac_f32_e32 v140, v220, v52
	v_fmac_f32_e32 v141, v221, v53
	v_fmac_f32_e32 v142, v222, v54
	v_fmac_f32_e32 v143, v223, v55
	v_lshlrev_b32_e32 v208, 16, v152
	v_and_b32_e32 v209, 0xffff0000, v152
	v_lshlrev_b32_e32 v210, 16, v153
	v_and_b32_e32 v211, 0xffff0000, v153
	v_lshlrev_b32_e32 v212, 16, v154
	v_and_b32_e32 v213, 0xffff0000, v154
	v_lshlrev_b32_e32 v214, 16, v155
	v_and_b32_e32 v215, 0xffff0000, v155
	v_lshlrev_b32_e32 v216, 16, v156
	v_and_b32_e32 v217, 0xffff0000, v156
	v_lshlrev_b32_e32 v218, 16, v157
	v_and_b32_e32 v219, 0xffff0000, v157
	v_lshlrev_b32_e32 v220, 16, v158
	v_and_b32_e32 v221, 0xffff0000, v158
	v_lshlrev_b32_e32 v222, 16, v159
	v_and_b32_e32 v223, 0xffff0000, v159
	v_mul_f32_e32 v224, v208, v208
	v_fmac_f32_e32 v224, v209, v209
	v_fmac_f32_e32 v224, v210, v210
	v_fmac_f32_e32 v224, v211, v211
	v_fmac_f32_e32 v224, v212, v212
	v_fmac_f32_e32 v224, v213, v213
	v_fmac_f32_e32 v224, v214, v214
	v_fmac_f32_e32 v224, v215, v215
	v_fmac_f32_e32 v224, v216, v216
	v_fmac_f32_e32 v224, v217, v217
; DI unsigned pk_bf16(float a, float b) { f32x2_t v = {a, b}; bf16x2_t r = __builtin_convertvector(v, bf16x2_t); return __builtin_bit_cast(unsigned, r); }
; DI float shx(float v, int mask) { const int l = olane(); return __builtin_bit_cast(float, __builtin_amdgcn_ds_bpermute(((l ^ mask) & 63) << 2, __builtin_bit_cast(int, v))); }
; DI void row_phase(const bf16_t* msrc, const float* xsrc, float* xdst, const float* g_post, const float* g_next, bf16_t* hdst, const int gw) {
;     ...
;             for (int r = 0; r < RB; ++r) { ss[r] = 0.f;
; #pragma unroll
;                 for (int j = 0; j < 4; ++j) ss[r] += mv[r][j][0] * mv[r][j][0] + mv[r][j][1] * mv[r][j][1] + mv[r][j][2] * mv[r][j][2] + mv[r][j][3] * mv[r][j][3]; }
; #pragma unroll
;             for (int o = 32; o >= 1; o >>= 1)
; #pragma unroll
;                 for (int r = 0; r < RB; ++r) ss[r] += shx(ss[r], o);
; #pragma unroll
;             for (int j = 0; j < 4; ++j) { const f32x4 g = *(const f32x4*)(g_post + lane * 4 + 256 * j);
; #pragma unroll
;                 for (int r = 0; r < RB; ++r) { const float r1 = rsqrtf(ss[r] * (1.f / DM) + EPS); xv[r][j] = xv[r][j] + mv[r][j] * r1 * g; *(f32x4*)(xdst + (size_t)(rowb + r) * DM + lane * 4 + 256 * j) = xv[r][j]; } }
;         }
;         if (hdst) {
;             float ss[RB];
; #pragma unroll
;             for (int r = 0; r < RB; ++r) { ss[r] = 0.f;
; #pragma unroll
;                 for (int j = 0; j < 4; ++j) ss[r] += xv[r][j][0] * xv[r][j][0] + xv[r][j][1] * xv[r][j][1] + xv[r][j][2] * xv[r][j][2] + xv[r][j][3] * xv[r][j][3]; }
; #pragma unroll
;             for (int o = 32; o >= 1; o >>= 1)
; #pragma unroll
;                 for (int r = 0; r < RB; ++r) ss[r] += shx(ss[r], o);
; #pragma unroll
;             for (int j = 0; j < 4; ++j) { const f32x4 g = *(const f32x4*)(g_next + lane * 4 + 256 * j);
; #pragma unroll
;                 for (int r = 0; r < RB; ++r) { const float r2 = rsqrtf(ss[r] * (1.f / DM) + EPS); const f32x4 hv = xv[r][j] * r2 * g;
;                     u32x2 o; o[0] = pk_bf16(hv[0], hv[1]); o[1] = pk_bf16(hv[2], hv[3]); *(u32x2*)(hdst + (size_t)(rowb + r) * DM + lane * 4 + 256 * j) = o; } }
	v_fmac_f32_e32 v224, v218, v218
	v_fmac_f32_e32 v224, v219, v219
	v_fmac_f32_e32 v224, v220, v220
	v_fmac_f32_e32 v224, v221, v221
	v_fmac_f32_e32 v224, v222, v222
	v_fmac_f32_e32 v224, v223, v223
	s_nop 1
	v_add_f32_dpp v224, v224, v224 quad_perm:[1,0,3,2] row_mask:0xf bank_mask:0xf
	s_nop 1
	v_add_f32_dpp v224, v224, v224 quad_perm:[2,3,0,1] row_mask:0xf bank_mask:0xf
	s_nop 1
	v_add_f32_dpp v224, v224, v224 row_ror:4 row_mask:0xf bank_mask:0xf
	s_nop 1
	v_add_f32_dpp v224, v224, v224 row_ror:8 row_mask:0xf bank_mask:0xf
	s_nop 1
	v_readlane_b32 s20, v224, 0
	v_readlane_b32 s21, v224, 16
	v_readlane_b32 s22, v224, 32
	v_readlane_b32 s23, v224, 48
	s_nop 1
	v_mov_b32_e32 v225, s20
	v_add_f32_e32 v225, s21, v225
	v_add_f32_e32 v225, s22, v225
	v_add_f32_e32 v225, s23, v225
	v_mov_b32_e32 v226, 0x358637bd
	v_fmac_f32_e32 v226, 0x3a800000, v225
	v_rsq_f32_e32 v226, v226
	s_nop 0
	v_mul_f32_e32 v208, v208, v226
	v_mul_f32_e32 v209, v209, v226
	v_mul_f32_e32 v210, v210, v226
	v_mul_f32_e32 v211, v211, v226
	v_mul_f32_e32 v212, v212, v226
	v_mul_f32_e32 v213, v213, v226
	v_mul_f32_e32 v214, v214, v226
	v_mul_f32_e32 v215, v215, v226
	v_mul_f32_e32 v216, v216, v226
	v_mul_f32_e32 v217, v217, v226
	v_mul_f32_e32 v218, v218, v226
	v_mul_f32_e32 v219, v219, v226
	v_mul_f32_e32 v220, v220, v226
	v_mul_f32_e32 v221, v221, v226
	v_mul_f32_e32 v222, v222, v226
	v_mul_f32_e32 v223, v223, v226
	v_fmac_f32_e32 v128, v208, v56
	v_fmac_f32_e32 v129, v209, v57
	v_fmac_f32_e32 v130, v210, v58
	v_fmac_f32_e32 v131, v211, v59
	v_fmac_f32_e32 v132, v212, v60
	v_fmac_f32_e32 v133, v213, v61
	v_fmac_f32_e32 v134, v214, v62
	v_fmac_f32_e32 v135, v215, v63
	v_fmac_f32_e32 v136, v216, v64
	v_fmac_f32_e32 v137, v217, v65
	v_fmac_f32_e32 v138, v218, v66
	v_fmac_f32_e32 v139, v219, v67
	v_fmac_f32_e32 v140, v220, v68
	v_fmac_f32_e32 v141, v221, v69
	v_fmac_f32_e32 v142, v222, v70
	v_fmac_f32_e32 v143, v223, v71
	global_store_dwordx4 v1, v[128:131], s[8:9] offset:0
	global_store_dwordx4 v1, v[132:135], s[8:9] offset:16
	global_store_dwordx4 v1, v[136:139], s[8:9] offset:2048
	global_store_dwordx4 v1, v[140:143], s[8:9] offset:2064
	s_add_u32 s8, s8, 0x1000
	s_addc_u32 s9, s9, 0
	v_mul_f32_e32 v224, v128, v128
	v_fmac_f32_e32 v224, v129, v129
	v_fmac_f32_e32 v224, v130, v130
	v_fmac_f32_e32 v224, v131, v131
	v_fmac_f32_e32 v224, v132, v132
	v_fmac_f32_e32 v224, v133, v133
	v_fmac_f32_e32 v224, v134, v134
	v_fmac_f32_e32 v224, v135, v135
	v_fmac_f32_e32 v224, v136, v136
	v_fmac_f32_e32 v224, v137, v137
	v_fmac_f32_e32 v224, v138, v138
	v_fmac_f32_e32 v224, v139, v139
	v_fmac_f32_e32 v224, v140, v140
	v_fmac_f32_e32 v224, v141, v141
	v_fmac_f32_e32 v224, v142, v142
	v_fmac_f32_e32 v224, v143, v143
	s_nop 1
	v_add_f32_dpp v224, v224, v224 quad_perm:[1,0,3,2] row_mask:0xf bank_mask:0xf
	s_nop 1
	v_add_f32_dpp v224, v224, v224 quad_perm:[2,3,0,1] row_mask:0xf bank_mask:0xf
	s_nop 1
	v_add_f32_dpp v224, v224, v224 row_ror:4 row_mask:0xf bank_mask:0xf
	s_nop 1
	v_add_f32_dpp v224, v224, v224 row_ror:8 row_mask:0xf bank_mask:0xf
	s_nop 1
	v_readlane_b32 s20, v224, 0
	v_readlane_b32 s21, v224, 16
	v_readlane_b32 s22, v224, 32
	v_readlane_b32 s23, v224, 48
	s_nop 1
	v_mov_b32_e32 v225, s20
	v_add_f32_e32 v225, s21, v225
	v_add_f32_e32 v225, s22, v225
	v_add_f32_e32 v225, s23, v225
	v_mov_b32_e32 v226, 0x358637bd
	v_fmac_f32_e32 v226, 0x3a800000, v225
	v_rsq_f32_e32 v226, v226
	s_nop 0
	v_mul_f32_e32 v208, v128, v226
	v_mul_f32_e32 v209, v129, v226
	v_mul_f32_e32 v210, v130, v226
	v_mul_f32_e32 v211, v131, v226
	v_mul_f32_e32 v212, v132, v226
	v_mul_f32_e32 v213, v133, v226
	v_mul_f32_e32 v214, v134, v226
	v_mul_f32_e32 v215, v135, v226
	v_mul_f32_e32 v216, v136, v226
	v_mul_f32_e32 v217, v137, v226
	v_mul_f32_e32 v218, v138, v226
	v_mul_f32_e32 v219, v139, v226
	v_mul_f32_e32 v220, v140, v226
	v_mul_f32_e32 v221, v141, v226
	v_mul_f32_e32 v222, v142, v226
	v_mul_f32_e32 v223, v143, v226
	v_mul_f32_e32 v208, v208, v72
	v_mul_f32_e32 v209, v209, v73
	v_mul_f32_e32 v210, v210, v74
	v_mul_f32_e32 v211, v211, v75
	v_mul_f32_e32 v212, v212, v76
	v_mul_f32_e32 v213, v213, v77
	v_mul_f32_e32 v214, v214, v78
	v_mul_f32_e32 v215, v215, v79
	v_mul_f32_e32 v216, v216, v80
	v_mul_f32_e32 v217, v217, v81
	v_mul_f32_e32 v218, v218, v82
	v_mul_f32_e32 v219, v219, v83
	v_mul_f32_e32 v220, v220, v84
	v_mul_f32_e32 v221, v221, v85
	v_mul_f32_e32 v222, v222, v86
	v_mul_f32_e32 v223, v223, v87
	v_cvt_pk_bf16_f32 v144, v208, v209
	v_cvt_pk_bf16_f32 v145, v210, v211
	v_cvt_pk_bf16_f32 v146, v212, v213
	v_cvt_pk_bf16_f32 v147, v214, v215
	v_cvt_pk_bf16_f32 v148, v216, v217
	v_cvt_pk_bf16_f32 v149, v218, v219
	v_cvt_pk_bf16_f32 v150, v220, v221
	v_cvt_pk_bf16_f32 v151, v222, v223
	global_store_dwordx4 v2, v[144:147], s[14:15]
	global_store_dwordx4 v2, v[148:151], s[14:15] offset:1024
	s_add_u32 s14, s14, 0x800
	s_addc_u32 s15, s15, 0
	global_load_dwordx4 v[128:131], v1, s[6:7] offset:0
	global_load_dwordx4 v[132:135], v1, s[6:7] offset:16
	global_load_dwordx4 v[136:139], v1, s[6:7] offset:2048
	global_load_dwordx4 v[140:143], v1, s[6:7] offset:2064
	global_load_dwordx4 v[144:147], v2, s[10:11]
	global_load_dwordx4 v[148:151], v2, s[10:11] offset:1024
	global_load_dwordx4 v[152:155], v2, s[12:13]
	global_load_dwordx4 v[156:159], v2, s[12:13] offset:1024
	s_add_u32 s6, s6, 0x1000
	s_addc_u32 s7, s7, 0
	s_add_u32 s10, s10, 0x800
	s_addc_u32 s11, s11, 0
	s_add_u32 s12, s12, 0x800
	s_addc_u32 s13, s13, 0
	s_waitcnt vmcnt(28)
; DI float shx(float v, int mask) { const int l = olane(); return __builtin_bit_cast(float, __builtin_amdgcn_ds_bpermute(((l ^ mask) & 63) << 2, __builtin_bit_cast(int, v))); }
; DI void row_phase(const bf16_t* msrc, const float* xsrc, float* xdst, const float* g_post, const float* g_next, bf16_t* hdst, const int gw) {
;     ...
;                     mv[r][j] = (f32x4){__uint_as_float(mw[0] << 16), __uint_as_float(mw[0] & 0xffff0000u), __uint_as_float(mw[1] << 16), __uint_as_float(mw[1] & 0xffff0000u)}; }
;             float ss[RB];
; #pragma unroll
;             for (int r = 0; r < RB; ++r) { ss[r] = 0.f;
; #pragma unroll
;                 for (int j = 0; j < 4; ++j) ss[r] += mv[r][j][0] * mv[r][j][0] + mv[r][j][1] * mv[r][j][1] + mv[r][j][2] * mv[r][j][2] + mv[r][j][3] * mv[r][j][3]; }
; #pragma unroll
;             for (int o = 32; o >= 1; o >>= 1)
; #pragma unroll
;                 for (int r = 0; r < RB; ++r) ss[r] += shx(ss[r], o);
; #pragma unroll
;             for (int j = 0; j < 4; ++j) { const f32x4 g = *(const f32x4*)(g_post + lane * 4 + 256 * j);
; #pragma unroll
;                 for (int r = 0; r < RB; ++r) { const float r1 = rsqrtf(ss[r] * (1.f / DM) + EPS); xv[r][j] = xv[r][j] + mv[r][j] * r1 * g; *(f32x4*)(xdst + (size_t)(rowb + r) * DM + lane * 4 + 256 * j) = xv[r][j]; } }
	v_lshlrev_b32_e32 v208, 16, v176
	v_and_b32_e32 v209, 0xffff0000, v176
	v_lshlrev_b32_e32 v210, 16, v177
	v_and_b32_e32 v211, 0xffff0000, v177
	v_lshlrev_b32_e32 v212, 16, v178
	v_and_b32_e32 v213, 0xffff0000, v178
	v_lshlrev_b32_e32 v214, 16, v179
	v_and_b32_e32 v215, 0xffff0000, v179
	v_lshlrev_b32_e32 v216, 16, v180
	v_and_b32_e32 v217, 0xffff0000, v180
	v_lshlrev_b32_e32 v218, 16, v181
	v_and_b32_e32 v219, 0xffff0000, v181
	v_lshlrev_b32_e32 v220, 16, v182
	v_and_b32_e32 v221, 0xffff0000, v182
	v_lshlrev_b32_e32 v222, 16, v183
	v_and_b32_e32 v223, 0xffff0000, v183
	v_mul_f32_e32 v224, v208, v208
	v_fmac_f32_e32 v224, v209, v209
	v_fmac_f32_e32 v224, v210, v210
	v_fmac_f32_e32 v224, v211, v211
	v_fmac_f32_e32 v224, v212, v212
	v_fmac_f32_e32 v224, v213, v213
	v_fmac_f32_e32 v224, v214, v214
	v_fmac_f32_e32 v224, v215, v215
	v_fmac_f32_e32 v224, v216, v216
	v_fmac_f32_e32 v224, v217, v217
	v_fmac_f32_e32 v224, v218, v218
	v_fmac_f32_e32 v224, v219, v219
	v_fmac_f32_e32 v224, v220, v220
	v_fmac_f32_e32 v224, v221, v221
	v_fmac_f32_e32 v224, v222, v222
	v_fmac_f32_e32 v224, v223, v223
	s_nop 1
	v_add_f32_dpp v224, v224, v224 quad_perm:[1,0,3,2] row_mask:0xf bank_mask:0xf
	s_nop 1
	v_add_f32_dpp v224, v224, v224 quad_perm:[2,3,0,1] row_mask:0xf bank_mask:0xf
	s_nop 1
	v_add_f32_dpp v224, v224, v224 row_ror:4 row_mask:0xf bank_mask:0xf
	s_nop 1
	v_add_f32_dpp v224, v224, v224 row_ror:8 row_mask:0xf bank_mask:0xf
	s_nop 1
	v_readlane_b32 s20, v224, 0
	v_readlane_b32 s21, v224, 16
	v_readlane_b32 s22, v224, 32
	v_readlane_b32 s23, v224, 48
	s_nop 1
	v_mov_b32_e32 v225, s20
	v_add_f32_e32 v225, s21, v225
	v_add_f32_e32 v225, s22, v225
	v_add_f32_e32 v225, s23, v225
	v_mov_b32_e32 v226, 0x358637bd
	v_fmac_f32_e32 v226, 0x3a800000, v225
	v_rsq_f32_e32 v226, v226
	s_nop 0
	v_mul_f32_e32 v208, v208, v226
	v_mul_f32_e32 v209, v209, v226
	v_mul_f32_e32 v210, v210, v226
	v_mul_f32_e32 v211, v211, v226
	v_mul_f32_e32 v212, v212, v226
	v_mul_f32_e32 v213, v213, v226
	v_mul_f32_e32 v214, v214, v226
	v_mul_f32_e32 v215, v215, v226
	v_mul_f32_e32 v216, v216, v226
	v_mul_f32_e32 v217, v217, v226
	v_mul_f32_e32 v218, v218, v226
	v_mul_f32_e32 v219, v219, v226
	v_mul_f32_e32 v220, v220, v226
	v_mul_f32_e32 v221, v221, v226
	v_mul_f32_e32 v222, v222, v226
	v_mul_f32_e32 v223, v223, v226
	v_fmac_f32_e32 v160, v208, v40
	v_fmac_f32_e32 v161, v209, v41
	v_fmac_f32_e32 v162, v210, v42
	v_fmac_f32_e32 v163, v211, v43
	v_fmac_f32_e32 v164, v212, v44
	v_fmac_f32_e32 v165, v213, v45
	v_fmac_f32_e32 v166, v214, v46
	v_fmac_f32_e32 v167, v215, v47
	v_fmac_f32_e32 v168, v216, v48
	v_fmac_f32_e32 v169, v217, v49
	v_fmac_f32_e32 v170, v218, v50
	v_fmac_f32_e32 v171, v219, v51
	v_fmac_f32_e32 v172, v220, v52
	v_fmac_f32_e32 v173, v221, v53
	v_fmac_f32_e32 v174, v222, v54
	v_fmac_f32_e32 v175, v223, v55
	v_lshlrev_b32_e32 v208, 16, v184
	v_and_b32_e32 v209, 0xffff0000, v184
	v_lshlrev_b32_e32 v210, 16, v185
	v_and_b32_e32 v211, 0xffff0000, v185
	v_lshlrev_b32_e32 v212, 16, v186
	v_and_b32_e32 v213, 0xffff0000, v186
	v_lshlrev_b32_e32 v214, 16, v187
	v_and_b32_e32 v215, 0xffff0000, v187
	v_lshlrev_b32_e32 v216, 16, v188
	v_and_b32_e32 v217, 0xffff0000, v188
	v_lshlrev_b32_e32 v218, 16, v189
	v_and_b32_e32 v219, 0xffff0000, v189
	v_lshlrev_b32_e32 v220, 16, v190
	v_and_b32_e32 v221, 0xffff0000, v190
	v_lshlrev_b32_e32 v222, 16, v191
	v_and_b32_e32 v223, 0xffff0000, v191
	v_mul_f32_e32 v224, v208, v208
	v_fmac_f32_e32 v224, v209, v209
	v_fmac_f32_e32 v224, v210, v210
	v_fmac_f32_e32 v224, v211, v211
	v_fmac_f32_e32 v224, v212, v212
	v_fmac_f32_e32 v224, v213, v213
	v_fmac_f32_e32 v224, v214, v214
	v_fmac_f32_e32 v224, v215, v215
	v_fmac_f32_e32 v224, v216, v216
	v_fmac_f32_e32 v224, v217, v217
	v_fmac_f32_e32 v224, v218, v218
	v_fmac_f32_e32 v224, v219, v219
	v_fmac_f32_e32 v224, v220, v220
	v_fmac_f32_e32 v224, v221, v221
	v_fmac_f32_e32 v224, v222, v222
	v_fmac_f32_e32 v224, v223, v223
	s_nop 1
	v_add_f32_dpp v224, v224, v224 quad_perm:[1,0,3,2] row_mask:0xf bank_mask:0xf
	s_nop 1
	v_add_f32_dpp v224, v224, v224 quad_perm:[2,3,0,1] row_mask:0xf bank_mask:0xf
	s_nop 1
	v_add_f32_dpp v224, v224, v224 row_ror:4 row_mask:0xf bank_mask:0xf
	s_nop 1
	v_add_f32_dpp v224, v224, v224 row_ror:8 row_mask:0xf bank_mask:0xf
	s_nop 1
	v_readlane_b32 s20, v224, 0
	v_readlane_b32 s21, v224, 16
	v_readlane_b32 s22, v224, 32
	v_readlane_b32 s23, v224, 48
	s_nop 1
	v_mov_b32_e32 v225, s20
	v_add_f32_e32 v225, s21, v225
	v_add_f32_e32 v225, s22, v225
	v_add_f32_e32 v225, s23, v225
	v_mov_b32_e32 v226, 0x358637bd
	v_fmac_f32_e32 v226, 0x3a800000, v225
	v_rsq_f32_e32 v226, v226
	s_nop 0
	v_mul_f32_e32 v208, v208, v226
	v_mul_f32_e32 v209, v209, v226
	v_mul_f32_e32 v210, v210, v226
	v_mul_f32_e32 v211, v211, v226
	v_mul_f32_e32 v212, v212, v226
	v_mul_f32_e32 v213, v213, v226
	v_mul_f32_e32 v214, v214, v226
	v_mul_f32_e32 v215, v215, v226
	v_mul_f32_e32 v216, v216, v226
	v_mul_f32_e32 v217, v217, v226
	v_mul_f32_e32 v218, v218, v226
	v_mul_f32_e32 v219, v219, v226
	v_mul_f32_e32 v220, v220, v226
	v_mul_f32_e32 v221, v221, v226
	v_mul_f32_e32 v222, v222, v226
	v_mul_f32_e32 v223, v223, v226
	v_fmac_f32_e32 v160, v208, v56
	v_fmac_f32_e32 v161, v209, v57
	v_fmac_f32_e32 v162, v210, v58
	v_fmac_f32_e32 v163, v211, v59
	v_fmac_f32_e32 v164, v212, v60
	v_fmac_f32_e32 v165, v213, v61
	v_fmac_f32_e32 v166, v214, v62
	v_fmac_f32_e32 v167, v215, v63
	v_fmac_f32_e32 v168, v216, v64
	v_fmac_f32_e32 v169, v217, v65
	v_fmac_f32_e32 v170, v218, v66
	v_fmac_f32_e32 v171, v219, v67
	v_fmac_f32_e32 v172, v220, v68
	v_fmac_f32_e32 v173, v221, v69
	v_fmac_f32_e32 v174, v222, v70
	v_fmac_f32_e32 v175, v223, v71
; DI void row_phase(const bf16_t* msrc, const float* xsrc, float* xdst, const float* g_post, const float* g_next, bf16_t* hdst, const int gw) {
;     ...
;             for (int j = 0; j < 4; ++j) xv[r][j] = *(const f32x4*)(xsrc + (size_t)(rowb + r) * DM + lane * 4 + 256 * j);
;         if (msrc) {
; #pragma unroll
;             for (int r = 0; r < RB; ++r)
; #pragma unroll
;                 for (int j = 0; j < 4; ++j) { const u32x2 mw = *(const u32x2*)(msrc + (size_t)(rowb + r) * DM + lane * 4 + 256 * j);
;                     mv[r][j] = (f32x4){__uint_as_float(mw[0] << 16), __uint_as_float(mw[0] & 0xffff0000u), __uint_as_float(mw[1] << 16), __uint_as_float(mw[1] & 0xffff0000u)}; }
;             float ss[RB];
; #pragma unroll
;             for (int r = 0; r < RB; ++r) { ss[r] = 0.f;
; #pragma unroll
;                 for (int j = 0; j < 4; ++j) ss[r] += mv[r][j][0] * mv[r][j][0] + mv[r][j][1] * mv[r][j][1] + mv[r][j][2] * mv[r][j][2] + mv[r][j][3] * mv[r][j][3]; }
; #pragma unroll
;             for (int o = 32; o >= 1; o >>= 1)
; #pragma unroll
;                 for (int r = 0; r < RB; ++r) ss[r] += shx(ss[r], o);
; #pragma unroll
;             for (int j = 0; j < 4; ++j) { const f32x4 g = *(const f32x4*)(g_post + lane * 4 + 256 * j);
; #pragma unroll
;                 for (int r = 0; r < RB; ++r) { const float r1 = rsqrtf(ss[r] * (1.f / DM) + EPS); xv[r][j] = xv[r][j] + mv[r][j] * r1 * g; *(f32x4*)(xdst + (size_t)(rowb + r) * DM + lane * 4 + 256 * j) = xv[r][j]; } }
;         }
;         if (hdst) {
;             float ss[RB];
; #pragma unroll
;             for (int r = 0; r < RB; ++r) { ss[r] = 0.f;
; #pragma unroll
;                 for (int j = 0; j < 4; ++j) ss[r] += xv[r][j][0] * xv[r][j][0] + xv[r][j][1] * xv[r][j][1] + xv[r][j][2] * xv[r][j][2] + xv[r][j][3] * xv[r][j][3]; }
; #pragma unroll
;             for (int o = 32; o >= 1; o >>= 1)
; #pragma unroll
;                 for (int r = 0; r < RB; ++r) ss[r] += shx(ss[r], o);
; #pragma unroll
;             for (int j = 0; j < 4; ++j) { const f32x4 g = *(const f32x4*)(g_next + lane * 4 + 256 * j);
; #pragma unroll
;                 for (int r = 0; r < RB; ++r) { const float r2 = rsqrtf(ss[r] * (1.f / DM) + EPS); const f32x4 hv = xv[r][j] * r2 * g;
;                     u32x2 o; o[0] = pk_bf16(hv[0], hv[1]); o[1] = pk_bf16(hv[2], hv[3]); *(u32x2*)(hdst + (size_t)(rowb + r) * DM + lane * 4 + 256 * j) = o; } }
	global_store_dwordx4 v1, v[160:163], s[8:9] offset:0
	global_store_dwordx4 v1, v[164:167], s[8:9] offset:16
	global_store_dwordx4 v1, v[168:171], s[8:9] offset:2048
	global_store_dwordx4 v1, v[172:175], s[8:9] offset:2064
	s_add_u32 s8, s8, 0x1000
	s_addc_u32 s9, s9, 0
	v_mul_f32_e32 v224, v160, v160
	v_fmac_f32_e32 v224, v161, v161
	v_fmac_f32_e32 v224, v162, v162
	v_fmac_f32_e32 v224, v163, v163
	v_fmac_f32_e32 v224, v164, v164
	v_fmac_f32_e32 v224, v165, v165
	v_fmac_f32_e32 v224, v166, v166
	v_fmac_f32_e32 v224, v167, v167
	v_fmac_f32_e32 v224, v168, v168
	v_fmac_f32_e32 v224, v169, v169
	v_fmac_f32_e32 v224, v170, v170
	v_fmac_f32_e32 v224, v171, v171
	v_fmac_f32_e32 v224, v172, v172
	v_fmac_f32_e32 v224, v173, v173
	v_fmac_f32_e32 v224, v174, v174
	v_fmac_f32_e32 v224, v175, v175
	s_nop 1
	v_add_f32_dpp v224, v224, v224 quad_perm:[1,0,3,2] row_mask:0xf bank_mask:0xf
	s_nop 1
	v_add_f32_dpp v224, v224, v224 quad_perm:[2,3,0,1] row_mask:0xf bank_mask:0xf
	s_nop 1
	v_add_f32_dpp v224, v224, v224 row_ror:4 row_mask:0xf bank_mask:0xf
	s_nop 1
	v_add_f32_dpp v224, v224, v224 row_ror:8 row_mask:0xf bank_mask:0xf
	s_nop 1
	v_readlane_b32 s20, v224, 0
	v_readlane_b32 s21, v224, 16
	v_readlane_b32 s22, v224, 32
	v_readlane_b32 s23, v224, 48
	s_nop 1
	v_mov_b32_e32 v225, s20
	v_add_f32_e32 v225, s21, v225
	v_add_f32_e32 v225, s22, v225
	v_add_f32_e32 v225, s23, v225
	v_mov_b32_e32 v226, 0x358637bd
	v_fmac_f32_e32 v226, 0x3a800000, v225
	v_rsq_f32_e32 v226, v226
	s_nop 0
	v_mul_f32_e32 v208, v160, v226
	v_mul_f32_e32 v209, v161, v226
	v_mul_f32_e32 v210, v162, v226
	v_mul_f32_e32 v211, v163, v226
	v_mul_f32_e32 v212, v164, v226
	v_mul_f32_e32 v213, v165, v226
	v_mul_f32_e32 v214, v166, v226
	v_mul_f32_e32 v215, v167, v226
	v_mul_f32_e32 v216, v168, v226
	v_mul_f32_e32 v217, v169, v226
	v_mul_f32_e32 v218, v170, v226
	v_mul_f32_e32 v219, v171, v226
	v_mul_f32_e32 v220, v172, v226
	v_mul_f32_e32 v221, v173, v226
	v_mul_f32_e32 v222, v174, v226
	v_mul_f32_e32 v223, v175, v226
	v_mul_f32_e32 v208, v208, v72
	v_mul_f32_e32 v209, v209, v73
	v_mul_f32_e32 v210, v210, v74
	v_mul_f32_e32 v211, v211, v75
	v_mul_f32_e32 v212, v212, v76
	v_mul_f32_e32 v213, v213, v77
	v_mul_f32_e32 v214, v214, v78
	v_mul_f32_e32 v215, v215, v79
	v_mul_f32_e32 v216, v216, v80
	v_mul_f32_e32 v217, v217, v81
	v_mul_f32_e32 v218, v218, v82
	v_mul_f32_e32 v219, v219, v83
	v_mul_f32_e32 v220, v220, v84
	v_mul_f32_e32 v221, v221, v85
	v_mul_f32_e32 v222, v222, v86
	v_mul_f32_e32 v223, v223, v87
	v_cvt_pk_bf16_f32 v176, v208, v209
	v_cvt_pk_bf16_f32 v177, v210, v211
	v_cvt_pk_bf16_f32 v178, v212, v213
	v_cvt_pk_bf16_f32 v179, v214, v215
	v_cvt_pk_bf16_f32 v180, v216, v217
	v_cvt_pk_bf16_f32 v181, v218, v219
	v_cvt_pk_bf16_f32 v182, v220, v221
	v_cvt_pk_bf16_f32 v183, v222, v223
	global_store_dwordx4 v2, v[176:179], s[14:15]
	global_store_dwordx4 v2, v[180:183], s[14:15] offset:1024
	s_add_u32 s14, s14, 0x800
	s_addc_u32 s15, s15, 0
	global_load_dwordx4 v[160:163], v1, s[6:7] offset:0
	global_load_dwordx4 v[164:167], v1, s[6:7] offset:16
	global_load_dwordx4 v[168:171], v1, s[6:7] offset:2048
	global_load_dwordx4 v[172:175], v1, s[6:7] offset:2064
	global_load_dwordx4 v[176:179], v2, s[10:11]
	global_load_dwordx4 v[180:183], v2, s[10:11] offset:1024
	global_load_dwordx4 v[184:187], v2, s[12:13]
	global_load_dwordx4 v[188:191], v2, s[12:13] offset:1024
	s_add_u32 s6, s6, 0x1000
	s_addc_u32 s7, s7, 0
	s_add_u32 s10, s10, 0x800
	s_addc_u32 s11, s11, 0
	s_add_u32 s12, s12, 0x800
	s_addc_u32 s13, s13, 0
	s_waitcnt vmcnt(28)
	v_lshlrev_b32_e32 v208, 16, v112
	v_and_b32_e32 v209, 0xffff0000, v112
	v_lshlrev_b32_e32 v210, 16, v113
	v_and_b32_e32 v211, 0xffff0000, v113
	v_lshlrev_b32_e32 v212, 16, v114
	v_and_b32_e32 v213, 0xffff0000, v114
	v_lshlrev_b32_e32 v214, 16, v115
	v_and_b32_e32 v215, 0xffff0000, v115
	v_lshlrev_b32_e32 v216, 16, v116
	v_and_b32_e32 v217, 0xffff0000, v116
	v_lshlrev_b32_e32 v218, 16, v117
	v_and_b32_e32 v219, 0xffff0000, v117
	v_lshlrev_b32_e32 v220, 16, v118
	v_and_b32_e32 v221, 0xffff0000, v118
	v_lshlrev_b32_e32 v222, 16, v119
	v_and_b32_e32 v223, 0xffff0000, v119
	v_mul_f32_e32 v224, v208, v208
	v_fmac_f32_e32 v224, v209, v209
	v_fmac_f32_e32 v224, v210, v210
	v_fmac_f32_e32 v224, v211, v211
	v_fmac_f32_e32 v224, v212, v212
	v_fmac_f32_e32 v224, v213, v213
	v_fmac_f32_e32 v224, v214, v214
	v_fmac_f32_e32 v224, v215, v215
	v_fmac_f32_e32 v224, v216, v216
	v_fmac_f32_e32 v224, v217, v217
	v_fmac_f32_e32 v224, v218, v218
	v_fmac_f32_e32 v224, v219, v219
	v_fmac_f32_e32 v224, v220, v220
	v_fmac_f32_e32 v224, v221, v221
	v_fmac_f32_e32 v224, v222, v222
	v_fmac_f32_e32 v224, v223, v223
	s_nop 1
	v_add_f32_dpp v224, v224, v224 quad_perm:[1,0,3,2] row_mask:0xf bank_mask:0xf
	s_nop 1
	v_add_f32_dpp v224, v224, v224 quad_perm:[2,3,0,1] row_mask:0xf bank_mask:0xf
	s_nop 1
	v_add_f32_dpp v224, v224, v224 row_ror:4 row_mask:0xf bank_mask:0xf
	s_nop 1
	v_add_f32_dpp v224, v224, v224 row_ror:8 row_mask:0xf bank_mask:0xf
	s_nop 1
	v_readlane_b32 s20, v224, 0
	v_readlane_b32 s21, v224, 16
	v_readlane_b32 s22, v224, 32
	v_readlane_b32 s23, v224, 48
	s_nop 1
	v_mov_b32_e32 v225, s20
	v_add_f32_e32 v225, s21, v225
	v_add_f32_e32 v225, s22, v225
	v_add_f32_e32 v225, s23, v225
	v_mov_b32_e32 v226, 0x358637bd
	v_fmac_f32_e32 v226, 0x3a800000, v225
	v_rsq_f32_e32 v226, v226
	s_nop 0
	v_mul_f32_e32 v208, v208, v226
	v_mul_f32_e32 v209, v209, v226
	v_mul_f32_e32 v210, v210, v226
	v_mul_f32_e32 v211, v211, v226
	v_mul_f32_e32 v212, v212, v226
	v_mul_f32_e32 v213, v213, v226
	v_mul_f32_e32 v214, v214, v226
	v_mul_f32_e32 v215, v215, v226
	v_mul_f32_e32 v216, v216, v226
; DI unsigned pk_bf16(float a, float b) { f32x2_t v = {a, b}; bf16x2_t r = __builtin_convertvector(v, bf16x2_t); return __builtin_bit_cast(unsigned, r); }
; DI float shx(float v, int mask) { const int l = olane(); return __builtin_bit_cast(float, __builtin_amdgcn_ds_bpermute(((l ^ mask) & 63) << 2, __builtin_bit_cast(int, v))); }
; DI void row_phase(const bf16_t* msrc, const float* xsrc, float* xdst, const float* g_post, const float* g_next, bf16_t* hdst, const int gw) {
;     ...
;                     mv[r][j] = (f32x4){__uint_as_float(mw[0] << 16), __uint_as_float(mw[0] & 0xffff0000u), __uint_as_float(mw[1] << 16), __uint_as_float(mw[1] & 0xffff0000u)}; }
;             float ss[RB];
; #pragma unroll
;             for (int r = 0; r < RB; ++r) { ss[r] = 0.f;
; #pragma unroll
;                 for (int j = 0; j < 4; ++j) ss[r] += mv[r][j][0] * mv[r][j][0] + mv[r][j][1] * mv[r][j][1] + mv[r][j][2] * mv[r][j][2] + mv[r][j][3] * mv[r][j][3]; }
; #pragma unroll
;             for (int o = 32; o >= 1; o >>= 1)
; #pragma unroll
;                 for (int r = 0; r < RB; ++r) ss[r] += shx(ss[r], o);
; #pragma unroll
;             for (int j = 0; j < 4; ++j) { const f32x4 g = *(const f32x4*)(g_post + lane * 4 + 256 * j);
; #pragma unroll
;                 for (int r = 0; r < RB; ++r) { const float r1 = rsqrtf(ss[r] * (1.f / DM) + EPS); xv[r][j] = xv[r][j] + mv[r][j] * r1 * g; *(f32x4*)(xdst + (size_t)(rowb + r) * DM + lane * 4 + 256 * j) = xv[r][j]; } }
;         }
;         if (hdst) {
;             float ss[RB];
; #pragma unroll
;             for (int r = 0; r < RB; ++r) { ss[r] = 0.f;
; #pragma unroll
;                 for (int j = 0; j < 4; ++j) ss[r] += xv[r][j][0] * xv[r][j][0] + xv[r][j][1] * xv[r][j][1] + xv[r][j][2] * xv[r][j][2] + xv[r][j][3] * xv[r][j][3]; }
; #pragma unroll
;             for (int o = 32; o >= 1; o >>= 1)
; #pragma unroll
;                 for (int r = 0; r < RB; ++r) ss[r] += shx(ss[r], o);
; #pragma unroll
;             for (int j = 0; j < 4; ++j) { const f32x4 g = *(const f32x4*)(g_next + lane * 4 + 256 * j);
; #pragma unroll
;                 for (int r = 0; r < RB; ++r) { const float r2 = rsqrtf(ss[r] * (1.f / DM) + EPS); const f32x4 hv = xv[r][j] * r2 * g;
;                     u32x2 o; o[0] = pk_bf16(hv[0], hv[1]); o[1] = pk_bf16(hv[2], hv[3]); *(u32x2*)(hdst + (size_t)(rowb + r) * DM + lane * 4 + 256 * j) = o; } }
	v_mul_f32_e32 v217, v217, v226
	v_mul_f32_e32 v218, v218, v226
	v_mul_f32_e32 v219, v219, v226
	v_mul_f32_e32 v220, v220, v226
	v_mul_f32_e32 v221, v221, v226
	v_mul_f32_e32 v222, v222, v226
	v_mul_f32_e32 v223, v223, v226
	v_fmac_f32_e32 v96, v208, v40
	v_fmac_f32_e32 v97, v209, v41
	v_fmac_f32_e32 v98, v210, v42
	v_fmac_f32_e32 v99, v211, v43
	v_fmac_f32_e32 v100, v212, v44
	v_fmac_f32_e32 v101, v213, v45
	v_fmac_f32_e32 v102, v214, v46
	v_fmac_f32_e32 v103, v215, v47
	v_fmac_f32_e32 v104, v216, v48
	v_fmac_f32_e32 v105, v217, v49
	v_fmac_f32_e32 v106, v218, v50
	v_fmac_f32_e32 v107, v219, v51
	v_fmac_f32_e32 v108, v220, v52
	v_fmac_f32_e32 v109, v221, v53
	v_fmac_f32_e32 v110, v222, v54
	v_fmac_f32_e32 v111, v223, v55
	v_lshlrev_b32_e32 v208, 16, v120
	v_and_b32_e32 v209, 0xffff0000, v120
	v_lshlrev_b32_e32 v210, 16, v121
	v_and_b32_e32 v211, 0xffff0000, v121
	v_lshlrev_b32_e32 v212, 16, v122
	v_and_b32_e32 v213, 0xffff0000, v122
	v_lshlrev_b32_e32 v214, 16, v123
	v_and_b32_e32 v215, 0xffff0000, v123
	v_lshlrev_b32_e32 v216, 16, v124
	v_and_b32_e32 v217, 0xffff0000, v124
	v_lshlrev_b32_e32 v218, 16, v125
	v_and_b32_e32 v219, 0xffff0000, v125
	v_lshlrev_b32_e32 v220, 16, v126
	v_and_b32_e32 v221, 0xffff0000, v126
	v_lshlrev_b32_e32 v222, 16, v127
	v_and_b32_e32 v223, 0xffff0000, v127
	v_mul_f32_e32 v224, v208, v208
	v_fmac_f32_e32 v224, v209, v209
	v_fmac_f32_e32 v224, v210, v210
	v_fmac_f32_e32 v224, v211, v211
	v_fmac_f32_e32 v224, v212, v212
	v_fmac_f32_e32 v224, v213, v213
	v_fmac_f32_e32 v224, v214, v214
	v_fmac_f32_e32 v224, v215, v215
	v_fmac_f32_e32 v224, v216, v216
	v_fmac_f32_e32 v224, v217, v217
	v_fmac_f32_e32 v224, v218, v218
	v_fmac_f32_e32 v224, v219, v219
	v_fmac_f32_e32 v224, v220, v220
	v_fmac_f32_e32 v224, v221, v221
	v_fmac_f32_e32 v224, v222, v222
	v_fmac_f32_e32 v224, v223, v223
	s_nop 1
	v_add_f32_dpp v224, v224, v224 quad_perm:[1,0,3,2] row_mask:0xf bank_mask:0xf
	s_nop 1
	v_add_f32_dpp v224, v224, v224 quad_perm:[2,3,0,1] row_mask:0xf bank_mask:0xf
	s_nop 1
	v_add_f32_dpp v224, v224, v224 row_ror:4 row_mask:0xf bank_mask:0xf
	s_nop 1
	v_add_f32_dpp v224, v224, v224 row_ror:8 row_mask:0xf bank_mask:0xf
	s_nop 1
	v_readlane_b32 s20, v224, 0
	v_readlane_b32 s21, v224, 16
	v_readlane_b32 s22, v224, 32
	v_readlane_b32 s23, v224, 48
	s_nop 1
	v_mov_b32_e32 v225, s20
	v_add_f32_e32 v225, s21, v225
	v_add_f32_e32 v225, s22, v225
	v_add_f32_e32 v225, s23, v225
	v_mov_b32_e32 v226, 0x358637bd
	v_fmac_f32_e32 v226, 0x3a800000, v225
	v_rsq_f32_e32 v226, v226
	s_nop 0
	v_mul_f32_e32 v208, v208, v226
	v_mul_f32_e32 v209, v209, v226
	v_mul_f32_e32 v210, v210, v226
	v_mul_f32_e32 v211, v211, v226
	v_mul_f32_e32 v212, v212, v226
	v_mul_f32_e32 v213, v213, v226
	v_mul_f32_e32 v214, v214, v226
	v_mul_f32_e32 v215, v215, v226
	v_mul_f32_e32 v216, v216, v226
	v_mul_f32_e32 v217, v217, v226
	v_mul_f32_e32 v218, v218, v226
	v_mul_f32_e32 v219, v219, v226
	v_mul_f32_e32 v220, v220, v226
	v_mul_f32_e32 v221, v221, v226
	v_mul_f32_e32 v222, v222, v226
	v_mul_f32_e32 v223, v223, v226
	v_fmac_f32_e32 v96, v208, v56
	v_fmac_f32_e32 v97, v209, v57
	v_fmac_f32_e32 v98, v210, v58
	v_fmac_f32_e32 v99, v211, v59
	v_fmac_f32_e32 v100, v212, v60
	v_fmac_f32_e32 v101, v213, v61
	v_fmac_f32_e32 v102, v214, v62
	v_fmac_f32_e32 v103, v215, v63
	v_fmac_f32_e32 v104, v216, v64
	v_fmac_f32_e32 v105, v217, v65
	v_fmac_f32_e32 v106, v218, v66
	v_fmac_f32_e32 v107, v219, v67
	v_fmac_f32_e32 v108, v220, v68
	v_fmac_f32_e32 v109, v221, v69
	v_fmac_f32_e32 v110, v222, v70
	v_fmac_f32_e32 v111, v223, v71
	global_store_dwordx4 v1, v[96:99], s[8:9] offset:0
	global_store_dwordx4 v1, v[100:103], s[8:9] offset:16
	global_store_dwordx4 v1, v[104:107], s[8:9] offset:2048
	global_store_dwordx4 v1, v[108:111], s[8:9] offset:2064
	s_add_u32 s8, s8, 0x1000
	s_addc_u32 s9, s9, 0
	v_mul_f32_e32 v224, v96, v96
	v_fmac_f32_e32 v224, v97, v97
	v_fmac_f32_e32 v224, v98, v98
	v_fmac_f32_e32 v224, v99, v99
	v_fmac_f32_e32 v224, v100, v100
	v_fmac_f32_e32 v224, v101, v101
	v_fmac_f32_e32 v224, v102, v102
	v_fmac_f32_e32 v224, v103, v103
	v_fmac_f32_e32 v224, v104, v104
	v_fmac_f32_e32 v224, v105, v105
	v_fmac_f32_e32 v224, v106, v106
	v_fmac_f32_e32 v224, v107, v107
	v_fmac_f32_e32 v224, v108, v108
	v_fmac_f32_e32 v224, v109, v109
	v_fmac_f32_e32 v224, v110, v110
	v_fmac_f32_e32 v224, v111, v111
	s_nop 1
	v_add_f32_dpp v224, v224, v224 quad_perm:[1,0,3,2] row_mask:0xf bank_mask:0xf
	s_nop 1
	v_add_f32_dpp v224, v224, v224 quad_perm:[2,3,0,1] row_mask:0xf bank_mask:0xf
	s_nop 1
	v_add_f32_dpp v224, v224, v224 row_ror:4 row_mask:0xf bank_mask:0xf
	s_nop 1
	v_add_f32_dpp v224, v224, v224 row_ror:8 row_mask:0xf bank_mask:0xf
	s_nop 1
	v_readlane_b32 s20, v224, 0
	v_readlane_b32 s21, v224, 16
	v_readlane_b32 s22, v224, 32
	v_readlane_b32 s23, v224, 48
	s_nop 1
	v_mov_b32_e32 v225, s20
	v_add_f32_e32 v225, s21, v225
	v_add_f32_e32 v225, s22, v225
	v_add_f32_e32 v225, s23, v225
	v_mov_b32_e32 v226, 0x358637bd
	v_fmac_f32_e32 v226, 0x3a800000, v225
	v_rsq_f32_e32 v226, v226
	s_nop 0
	v_mul_f32_e32 v208, v96, v226
	v_mul_f32_e32 v209, v97, v226
	v_mul_f32_e32 v210, v98, v226
	v_mul_f32_e32 v211, v99, v226
	v_mul_f32_e32 v212, v100, v226
	v_mul_f32_e32 v213, v101, v226
	v_mul_f32_e32 v214, v102, v226
	v_mul_f32_e32 v215, v103, v226
	v_mul_f32_e32 v216, v104, v226
	v_mul_f32_e32 v217, v105, v226
	v_mul_f32_e32 v218, v106, v226
	v_mul_f32_e32 v219, v107, v226
	v_mul_f32_e32 v220, v108, v226
	v_mul_f32_e32 v221, v109, v226
	v_mul_f32_e32 v222, v110, v226
	v_mul_f32_e32 v223, v111, v226
	v_mul_f32_e32 v208, v208, v72
	v_mul_f32_e32 v209, v209, v73
	v_mul_f32_e32 v210, v210, v74
; DI void row_phase(const bf16_t* msrc, const float* xsrc, float* xdst, const float* g_post, const float* g_next, bf16_t* hdst, const int gw) {
;     ...
;             for (int j = 0; j < 4; ++j) xv[r][j] = *(const f32x4*)(xsrc + (size_t)(rowb + r) * DM + lane * 4 + 256 * j);
;         if (msrc) {
; #pragma unroll
;             for (int r = 0; r < RB; ++r)
; #pragma unroll
;                 for (int j = 0; j < 4; ++j) { const u32x2 mw = *(const u32x2*)(msrc + (size_t)(rowb + r) * DM + lane * 4 + 256 * j);
;                     mv[r][j] = (f32x4){__uint_as_float(mw[0] << 16), __uint_as_float(mw[0] & 0xffff0000u), __uint_as_float(mw[1] << 16), __uint_as_float(mw[1] & 0xffff0000u)}; }
;             float ss[RB];
; #pragma unroll
;             for (int r = 0; r < RB; ++r) { ss[r] = 0.f;
; #pragma unroll
;                 for (int j = 0; j < 4; ++j) ss[r] += mv[r][j][0] * mv[r][j][0] + mv[r][j][1] * mv[r][j][1] + mv[r][j][2] * mv[r][j][2] + mv[r][j][3] * mv[r][j][3]; }
; #pragma unroll
;             for (int o = 32; o >= 1; o >>= 1)
; #pragma unroll
;                 for (int r = 0; r < RB; ++r) ss[r] += shx(ss[r], o);
; #pragma unroll
;             for (int j = 0; j < 4; ++j) { const f32x4 g = *(const f32x4*)(g_post + lane * 4 + 256 * j);
; #pragma unroll
;                 for (int r = 0; r < RB; ++r) { const float r1 = rsqrtf(ss[r] * (1.f / DM) + EPS); xv[r][j] = xv[r][j] + mv[r][j] * r1 * g; *(f32x4*)(xdst + (size_t)(rowb + r) * DM + lane * 4 + 256 * j) = xv[r][j]; } }
;         }
;         if (hdst) {
;             float ss[RB];
; #pragma unroll
;             for (int r = 0; r < RB; ++r) { ss[r] = 0.f;
; #pragma unroll
;                 for (int j = 0; j < 4; ++j) ss[r] += xv[r][j][0] * xv[r][j][0] + xv[r][j][1] * xv[r][j][1] + xv[r][j][2] * xv[r][j][2] + xv[r][j][3] * xv[r][j][3]; }
; #pragma unroll
;             for (int o = 32; o >= 1; o >>= 1)
; #pragma unroll
;                 for (int r = 0; r < RB; ++r) ss[r] += shx(ss[r], o);
; #pragma unroll
;             for (int j = 0; j < 4; ++j) { const f32x4 g = *(const f32x4*)(g_next + lane * 4 + 256 * j);
; #pragma unroll
;                 for (int r = 0; r < RB; ++r) { const float r2 = rsqrtf(ss[r] * (1.f / DM) + EPS); const f32x4 hv = xv[r][j] * r2 * g;
;                     u32x2 o; o[0] = pk_bf16(hv[0], hv[1]); o[1] = pk_bf16(hv[2], hv[3]); *(u32x2*)(hdst + (size_t)(rowb + r) * DM + lane * 4 + 256 * j) = o; } }
	v_mul_f32_e32 v211, v211, v75
	v_mul_f32_e32 v212, v212, v76
	v_mul_f32_e32 v213, v213, v77
	v_mul_f32_e32 v214, v214, v78
	v_mul_f32_e32 v215, v215, v79
	v_mul_f32_e32 v216, v216, v80
	v_mul_f32_e32 v217, v217, v81
	v_mul_f32_e32 v218, v218, v82
	v_mul_f32_e32 v219, v219, v83
	v_mul_f32_e32 v220, v220, v84
	v_mul_f32_e32 v221, v221, v85
	v_mul_f32_e32 v222, v222, v86
	v_mul_f32_e32 v223, v223, v87
	v_cvt_pk_bf16_f32 v112, v208, v209
	v_cvt_pk_bf16_f32 v113, v210, v211
	v_cvt_pk_bf16_f32 v114, v212, v213
	v_cvt_pk_bf16_f32 v115, v214, v215
	v_cvt_pk_bf16_f32 v116, v216, v217
	v_cvt_pk_bf16_f32 v117, v218, v219
	v_cvt_pk_bf16_f32 v118, v220, v221
	v_cvt_pk_bf16_f32 v119, v222, v223
	global_store_dwordx4 v2, v[112:115], s[14:15]
	global_store_dwordx4 v2, v[116:119], s[14:15] offset:1024
	s_add_u32 s14, s14, 0x800
	s_addc_u32 s15, s15, 0
	global_load_dwordx4 v[96:99], v1, s[6:7] offset:0
	global_load_dwordx4 v[100:103], v1, s[6:7] offset:16
	global_load_dwordx4 v[104:107], v1, s[6:7] offset:2048
	global_load_dwordx4 v[108:111], v1, s[6:7] offset:2064
	global_load_dwordx4 v[112:115], v2, s[10:11]
	global_load_dwordx4 v[116:119], v2, s[10:11] offset:1024
	global_load_dwordx4 v[120:123], v2, s[12:13]
	global_load_dwordx4 v[124:127], v2, s[12:13] offset:1024
	s_add_u32 s6, s6, 0x1000
	s_addc_u32 s7, s7, 0
	s_add_u32 s10, s10, 0x800
	s_addc_u32 s11, s11, 0
	s_add_u32 s12, s12, 0x800
	s_addc_u32 s13, s13, 0
	s_waitcnt vmcnt(28)
	v_lshlrev_b32_e32 v208, 16, v144
	v_and_b32_e32 v209, 0xffff0000, v144
	v_lshlrev_b32_e32 v210, 16, v145
	v_and_b32_e32 v211, 0xffff0000, v145
	v_lshlrev_b32_e32 v212, 16, v146
	v_and_b32_e32 v213, 0xffff0000, v146
	v_lshlrev_b32_e32 v214, 16, v147
	v_and_b32_e32 v215, 0xffff0000, v147
	v_lshlrev_b32_e32 v216, 16, v148
	v_and_b32_e32 v217, 0xffff0000, v148
	v_lshlrev_b32_e32 v218, 16, v149
	v_and_b32_e32 v219, 0xffff0000, v149
	v_lshlrev_b32_e32 v220, 16, v150
	v_and_b32_e32 v221, 0xffff0000, v150
	v_lshlrev_b32_e32 v222, 16, v151
	v_and_b32_e32 v223, 0xffff0000, v151
	v_mul_f32_e32 v224, v208, v208
	v_fmac_f32_e32 v224, v209, v209
	v_fmac_f32_e32 v224, v210, v210
	v_fmac_f32_e32 v224, v211, v211
	v_fmac_f32_e32 v224, v212, v212
	v_fmac_f32_e32 v224, v213, v213
	v_fmac_f32_e32 v224, v214, v214
	v_fmac_f32_e32 v224, v215, v215
	v_fmac_f32_e32 v224, v216, v216
	v_fmac_f32_e32 v224, v217, v217
	v_fmac_f32_e32 v224, v218, v218
	v_fmac_f32_e32 v224, v219, v219
	v_fmac_f32_e32 v224, v220, v220
	v_fmac_f32_e32 v224, v221, v221
	v_fmac_f32_e32 v224, v222, v222
	v_fmac_f32_e32 v224, v223, v223
	s_nop 1
	v_add_f32_dpp v224, v224, v224 quad_perm:[1,0,3,2] row_mask:0xf bank_mask:0xf
	s_nop 1
	v_add_f32_dpp v224, v224, v224 quad_perm:[2,3,0,1] row_mask:0xf bank_mask:0xf
	s_nop 1
	v_add_f32_dpp v224, v224, v224 row_ror:4 row_mask:0xf bank_mask:0xf
	s_nop 1
	v_add_f32_dpp v224, v224, v224 row_ror:8 row_mask:0xf bank_mask:0xf
	s_nop 1
	v_readlane_b32 s20, v224, 0
	v_readlane_b32 s21, v224, 16
	v_readlane_b32 s22, v224, 32
	v_readlane_b32 s23, v224, 48
	s_nop 1
	v_mov_b32_e32 v225, s20
	v_add_f32_e32 v225, s21, v225
	v_add_f32_e32 v225, s22, v225
	v_add_f32_e32 v225, s23, v225
	v_mov_b32_e32 v226, 0x358637bd
	v_fmac_f32_e32 v226, 0x3a800000, v225
	v_rsq_f32_e32 v226, v226
	s_nop 0
	v_mul_f32_e32 v208, v208, v226
	v_mul_f32_e32 v209, v209, v226
	v_mul_f32_e32 v210, v210, v226
	v_mul_f32_e32 v211, v211, v226
	v_mul_f32_e32 v212, v212, v226
	v_mul_f32_e32 v213, v213, v226
	v_mul_f32_e32 v214, v214, v226
	v_mul_f32_e32 v215, v215, v226
	v_mul_f32_e32 v216, v216, v226
	v_mul_f32_e32 v217, v217, v226
	v_mul_f32_e32 v218, v218, v226
	v_mul_f32_e32 v219, v219, v226
	v_mul_f32_e32 v220, v220, v226
	v_mul_f32_e32 v221, v221, v226
	v_mul_f32_e32 v222, v222, v226
	v_mul_f32_e32 v223, v223, v226
	v_fmac_f32_e32 v128, v208, v40
	v_fmac_f32_e32 v129, v209, v41
	v_fmac_f32_e32 v130, v210, v42
	v_fmac_f32_e32 v131, v211, v43
	v_fmac_f32_e32 v132, v212, v44
	v_fmac_f32_e32 v133, v213, v45
	v_fmac_f32_e32 v134, v214, v46
	v_fmac_f32_e32 v135, v215, v47
	v_fmac_f32_e32 v136, v216, v48
	v_fmac_f32_e32 v137, v217, v49
	v_fmac_f32_e32 v138, v218, v50
	v_fmac_f32_e32 v139, v219, v51
	v_fmac_f32_e32 v140, v220, v52
	v_fmac_f32_e32 v141, v221, v53
	v_fmac_f32_e32 v142, v222, v54
	v_fmac_f32_e32 v143, v223, v55
	v_lshlrev_b32_e32 v208, 16, v152
	v_and_b32_e32 v209, 0xffff0000, v152
	v_lshlrev_b32_e32 v210, 16, v153
	v_and_b32_e32 v211, 0xffff0000, v153
	v_lshlrev_b32_e32 v212, 16, v154
	v_and_b32_e32 v213, 0xffff0000, v154
	v_lshlrev_b32_e32 v214, 16, v155
	v_and_b32_e32 v215, 0xffff0000, v155
	v_lshlrev_b32_e32 v216, 16, v156
	v_and_b32_e32 v217, 0xffff0000, v156
	v_lshlrev_b32_e32 v218, 16, v157
	v_and_b32_e32 v219, 0xffff0000, v157
	v_lshlrev_b32_e32 v220, 16, v158
	v_and_b32_e32 v221, 0xffff0000, v158
	v_lshlrev_b32_e32 v222, 16, v159
	v_and_b32_e32 v223, 0xffff0000, v159
	v_mul_f32_e32 v224, v208, v208
	v_fmac_f32_e32 v224, v209, v209
	v_fmac_f32_e32 v224, v210, v210
	v_fmac_f32_e32 v224, v211, v211
	v_fmac_f32_e32 v224, v212, v212
	v_fmac_f32_e32 v224, v213, v213
	v_fmac_f32_e32 v224, v214, v214
	v_fmac_f32_e32 v224, v215, v215
	v_fmac_f32_e32 v224, v216, v216
	v_fmac_f32_e32 v224, v217, v217
	v_fmac_f32_e32 v224, v218, v218
	v_fmac_f32_e32 v224, v219, v219
	v_fmac_f32_e32 v224, v220, v220
	v_fmac_f32_e32 v224, v221, v221
	v_fmac_f32_e32 v224, v222, v222
	v_fmac_f32_e32 v224, v223, v223
	s_nop 1
	v_add_f32_dpp v224, v224, v224 quad_perm:[1,0,3,2] row_mask:0xf bank_mask:0xf
	s_nop 1
	v_add_f32_dpp v224, v224, v224 quad_perm:[2,3,0,1] row_mask:0xf bank_mask:0xf
	s_nop 1
	v_add_f32_dpp v224, v224, v224 row_ror:4 row_mask:0xf bank_mask:0xf
	s_nop 1
; DI void row_phase(const bf16_t* msrc, const float* xsrc, float* xdst, const float* g_post, const float* g_next, bf16_t* hdst, const int gw) {
;     ...
;             for (int j = 0; j < 4; ++j) xv[r][j] = *(const f32x4*)(xsrc + (size_t)(rowb + r) * DM + lane * 4 + 256 * j);
;         if (msrc) {
; #pragma unroll
;             for (int r = 0; r < RB; ++r)
; #pragma unroll
;                 for (int j = 0; j < 4; ++j) { const u32x2 mw = *(const u32x2*)(msrc + (size_t)(rowb + r) * DM + lane * 4 + 256 * j);
;                     mv[r][j] = (f32x4){__uint_as_float(mw[0] << 16), __uint_as_float(mw[0] & 0xffff0000u), __uint_as_float(mw[1] << 16), __uint_as_float(mw[1] & 0xffff0000u)}; }
;             float ss[RB];
; #pragma unroll
;             for (int r = 0; r < RB; ++r) { ss[r] = 0.f;
; #pragma unroll
;                 for (int j = 0; j < 4; ++j) ss[r] += mv[r][j][0] * mv[r][j][0] + mv[r][j][1] * mv[r][j][1] + mv[r][j][2] * mv[r][j][2] + mv[r][j][3] * mv[r][j][3]; }
; #pragma unroll
;             for (int o = 32; o >= 1; o >>= 1)
; #pragma unroll
;                 for (int r = 0; r < RB; ++r) ss[r] += shx(ss[r], o);
; #pragma unroll
;             for (int j = 0; j < 4; ++j) { const f32x4 g = *(const f32x4*)(g_post + lane * 4 + 256 * j);
; #pragma unroll
;                 for (int r = 0; r < RB; ++r) { const float r1 = rsqrtf(ss[r] * (1.f / DM) + EPS); xv[r][j] = xv[r][j] + mv[r][j] * r1 * g; *(f32x4*)(xdst + (size_t)(rowb + r) * DM + lane * 4 + 256 * j) = xv[r][j]; } }
;         }
;         if (hdst) {
;             float ss[RB];
; #pragma unroll
;             for (int r = 0; r < RB; ++r) { ss[r] = 0.f;
; #pragma unroll
;                 for (int j = 0; j < 4; ++j) ss[r] += xv[r][j][0] * xv[r][j][0] + xv[r][j][1] * xv[r][j][1] + xv[r][j][2] * xv[r][j][2] + xv[r][j][3] * xv[r][j][3]; }
; #pragma unroll
;             for (int o = 32; o >= 1; o >>= 1)
; #pragma unroll
;                 for (int r = 0; r < RB; ++r) ss[r] += shx(ss[r], o);
; #pragma unroll
;             for (int j = 0; j < 4; ++j) { const f32x4 g = *(const f32x4*)(g_next + lane * 4 + 256 * j);
; #pragma unroll
;                 for (int r = 0; r < RB; ++r) { const float r2 = rsqrtf(ss[r] * (1.f / DM) + EPS); const f32x4 hv = xv[r][j] * r2 * g;
;                     u32x2 o; o[0] = pk_bf16(hv[0], hv[1]); o[1] = pk_bf16(hv[2], hv[3]); *(u32x2*)(hdst + (size_t)(rowb + r) * DM + lane * 4 + 256 * j) = o; } }
	v_add_f32_dpp v224, v224, v224 row_ror:8 row_mask:0xf bank_mask:0xf
	s_nop 1
	v_readlane_b32 s20, v224, 0
	v_readlane_b32 s21, v224, 16
	v_readlane_b32 s22, v224, 32
	v_readlane_b32 s23, v224, 48
	s_nop 1
	v_mov_b32_e32 v225, s20
	v_add_f32_e32 v225, s21, v225
	v_add_f32_e32 v225, s22, v225
	v_add_f32_e32 v225, s23, v225
	v_mov_b32_e32 v226, 0x358637bd
	v_fmac_f32_e32 v226, 0x3a800000, v225
	v_rsq_f32_e32 v226, v226
	s_nop 0
	v_mul_f32_e32 v208, v208, v226
	v_mul_f32_e32 v209, v209, v226
	v_mul_f32_e32 v210, v210, v226
	v_mul_f32_e32 v211, v211, v226
	v_mul_f32_e32 v212, v212, v226
	v_mul_f32_e32 v213, v213, v226
	v_mul_f32_e32 v214, v214, v226
	v_mul_f32_e32 v215, v215, v226
	v_mul_f32_e32 v216, v216, v226
	v_mul_f32_e32 v217, v217, v226
	v_mul_f32_e32 v218, v218, v226
	v_mul_f32_e32 v219, v219, v226
	v_mul_f32_e32 v220, v220, v226
	v_mul_f32_e32 v221, v221, v226
	v_mul_f32_e32 v222, v222, v226
	v_mul_f32_e32 v223, v223, v226
	v_fmac_f32_e32 v128, v208, v56
	v_fmac_f32_e32 v129, v209, v57
	v_fmac_f32_e32 v130, v210, v58
	v_fmac_f32_e32 v131, v211, v59
	v_fmac_f32_e32 v132, v212, v60
	v_fmac_f32_e32 v133, v213, v61
	v_fmac_f32_e32 v134, v214, v62
	v_fmac_f32_e32 v135, v215, v63
	v_fmac_f32_e32 v136, v216, v64
	v_fmac_f32_e32 v137, v217, v65
	v_fmac_f32_e32 v138, v218, v66
	v_fmac_f32_e32 v139, v219, v67
	v_fmac_f32_e32 v140, v220, v68
	v_fmac_f32_e32 v141, v221, v69
	v_fmac_f32_e32 v142, v222, v70
	v_fmac_f32_e32 v143, v223, v71
	global_store_dwordx4 v1, v[128:131], s[8:9] offset:0
	global_store_dwordx4 v1, v[132:135], s[8:9] offset:16
	global_store_dwordx4 v1, v[136:139], s[8:9] offset:2048
	global_store_dwordx4 v1, v[140:143], s[8:9] offset:2064
	s_add_u32 s8, s8, 0x1000
	s_addc_u32 s9, s9, 0
	v_mul_f32_e32 v224, v128, v128
	v_fmac_f32_e32 v224, v129, v129
	v_fmac_f32_e32 v224, v130, v130
	v_fmac_f32_e32 v224, v131, v131
	v_fmac_f32_e32 v224, v132, v132
	v_fmac_f32_e32 v224, v133, v133
	v_fmac_f32_e32 v224, v134, v134
	v_fmac_f32_e32 v224, v135, v135
	v_fmac_f32_e32 v224, v136, v136
	v_fmac_f32_e32 v224, v137, v137
	v_fmac_f32_e32 v224, v138, v138
	v_fmac_f32_e32 v224, v139, v139
	v_fmac_f32_e32 v224, v140, v140
	v_fmac_f32_e32 v224, v141, v141
	v_fmac_f32_e32 v224, v142, v142
	v_fmac_f32_e32 v224, v143, v143
	s_nop 1
	v_add_f32_dpp v224, v224, v224 quad_perm:[1,0,3,2] row_mask:0xf bank_mask:0xf
	s_nop 1
	v_add_f32_dpp v224, v224, v224 quad_perm:[2,3,0,1] row_mask:0xf bank_mask:0xf
	s_nop 1
	v_add_f32_dpp v224, v224, v224 row_ror:4 row_mask:0xf bank_mask:0xf
	s_nop 1
	v_add_f32_dpp v224, v224, v224 row_ror:8 row_mask:0xf bank_mask:0xf
	s_nop 1
	v_readlane_b32 s20, v224, 0
	v_readlane_b32 s21, v224, 16
	v_readlane_b32 s22, v224, 32
	v_readlane_b32 s23, v224, 48
	s_nop 1
	v_mov_b32_e32 v225, s20
	v_add_f32_e32 v225, s21, v225
	v_add_f32_e32 v225, s22, v225
	v_add_f32_e32 v225, s23, v225
	v_mov_b32_e32 v226, 0x358637bd
	v_fmac_f32_e32 v226, 0x3a800000, v225
	v_rsq_f32_e32 v226, v226
	s_nop 0
	v_mul_f32_e32 v208, v128, v226
	v_mul_f32_e32 v209, v129, v226
	v_mul_f32_e32 v210, v130, v226
	v_mul_f32_e32 v211, v131, v226
	v_mul_f32_e32 v212, v132, v226
	v_mul_f32_e32 v213, v133, v226
	v_mul_f32_e32 v214, v134, v226
	v_mul_f32_e32 v215, v135, v226
	v_mul_f32_e32 v216, v136, v226
	v_mul_f32_e32 v217, v137, v226
	v_mul_f32_e32 v218, v138, v226
	v_mul_f32_e32 v219, v139, v226
	v_mul_f32_e32 v220, v140, v226
	v_mul_f32_e32 v221, v141, v226
	v_mul_f32_e32 v222, v142, v226
	v_mul_f32_e32 v223, v143, v226
	v_mul_f32_e32 v208, v208, v72
	v_mul_f32_e32 v209, v209, v73
	v_mul_f32_e32 v210, v210, v74
	v_mul_f32_e32 v211, v211, v75
	v_mul_f32_e32 v212, v212, v76
	v_mul_f32_e32 v213, v213, v77
	v_mul_f32_e32 v214, v214, v78
	v_mul_f32_e32 v215, v215, v79
	v_mul_f32_e32 v216, v216, v80
	v_mul_f32_e32 v217, v217, v81
	v_mul_f32_e32 v218, v218, v82
	v_mul_f32_e32 v219, v219, v83
	v_mul_f32_e32 v220, v220, v84
	v_mul_f32_e32 v221, v221, v85
	v_mul_f32_e32 v222, v222, v86
	v_mul_f32_e32 v223, v223, v87
	v_cvt_pk_bf16_f32 v144, v208, v209
	v_cvt_pk_bf16_f32 v145, v210, v211
	v_cvt_pk_bf16_f32 v146, v212, v213
	v_cvt_pk_bf16_f32 v147, v214, v215
	v_cvt_pk_bf16_f32 v148, v216, v217
	v_cvt_pk_bf16_f32 v149, v218, v219
	v_cvt_pk_bf16_f32 v150, v220, v221
	v_cvt_pk_bf16_f32 v151, v222, v223
	global_store_dwordx4 v2, v[144:147], s[14:15]
	global_store_dwordx4 v2, v[148:151], s[14:15] offset:1024
	s_add_u32 s14, s14, 0x800
	s_addc_u32 s15, s15, 0
	global_load_dwordx4 v[128:131], v1, s[6:7] offset:0
	global_load_dwordx4 v[132:135], v1, s[6:7] offset:16
	global_load_dwordx4 v[136:139], v1, s[6:7] offset:2048
	global_load_dwordx4 v[140:143], v1, s[6:7] offset:2064
	global_load_dwordx4 v[144:147], v2, s[10:11]
	global_load_dwordx4 v[148:151], v2, s[10:11] offset:1024
	global_load_dwordx4 v[152:155], v2, s[12:13]
	global_load_dwordx4 v[156:159], v2, s[12:13] offset:1024
	s_add_u32 s6, s6, 0x1000
	s_addc_u32 s7, s7, 0
	s_add_u32 s10, s10, 0x800
	s_addc_u32 s11, s11, 0
	s_add_u32 s12, s12, 0x800
	s_addc_u32 s13, s13, 0
	s_waitcnt vmcnt(28)
; DI float shx(float v, int mask) { const int l = olane(); return __builtin_bit_cast(float, __builtin_amdgcn_ds_bpermute(((l ^ mask) & 63) << 2, __builtin_bit_cast(int, v))); }
; DI void row_phase(const bf16_t* msrc, const float* xsrc, float* xdst, const float* g_post, const float* g_next, bf16_t* hdst, const int gw) {
;     ...
;                     mv[r][j] = (f32x4){__uint_as_float(mw[0] << 16), __uint_as_float(mw[0] & 0xffff0000u), __uint_as_float(mw[1] << 16), __uint_as_float(mw[1] & 0xffff0000u)}; }
;             float ss[RB];
; #pragma unroll
;             for (int r = 0; r < RB; ++r) { ss[r] = 0.f;
; #pragma unroll
;                 for (int j = 0; j < 4; ++j) ss[r] += mv[r][j][0] * mv[r][j][0] + mv[r][j][1] * mv[r][j][1] + mv[r][j][2] * mv[r][j][2] + mv[r][j][3] * mv[r][j][3]; }
; #pragma unroll
;             for (int o = 32; o >= 1; o >>= 1)
; #pragma unroll
;                 for (int r = 0; r < RB; ++r) ss[r] += shx(ss[r], o);
; #pragma unroll
;             for (int j = 0; j < 4; ++j) { const f32x4 g = *(const f32x4*)(g_post + lane * 4 + 256 * j);
; #pragma unroll
;                 for (int r = 0; r < RB; ++r) { const float r1 = rsqrtf(ss[r] * (1.f / DM) + EPS); xv[r][j] = xv[r][j] + mv[r][j] * r1 * g; *(f32x4*)(xdst + (size_t)(rowb + r) * DM + lane * 4 + 256 * j) = xv[r][j]; } }
	v_lshlrev_b32_e32 v208, 16, v176
	v_and_b32_e32 v209, 0xffff0000, v176
	v_lshlrev_b32_e32 v210, 16, v177
	v_and_b32_e32 v211, 0xffff0000, v177
	v_lshlrev_b32_e32 v212, 16, v178
	v_and_b32_e32 v213, 0xffff0000, v178
	v_lshlrev_b32_e32 v214, 16, v179
	v_and_b32_e32 v215, 0xffff0000, v179
	v_lshlrev_b32_e32 v216, 16, v180
	v_and_b32_e32 v217, 0xffff0000, v180
	v_lshlrev_b32_e32 v218, 16, v181
	v_and_b32_e32 v219, 0xffff0000, v181
	v_lshlrev_b32_e32 v220, 16, v182
	v_and_b32_e32 v221, 0xffff0000, v182
	v_lshlrev_b32_e32 v222, 16, v183
	v_and_b32_e32 v223, 0xffff0000, v183
	v_mul_f32_e32 v224, v208, v208
	v_fmac_f32_e32 v224, v209, v209
	v_fmac_f32_e32 v224, v210, v210
	v_fmac_f32_e32 v224, v211, v211
	v_fmac_f32_e32 v224, v212, v212
	v_fmac_f32_e32 v224, v213, v213
	v_fmac_f32_e32 v224, v214, v214
	v_fmac_f32_e32 v224, v215, v215
	v_fmac_f32_e32 v224, v216, v216
	v_fmac_f32_e32 v224, v217, v217
	v_fmac_f32_e32 v224, v218, v218
	v_fmac_f32_e32 v224, v219, v219
	v_fmac_f32_e32 v224, v220, v220
	v_fmac_f32_e32 v224, v221, v221
	v_fmac_f32_e32 v224, v222, v222
	v_fmac_f32_e32 v224, v223, v223
	s_nop 1
	v_add_f32_dpp v224, v224, v224 quad_perm:[1,0,3,2] row_mask:0xf bank_mask:0xf
	s_nop 1
	v_add_f32_dpp v224, v224, v224 quad_perm:[2,3,0,1] row_mask:0xf bank_mask:0xf
	s_nop 1
	v_add_f32_dpp v224, v224, v224 row_ror:4 row_mask:0xf bank_mask:0xf
	s_nop 1
	v_add_f32_dpp v224, v224, v224 row_ror:8 row_mask:0xf bank_mask:0xf
	s_nop 1
	v_readlane_b32 s20, v224, 0
	v_readlane_b32 s21, v224, 16
	v_readlane_b32 s22, v224, 32
	v_readlane_b32 s23, v224, 48
	s_nop 1
	v_mov_b32_e32 v225, s20
	v_add_f32_e32 v225, s21, v225
	v_add_f32_e32 v225, s22, v225
	v_add_f32_e32 v225, s23, v225
	v_mov_b32_e32 v226, 0x358637bd
	v_fmac_f32_e32 v226, 0x3a800000, v225
	v_rsq_f32_e32 v226, v226
	s_nop 0
	v_mul_f32_e32 v208, v208, v226
	v_mul_f32_e32 v209, v209, v226
	v_mul_f32_e32 v210, v210, v226
	v_mul_f32_e32 v211, v211, v226
	v_mul_f32_e32 v212, v212, v226
	v_mul_f32_e32 v213, v213, v226
	v_mul_f32_e32 v214, v214, v226
	v_mul_f32_e32 v215, v215, v226
	v_mul_f32_e32 v216, v216, v226
	v_mul_f32_e32 v217, v217, v226
	v_mul_f32_e32 v218, v218, v226
	v_mul_f32_e32 v219, v219, v226
	v_mul_f32_e32 v220, v220, v226
	v_mul_f32_e32 v221, v221, v226
	v_mul_f32_e32 v222, v222, v226
	v_mul_f32_e32 v223, v223, v226
	v_fmac_f32_e32 v160, v208, v40
	v_fmac_f32_e32 v161, v209, v41
	v_fmac_f32_e32 v162, v210, v42
	v_fmac_f32_e32 v163, v211, v43
	v_fmac_f32_e32 v164, v212, v44
	v_fmac_f32_e32 v165, v213, v45
	v_fmac_f32_e32 v166, v214, v46
	v_fmac_f32_e32 v167, v215, v47
	v_fmac_f32_e32 v168, v216, v48
	v_fmac_f32_e32 v169, v217, v49
	v_fmac_f32_e32 v170, v218, v50
	v_fmac_f32_e32 v171, v219, v51
	v_fmac_f32_e32 v172, v220, v52
	v_fmac_f32_e32 v173, v221, v53
	v_fmac_f32_e32 v174, v222, v54
	v_fmac_f32_e32 v175, v223, v55
	v_lshlrev_b32_e32 v208, 16, v184
	v_and_b32_e32 v209, 0xffff0000, v184
	v_lshlrev_b32_e32 v210, 16, v185
	v_and_b32_e32 v211, 0xffff0000, v185
	v_lshlrev_b32_e32 v212, 16, v186
	v_and_b32_e32 v213, 0xffff0000, v186
	v_lshlrev_b32_e32 v214, 16, v187
	v_and_b32_e32 v215, 0xffff0000, v187
	v_lshlrev_b32_e32 v216, 16, v188
	v_and_b32_e32 v217, 0xffff0000, v188
	v_lshlrev_b32_e32 v218, 16, v189
	v_and_b32_e32 v219, 0xffff0000, v189
	v_lshlrev_b32_e32 v220, 16, v190
	v_and_b32_e32 v221, 0xffff0000, v190
	v_lshlrev_b32_e32 v222, 16, v191
	v_and_b32_e32 v223, 0xffff0000, v191
	v_mul_f32_e32 v224, v208, v208
	v_fmac_f32_e32 v224, v209, v209
	v_fmac_f32_e32 v224, v210, v210
	v_fmac_f32_e32 v224, v211, v211
	v_fmac_f32_e32 v224, v212, v212
	v_fmac_f32_e32 v224, v213, v213
	v_fmac_f32_e32 v224, v214, v214
	v_fmac_f32_e32 v224, v215, v215
	v_fmac_f32_e32 v224, v216, v216
	v_fmac_f32_e32 v224, v217, v217
	v_fmac_f32_e32 v224, v218, v218
	v_fmac_f32_e32 v224, v219, v219
	v_fmac_f32_e32 v224, v220, v220
	v_fmac_f32_e32 v224, v221, v221
	v_fmac_f32_e32 v224, v222, v222
	v_fmac_f32_e32 v224, v223, v223
	s_nop 1
	v_add_f32_dpp v224, v224, v224 quad_perm:[1,0,3,2] row_mask:0xf bank_mask:0xf
	s_nop 1
	v_add_f32_dpp v224, v224, v224 quad_perm:[2,3,0,1] row_mask:0xf bank_mask:0xf
	s_nop 1
	v_add_f32_dpp v224, v224, v224 row_ror:4 row_mask:0xf bank_mask:0xf
	s_nop 1
	v_add_f32_dpp v224, v224, v224 row_ror:8 row_mask:0xf bank_mask:0xf
	s_nop 1
	v_readlane_b32 s20, v224, 0
	v_readlane_b32 s21, v224, 16
	v_readlane_b32 s22, v224, 32
	v_readlane_b32 s23, v224, 48
	s_nop 1
	v_mov_b32_e32 v225, s20
	v_add_f32_e32 v225, s21, v225
	v_add_f32_e32 v225, s22, v225
	v_add_f32_e32 v225, s23, v225
	v_mov_b32_e32 v226, 0x358637bd
	v_fmac_f32_e32 v226, 0x3a800000, v225
	v_rsq_f32_e32 v226, v226
	s_nop 0
	v_mul_f32_e32 v208, v208, v226
	v_mul_f32_e32 v209, v209, v226
	v_mul_f32_e32 v210, v210, v226
	v_mul_f32_e32 v211, v211, v226
	v_mul_f32_e32 v212, v212, v226
	v_mul_f32_e32 v213, v213, v226
	v_mul_f32_e32 v214, v214, v226
	v_mul_f32_e32 v215, v215, v226
	v_mul_f32_e32 v216, v216, v226
	v_mul_f32_e32 v217, v217, v226
	v_mul_f32_e32 v218, v218, v226
	v_mul_f32_e32 v219, v219, v226
	v_mul_f32_e32 v220, v220, v226
	v_mul_f32_e32 v221, v221, v226
	v_mul_f32_e32 v222, v222, v226
	v_mul_f32_e32 v223, v223, v226
	v_fmac_f32_e32 v160, v208, v56
	v_fmac_f32_e32 v161, v209, v57
	v_fmac_f32_e32 v162, v210, v58
	v_fmac_f32_e32 v163, v211, v59
	v_fmac_f32_e32 v164, v212, v60
	v_fmac_f32_e32 v165, v213, v61
	v_fmac_f32_e32 v166, v214, v62
	v_fmac_f32_e32 v167, v215, v63
	v_fmac_f32_e32 v168, v216, v64
	v_fmac_f32_e32 v169, v217, v65
	v_fmac_f32_e32 v170, v218, v66
	v_fmac_f32_e32 v171, v219, v67
	v_fmac_f32_e32 v172, v220, v68
	v_fmac_f32_e32 v173, v221, v69
	v_fmac_f32_e32 v174, v222, v70
	v_fmac_f32_e32 v175, v223, v71
; DI unsigned pk_bf16(float a, float b) { f32x2_t v = {a, b}; bf16x2_t r = __builtin_convertvector(v, bf16x2_t); return __builtin_bit_cast(unsigned, r); }
; DI float shx(float v, int mask) { const int l = olane(); return __builtin_bit_cast(float, __builtin_amdgcn_ds_bpermute(((l ^ mask) & 63) << 2, __builtin_bit_cast(int, v))); }
; DI void row_phase(const bf16_t* msrc, const float* xsrc, float* xdst, const float* g_post, const float* g_next, bf16_t* hdst, const int gw) {
;     ...
;                     mv[r][j] = (f32x4){__uint_as_float(mw[0] << 16), __uint_as_float(mw[0] & 0xffff0000u), __uint_as_float(mw[1] << 16), __uint_as_float(mw[1] & 0xffff0000u)}; }
;             float ss[RB];
; #pragma unroll
;             for (int r = 0; r < RB; ++r) { ss[r] = 0.f;
; #pragma unroll
;                 for (int j = 0; j < 4; ++j) ss[r] += mv[r][j][0] * mv[r][j][0] + mv[r][j][1] * mv[r][j][1] + mv[r][j][2] * mv[r][j][2] + mv[r][j][3] * mv[r][j][3]; }
; #pragma unroll
;             for (int o = 32; o >= 1; o >>= 1)
; #pragma unroll
;                 for (int r = 0; r < RB; ++r) ss[r] += shx(ss[r], o);
; #pragma unroll
;             for (int j = 0; j < 4; ++j) { const f32x4 g = *(const f32x4*)(g_post + lane * 4 + 256 * j);
; #pragma unroll
;                 for (int r = 0; r < RB; ++r) { const float r1 = rsqrtf(ss[r] * (1.f / DM) + EPS); xv[r][j] = xv[r][j] + mv[r][j] * r1 * g; *(f32x4*)(xdst + (size_t)(rowb + r) * DM + lane * 4 + 256 * j) = xv[r][j]; } }
;         }
;         if (hdst) {
;             float ss[RB];
; #pragma unroll
;             for (int r = 0; r < RB; ++r) { ss[r] = 0.f;
; #pragma unroll
;                 for (int j = 0; j < 4; ++j) ss[r] += xv[r][j][0] * xv[r][j][0] + xv[r][j][1] * xv[r][j][1] + xv[r][j][2] * xv[r][j][2] + xv[r][j][3] * xv[r][j][3]; }
; #pragma unroll
;             for (int o = 32; o >= 1; o >>= 1)
; #pragma unroll
;                 for (int r = 0; r < RB; ++r) ss[r] += shx(ss[r], o);
; #pragma unroll
;             for (int j = 0; j < 4; ++j) { const f32x4 g = *(const f32x4*)(g_next + lane * 4 + 256 * j);
; #pragma unroll
;                 for (int r = 0; r < RB; ++r) { const float r2 = rsqrtf(ss[r] * (1.f / DM) + EPS); const f32x4 hv = xv[r][j] * r2 * g;
;                     u32x2 o; o[0] = pk_bf16(hv[0], hv[1]); o[1] = pk_bf16(hv[2], hv[3]); *(u32x2*)(hdst + (size_t)(rowb + r) * DM + lane * 4 + 256 * j) = o; } }
	global_store_dwordx4 v1, v[160:163], s[8:9] offset:0
	global_store_dwordx4 v1, v[164:167], s[8:9] offset:16
	global_store_dwordx4 v1, v[168:171], s[8:9] offset:2048
	global_store_dwordx4 v1, v[172:175], s[8:9] offset:2064
	s_add_u32 s8, s8, 0x1000
	s_addc_u32 s9, s9, 0
	v_mul_f32_e32 v224, v160, v160
	v_fmac_f32_e32 v224, v161, v161
	v_fmac_f32_e32 v224, v162, v162
	v_fmac_f32_e32 v224, v163, v163
	v_fmac_f32_e32 v224, v164, v164
	v_fmac_f32_e32 v224, v165, v165
	v_fmac_f32_e32 v224, v166, v166
	v_fmac_f32_e32 v224, v167, v167
	v_fmac_f32_e32 v224, v168, v168
	v_fmac_f32_e32 v224, v169, v169
	v_fmac_f32_e32 v224, v170, v170
	v_fmac_f32_e32 v224, v171, v171
	v_fmac_f32_e32 v224, v172, v172
	v_fmac_f32_e32 v224, v173, v173
	v_fmac_f32_e32 v224, v174, v174
	v_fmac_f32_e32 v224, v175, v175
	s_nop 1
	v_add_f32_dpp v224, v224, v224 quad_perm:[1,0,3,2] row_mask:0xf bank_mask:0xf
	s_nop 1
	v_add_f32_dpp v224, v224, v224 quad_perm:[2,3,0,1] row_mask:0xf bank_mask:0xf
	s_nop 1
	v_add_f32_dpp v224, v224, v224 row_ror:4 row_mask:0xf bank_mask:0xf
	s_nop 1
	v_add_f32_dpp v224, v224, v224 row_ror:8 row_mask:0xf bank_mask:0xf
	s_nop 1
	v_readlane_b32 s20, v224, 0
	v_readlane_b32 s21, v224, 16
	v_readlane_b32 s22, v224, 32
	v_readlane_b32 s23, v224, 48
	s_nop 1
	v_mov_b32_e32 v225, s20
	v_add_f32_e32 v225, s21, v225
	v_add_f32_e32 v225, s22, v225
	v_add_f32_e32 v225, s23, v225
	v_mov_b32_e32 v226, 0x358637bd
	v_fmac_f32_e32 v226, 0x3a800000, v225
	v_rsq_f32_e32 v226, v226
	s_nop 0
	v_mul_f32_e32 v208, v160, v226
	v_mul_f32_e32 v209, v161, v226
	v_mul_f32_e32 v210, v162, v226
	v_mul_f32_e32 v211, v163, v226
	v_mul_f32_e32 v212, v164, v226
	v_mul_f32_e32 v213, v165, v226
	v_mul_f32_e32 v214, v166, v226
	v_mul_f32_e32 v215, v167, v226
	v_mul_f32_e32 v216, v168, v226
	v_mul_f32_e32 v217, v169, v226
	v_mul_f32_e32 v218, v170, v226
	v_mul_f32_e32 v219, v171, v226
	v_mul_f32_e32 v220, v172, v226
	v_mul_f32_e32 v221, v173, v226
	v_mul_f32_e32 v222, v174, v226
	v_mul_f32_e32 v223, v175, v226
	v_mul_f32_e32 v208, v208, v72
	v_mul_f32_e32 v209, v209, v73
	v_mul_f32_e32 v210, v210, v74
	v_mul_f32_e32 v211, v211, v75
	v_mul_f32_e32 v212, v212, v76
	v_mul_f32_e32 v213, v213, v77
	v_mul_f32_e32 v214, v214, v78
	v_mul_f32_e32 v215, v215, v79
	v_mul_f32_e32 v216, v216, v80
	v_mul_f32_e32 v217, v217, v81
	v_mul_f32_e32 v218, v218, v82
	v_mul_f32_e32 v219, v219, v83
	v_mul_f32_e32 v220, v220, v84
	v_mul_f32_e32 v221, v221, v85
	v_mul_f32_e32 v222, v222, v86
	v_mul_f32_e32 v223, v223, v87
	v_cvt_pk_bf16_f32 v176, v208, v209
	v_cvt_pk_bf16_f32 v177, v210, v211
	v_cvt_pk_bf16_f32 v178, v212, v213
	v_cvt_pk_bf16_f32 v179, v214, v215
	v_cvt_pk_bf16_f32 v180, v216, v217
	v_cvt_pk_bf16_f32 v181, v218, v219
	v_cvt_pk_bf16_f32 v182, v220, v221
	v_cvt_pk_bf16_f32 v183, v222, v223
	global_store_dwordx4 v2, v[176:179], s[14:15]
	global_store_dwordx4 v2, v[180:183], s[14:15] offset:1024
	s_add_u32 s14, s14, 0x800
	s_addc_u32 s15, s15, 0
	s_waitcnt vmcnt(20)
	v_lshlrev_b32_e32 v208, 16, v112
	v_and_b32_e32 v209, 0xffff0000, v112
	v_lshlrev_b32_e32 v210, 16, v113
	v_and_b32_e32 v211, 0xffff0000, v113
	v_lshlrev_b32_e32 v212, 16, v114
	v_and_b32_e32 v213, 0xffff0000, v114
	v_lshlrev_b32_e32 v214, 16, v115
	v_and_b32_e32 v215, 0xffff0000, v115
	v_lshlrev_b32_e32 v216, 16, v116
	v_and_b32_e32 v217, 0xffff0000, v116
	v_lshlrev_b32_e32 v218, 16, v117
	v_and_b32_e32 v219, 0xffff0000, v117
	v_lshlrev_b32_e32 v220, 16, v118
	v_and_b32_e32 v221, 0xffff0000, v118
	v_lshlrev_b32_e32 v222, 16, v119
	v_and_b32_e32 v223, 0xffff0000, v119
	v_mul_f32_e32 v224, v208, v208
	v_fmac_f32_e32 v224, v209, v209
	v_fmac_f32_e32 v224, v210, v210
	v_fmac_f32_e32 v224, v211, v211
	v_fmac_f32_e32 v224, v212, v212
	v_fmac_f32_e32 v224, v213, v213
	v_fmac_f32_e32 v224, v214, v214
	v_fmac_f32_e32 v224, v215, v215
	v_fmac_f32_e32 v224, v216, v216
	v_fmac_f32_e32 v224, v217, v217
	v_fmac_f32_e32 v224, v218, v218
	v_fmac_f32_e32 v224, v219, v219
	v_fmac_f32_e32 v224, v220, v220
	v_fmac_f32_e32 v224, v221, v221
	v_fmac_f32_e32 v224, v222, v222
	v_fmac_f32_e32 v224, v223, v223
	s_nop 1
	v_add_f32_dpp v224, v224, v224 quad_perm:[1,0,3,2] row_mask:0xf bank_mask:0xf
	s_nop 1
	v_add_f32_dpp v224, v224, v224 quad_perm:[2,3,0,1] row_mask:0xf bank_mask:0xf
	s_nop 1
	v_add_f32_dpp v224, v224, v224 row_ror:4 row_mask:0xf bank_mask:0xf
	s_nop 1
	v_add_f32_dpp v224, v224, v224 row_ror:8 row_mask:0xf bank_mask:0xf
	s_nop 1
	v_readlane_b32 s20, v224, 0
	v_readlane_b32 s21, v224, 16
	v_readlane_b32 s22, v224, 32
	v_readlane_b32 s23, v224, 48
	s_nop 1
	v_mov_b32_e32 v225, s20
	v_add_f32_e32 v225, s21, v225
	v_add_f32_e32 v225, s22, v225
	v_add_f32_e32 v225, s23, v225
	v_mov_b32_e32 v226, 0x358637bd
	v_fmac_f32_e32 v226, 0x3a800000, v225
	v_rsq_f32_e32 v226, v226
	s_nop 0
	v_mul_f32_e32 v208, v208, v226
	v_mul_f32_e32 v209, v209, v226
	v_mul_f32_e32 v210, v210, v226
	v_mul_f32_e32 v211, v211, v226
	v_mul_f32_e32 v212, v212, v226
	v_mul_f32_e32 v213, v213, v226
	v_mul_f32_e32 v214, v214, v226
	v_mul_f32_e32 v215, v215, v226
	v_mul_f32_e32 v216, v216, v226
	v_mul_f32_e32 v217, v217, v226
	v_mul_f32_e32 v218, v218, v226
	v_mul_f32_e32 v219, v219, v226
	v_mul_f32_e32 v220, v220, v226
	v_mul_f32_e32 v221, v221, v226
	v_mul_f32_e32 v222, v222, v226
	v_mul_f32_e32 v223, v223, v226
	v_fmac_f32_e32 v96, v208, v40
	v_fmac_f32_e32 v97, v209, v41
	v_fmac_f32_e32 v98, v210, v42
	v_fmac_f32_e32 v99, v211, v43
	v_fmac_f32_e32 v100, v212, v44
	v_fmac_f32_e32 v101, v213, v45
	v_fmac_f32_e32 v102, v214, v46
	v_fmac_f32_e32 v103, v215, v47
	v_fmac_f32_e32 v104, v216, v48
	v_fmac_f32_e32 v105, v217, v49
	v_fmac_f32_e32 v106, v218, v50
	v_fmac_f32_e32 v107, v219, v51
; DI unsigned pk_bf16(float a, float b) { f32x2_t v = {a, b}; bf16x2_t r = __builtin_convertvector(v, bf16x2_t); return __builtin_bit_cast(unsigned, r); }
; DI float shx(float v, int mask) { const int l = olane(); return __builtin_bit_cast(float, __builtin_amdgcn_ds_bpermute(((l ^ mask) & 63) << 2, __builtin_bit_cast(int, v))); }
; DI void row_phase(const bf16_t* msrc, const float* xsrc, float* xdst, const float* g_post, const float* g_next, bf16_t* hdst, const int gw) {
;     ...
;                     mv[r][j] = (f32x4){__uint_as_float(mw[0] << 16), __uint_as_float(mw[0] & 0xffff0000u), __uint_as_float(mw[1] << 16), __uint_as_float(mw[1] & 0xffff0000u)}; }
;             float ss[RB];
; #pragma unroll
;             for (int r = 0; r < RB; ++r) { ss[r] = 0.f;
; #pragma unroll
;                 for (int j = 0; j < 4; ++j) ss[r] += mv[r][j][0] * mv[r][j][0] + mv[r][j][1] * mv[r][j][1] + mv[r][j][2] * mv[r][j][2] + mv[r][j][3] * mv[r][j][3]; }
; #pragma unroll
;             for (int o = 32; o >= 1; o >>= 1)
; #pragma unroll
;                 for (int r = 0; r < RB; ++r) ss[r] += shx(ss[r], o);
; #pragma unroll
;             for (int j = 0; j < 4; ++j) { const f32x4 g = *(const f32x4*)(g_post + lane * 4 + 256 * j);
; #pragma unroll
;                 for (int r = 0; r < RB; ++r) { const float r1 = rsqrtf(ss[r] * (1.f / DM) + EPS); xv[r][j] = xv[r][j] + mv[r][j] * r1 * g; *(f32x4*)(xdst + (size_t)(rowb + r) * DM + lane * 4 + 256 * j) = xv[r][j]; } }
;         }
;         if (hdst) {
;             float ss[RB];
; #pragma unroll
;             for (int r = 0; r < RB; ++r) { ss[r] = 0.f;
; #pragma unroll
;                 for (int j = 0; j < 4; ++j) ss[r] += xv[r][j][0] * xv[r][j][0] + xv[r][j][1] * xv[r][j][1] + xv[r][j][2] * xv[r][j][2] + xv[r][j][3] * xv[r][j][3]; }
; #pragma unroll
;             for (int o = 32; o >= 1; o >>= 1)
; #pragma unroll
;                 for (int r = 0; r < RB; ++r) ss[r] += shx(ss[r], o);
; #pragma unroll
;             for (int j = 0; j < 4; ++j) { const f32x4 g = *(const f32x4*)(g_next + lane * 4 + 256 * j);
; #pragma unroll
;                 for (int r = 0; r < RB; ++r) { const float r2 = rsqrtf(ss[r] * (1.f / DM) + EPS); const f32x4 hv = xv[r][j] * r2 * g;
;                     u32x2 o; o[0] = pk_bf16(hv[0], hv[1]); o[1] = pk_bf16(hv[2], hv[3]); *(u32x2*)(hdst + (size_t)(rowb + r) * DM + lane * 4 + 256 * j) = o; } }
	v_fmac_f32_e32 v108, v220, v52
	v_fmac_f32_e32 v109, v221, v53
	v_fmac_f32_e32 v110, v222, v54
	v_fmac_f32_e32 v111, v223, v55
	v_lshlrev_b32_e32 v208, 16, v120
	v_and_b32_e32 v209, 0xffff0000, v120
	v_lshlrev_b32_e32 v210, 16, v121
	v_and_b32_e32 v211, 0xffff0000, v121
	v_lshlrev_b32_e32 v212, 16, v122
	v_and_b32_e32 v213, 0xffff0000, v122
	v_lshlrev_b32_e32 v214, 16, v123
	v_and_b32_e32 v215, 0xffff0000, v123
	v_lshlrev_b32_e32 v216, 16, v124
	v_and_b32_e32 v217, 0xffff0000, v124
	v_lshlrev_b32_e32 v218, 16, v125
	v_and_b32_e32 v219, 0xffff0000, v125
	v_lshlrev_b32_e32 v220, 16, v126
	v_and_b32_e32 v221, 0xffff0000, v126
	v_lshlrev_b32_e32 v222, 16, v127
	v_and_b32_e32 v223, 0xffff0000, v127
	v_mul_f32_e32 v224, v208, v208
	v_fmac_f32_e32 v224, v209, v209
	v_fmac_f32_e32 v224, v210, v210
	v_fmac_f32_e32 v224, v211, v211
	v_fmac_f32_e32 v224, v212, v212
	v_fmac_f32_e32 v224, v213, v213
	v_fmac_f32_e32 v224, v214, v214
	v_fmac_f32_e32 v224, v215, v215
	v_fmac_f32_e32 v224, v216, v216
	v_fmac_f32_e32 v224, v217, v217
	v_fmac_f32_e32 v224, v218, v218
	v_fmac_f32_e32 v224, v219, v219
	v_fmac_f32_e32 v224, v220, v220
	v_fmac_f32_e32 v224, v221, v221
	v_fmac_f32_e32 v224, v222, v222
	v_fmac_f32_e32 v224, v223, v223
	s_nop 1
	v_add_f32_dpp v224, v224, v224 quad_perm:[1,0,3,2] row_mask:0xf bank_mask:0xf
	s_nop 1
	v_add_f32_dpp v224, v224, v224 quad_perm:[2,3,0,1] row_mask:0xf bank_mask:0xf
	s_nop 1
	v_add_f32_dpp v224, v224, v224 row_ror:4 row_mask:0xf bank_mask:0xf
	s_nop 1
	v_add_f32_dpp v224, v224, v224 row_ror:8 row_mask:0xf bank_mask:0xf
	s_nop 1
	v_readlane_b32 s20, v224, 0
	v_readlane_b32 s21, v224, 16
	v_readlane_b32 s22, v224, 32
	v_readlane_b32 s23, v224, 48
	s_nop 1
	v_mov_b32_e32 v225, s20
	v_add_f32_e32 v225, s21, v225
	v_add_f32_e32 v225, s22, v225
	v_add_f32_e32 v225, s23, v225
	v_mov_b32_e32 v226, 0x358637bd
	v_fmac_f32_e32 v226, 0x3a800000, v225
	v_rsq_f32_e32 v226, v226
	s_nop 0
	v_mul_f32_e32 v208, v208, v226
	v_mul_f32_e32 v209, v209, v226
	v_mul_f32_e32 v210, v210, v226
	v_mul_f32_e32 v211, v211, v226
	v_mul_f32_e32 v212, v212, v226
	v_mul_f32_e32 v213, v213, v226
	v_mul_f32_e32 v214, v214, v226
	v_mul_f32_e32 v215, v215, v226
	v_mul_f32_e32 v216, v216, v226
	v_mul_f32_e32 v217, v217, v226
	v_mul_f32_e32 v218, v218, v226
	v_mul_f32_e32 v219, v219, v226
	v_mul_f32_e32 v220, v220, v226
	v_mul_f32_e32 v221, v221, v226
	v_mul_f32_e32 v222, v222, v226
	v_mul_f32_e32 v223, v223, v226
	v_fmac_f32_e32 v96, v208, v56
	v_fmac_f32_e32 v97, v209, v57
	v_fmac_f32_e32 v98, v210, v58
	v_fmac_f32_e32 v99, v211, v59
	v_fmac_f32_e32 v100, v212, v60
	v_fmac_f32_e32 v101, v213, v61
	v_fmac_f32_e32 v102, v214, v62
	v_fmac_f32_e32 v103, v215, v63
	v_fmac_f32_e32 v104, v216, v64
	v_fmac_f32_e32 v105, v217, v65
	v_fmac_f32_e32 v106, v218, v66
	v_fmac_f32_e32 v107, v219, v67
	v_fmac_f32_e32 v108, v220, v68
	v_fmac_f32_e32 v109, v221, v69
	v_fmac_f32_e32 v110, v222, v70
	v_fmac_f32_e32 v111, v223, v71
	global_store_dwordx4 v1, v[96:99], s[8:9] offset:0
	global_store_dwordx4 v1, v[100:103], s[8:9] offset:16
	global_store_dwordx4 v1, v[104:107], s[8:9] offset:2048
	global_store_dwordx4 v1, v[108:111], s[8:9] offset:2064
	s_add_u32 s8, s8, 0x1000
	s_addc_u32 s9, s9, 0
	v_mul_f32_e32 v224, v96, v96
	v_fmac_f32_e32 v224, v97, v97
	v_fmac_f32_e32 v224, v98, v98
	v_fmac_f32_e32 v224, v99, v99
	v_fmac_f32_e32 v224, v100, v100
	v_fmac_f32_e32 v224, v101, v101
	v_fmac_f32_e32 v224, v102, v102
	v_fmac_f32_e32 v224, v103, v103
	v_fmac_f32_e32 v224, v104, v104
	v_fmac_f32_e32 v224, v105, v105
	v_fmac_f32_e32 v224, v106, v106
	v_fmac_f32_e32 v224, v107, v107
	v_fmac_f32_e32 v224, v108, v108
	v_fmac_f32_e32 v224, v109, v109
	v_fmac_f32_e32 v224, v110, v110
	v_fmac_f32_e32 v224, v111, v111
	s_nop 1
	v_add_f32_dpp v224, v224, v224 quad_perm:[1,0,3,2] row_mask:0xf bank_mask:0xf
	s_nop 1
	v_add_f32_dpp v224, v224, v224 quad_perm:[2,3,0,1] row_mask:0xf bank_mask:0xf
	s_nop 1
	v_add_f32_dpp v224, v224, v224 row_ror:4 row_mask:0xf bank_mask:0xf
	s_nop 1
	v_add_f32_dpp v224, v224, v224 row_ror:8 row_mask:0xf bank_mask:0xf
	s_nop 1
	v_readlane_b32 s20, v224, 0
	v_readlane_b32 s21, v224, 16
	v_readlane_b32 s22, v224, 32
	v_readlane_b32 s23, v224, 48
	s_nop 1
	v_mov_b32_e32 v225, s20
	v_add_f32_e32 v225, s21, v225
	v_add_f32_e32 v225, s22, v225
	v_add_f32_e32 v225, s23, v225
	v_mov_b32_e32 v226, 0x358637bd
	v_fmac_f32_e32 v226, 0x3a800000, v225
	v_rsq_f32_e32 v226, v226
	s_nop 0
	v_mul_f32_e32 v208, v96, v226
	v_mul_f32_e32 v209, v97, v226
	v_mul_f32_e32 v210, v98, v226
	v_mul_f32_e32 v211, v99, v226
	v_mul_f32_e32 v212, v100, v226
	v_mul_f32_e32 v213, v101, v226
	v_mul_f32_e32 v214, v102, v226
	v_mul_f32_e32 v215, v103, v226
	v_mul_f32_e32 v216, v104, v226
	v_mul_f32_e32 v217, v105, v226
	v_mul_f32_e32 v218, v106, v226
	v_mul_f32_e32 v219, v107, v226
	v_mul_f32_e32 v220, v108, v226
	v_mul_f32_e32 v221, v109, v226
	v_mul_f32_e32 v222, v110, v226
	v_mul_f32_e32 v223, v111, v226
	v_mul_f32_e32 v208, v208, v72
	v_mul_f32_e32 v209, v209, v73
	v_mul_f32_e32 v210, v210, v74
	v_mul_f32_e32 v211, v211, v75
	v_mul_f32_e32 v212, v212, v76
	v_mul_f32_e32 v213, v213, v77
	v_mul_f32_e32 v214, v214, v78
	v_mul_f32_e32 v215, v215, v79
	v_mul_f32_e32 v216, v216, v80
	v_mul_f32_e32 v217, v217, v81
	v_mul_f32_e32 v218, v218, v82
	v_mul_f32_e32 v219, v219, v83
	v_mul_f32_e32 v220, v220, v84
	v_mul_f32_e32 v221, v221, v85
	v_mul_f32_e32 v222, v222, v86
	v_mul_f32_e32 v223, v223, v87
	v_cvt_pk_bf16_f32 v112, v208, v209
	v_cvt_pk_bf16_f32 v113, v210, v211
	v_cvt_pk_bf16_f32 v114, v212, v213
	v_cvt_pk_bf16_f32 v115, v214, v215
	v_cvt_pk_bf16_f32 v116, v216, v217
	v_cvt_pk_bf16_f32 v117, v218, v219
	v_cvt_pk_bf16_f32 v118, v220, v221
	v_cvt_pk_bf16_f32 v119, v222, v223
	global_store_dwordx4 v2, v[112:115], s[14:15]
	global_store_dwordx4 v2, v[116:119], s[14:15] offset:1024
	s_add_u32 s14, s14, 0x800
	s_addc_u32 s15, s15, 0
	s_waitcnt vmcnt(12)
; DI float shx(float v, int mask) { const int l = olane(); return __builtin_bit_cast(float, __builtin_amdgcn_ds_bpermute(((l ^ mask) & 63) << 2, __builtin_bit_cast(int, v))); }
; DI void row_phase(const bf16_t* msrc, const float* xsrc, float* xdst, const float* g_post, const float* g_next, bf16_t* hdst, const int gw) {
;     ...
;                     mv[r][j] = (f32x4){__uint_as_float(mw[0] << 16), __uint_as_float(mw[0] & 0xffff0000u), __uint_as_float(mw[1] << 16), __uint_as_float(mw[1] & 0xffff0000u)}; }
;             float ss[RB];
; #pragma unroll
;             for (int r = 0; r < RB; ++r) { ss[r] = 0.f;
; #pragma unroll
;                 for (int j = 0; j < 4; ++j) ss[r] += mv[r][j][0] * mv[r][j][0] + mv[r][j][1] * mv[r][j][1] + mv[r][j][2] * mv[r][j][2] + mv[r][j][3] * mv[r][j][3]; }
; #pragma unroll
;             for (int o = 32; o >= 1; o >>= 1)
; #pragma unroll
;                 for (int r = 0; r < RB; ++r) ss[r] += shx(ss[r], o);
; #pragma unroll
;             for (int j = 0; j < 4; ++j) { const f32x4 g = *(const f32x4*)(g_post + lane * 4 + 256 * j);
; #pragma unroll
;                 for (int r = 0; r < RB; ++r) { const float r1 = rsqrtf(ss[r] * (1.f / DM) + EPS); xv[r][j] = xv[r][j] + mv[r][j] * r1 * g; *(f32x4*)(xdst + (size_t)(rowb + r) * DM + lane * 4 + 256 * j) = xv[r][j]; } }
	v_lshlrev_b32_e32 v208, 16, v144
	v_and_b32_e32 v209, 0xffff0000, v144
	v_lshlrev_b32_e32 v210, 16, v145
	v_and_b32_e32 v211, 0xffff0000, v145
	v_lshlrev_b32_e32 v212, 16, v146
	v_and_b32_e32 v213, 0xffff0000, v146
	v_lshlrev_b32_e32 v214, 16, v147
	v_and_b32_e32 v215, 0xffff0000, v147
	v_lshlrev_b32_e32 v216, 16, v148
	v_and_b32_e32 v217, 0xffff0000, v148
	v_lshlrev_b32_e32 v218, 16, v149
	v_and_b32_e32 v219, 0xffff0000, v149
	v_lshlrev_b32_e32 v220, 16, v150
	v_and_b32_e32 v221, 0xffff0000, v150
	v_lshlrev_b32_e32 v222, 16, v151
	v_and_b32_e32 v223, 0xffff0000, v151
	v_mul_f32_e32 v224, v208, v208
	v_fmac_f32_e32 v224, v209, v209
	v_fmac_f32_e32 v224, v210, v210
	v_fmac_f32_e32 v224, v211, v211
	v_fmac_f32_e32 v224, v212, v212
	v_fmac_f32_e32 v224, v213, v213
	v_fmac_f32_e32 v224, v214, v214
	v_fmac_f32_e32 v224, v215, v215
	v_fmac_f32_e32 v224, v216, v216
	v_fmac_f32_e32 v224, v217, v217
	v_fmac_f32_e32 v224, v218, v218
	v_fmac_f32_e32 v224, v219, v219
	v_fmac_f32_e32 v224, v220, v220
	v_fmac_f32_e32 v224, v221, v221
	v_fmac_f32_e32 v224, v222, v222
	v_fmac_f32_e32 v224, v223, v223
	s_nop 1
	v_add_f32_dpp v224, v224, v224 quad_perm:[1,0,3,2] row_mask:0xf bank_mask:0xf
	s_nop 1
	v_add_f32_dpp v224, v224, v224 quad_perm:[2,3,0,1] row_mask:0xf bank_mask:0xf
	s_nop 1
	v_add_f32_dpp v224, v224, v224 row_ror:4 row_mask:0xf bank_mask:0xf
	s_nop 1
	v_add_f32_dpp v224, v224, v224 row_ror:8 row_mask:0xf bank_mask:0xf
	s_nop 1
	v_readlane_b32 s20, v224, 0
	v_readlane_b32 s21, v224, 16
	v_readlane_b32 s22, v224, 32
	v_readlane_b32 s23, v224, 48
	s_nop 1
	v_mov_b32_e32 v225, s20
	v_add_f32_e32 v225, s21, v225
	v_add_f32_e32 v225, s22, v225
	v_add_f32_e32 v225, s23, v225
	v_mov_b32_e32 v226, 0x358637bd
	v_fmac_f32_e32 v226, 0x3a800000, v225
	v_rsq_f32_e32 v226, v226
	s_nop 0
	v_mul_f32_e32 v208, v208, v226
	v_mul_f32_e32 v209, v209, v226
	v_mul_f32_e32 v210, v210, v226
	v_mul_f32_e32 v211, v211, v226
	v_mul_f32_e32 v212, v212, v226
	v_mul_f32_e32 v213, v213, v226
	v_mul_f32_e32 v214, v214, v226
	v_mul_f32_e32 v215, v215, v226
	v_mul_f32_e32 v216, v216, v226
	v_mul_f32_e32 v217, v217, v226
	v_mul_f32_e32 v218, v218, v226
	v_mul_f32_e32 v219, v219, v226
	v_mul_f32_e32 v220, v220, v226
	v_mul_f32_e32 v221, v221, v226
	v_mul_f32_e32 v222, v222, v226
	v_mul_f32_e32 v223, v223, v226
	v_fmac_f32_e32 v128, v208, v40
	v_fmac_f32_e32 v129, v209, v41
	v_fmac_f32_e32 v130, v210, v42
	v_fmac_f32_e32 v131, v211, v43
	v_fmac_f32_e32 v132, v212, v44
	v_fmac_f32_e32 v133, v213, v45
	v_fmac_f32_e32 v134, v214, v46
	v_fmac_f32_e32 v135, v215, v47
	v_fmac_f32_e32 v136, v216, v48
	v_fmac_f32_e32 v137, v217, v49
	v_fmac_f32_e32 v138, v218, v50
	v_fmac_f32_e32 v139, v219, v51
	v_fmac_f32_e32 v140, v220, v52
	v_fmac_f32_e32 v141, v221, v53
	v_fmac_f32_e32 v142, v222, v54
	v_fmac_f32_e32 v143, v223, v55
	v_lshlrev_b32_e32 v208, 16, v152
	v_and_b32_e32 v209, 0xffff0000, v152
	v_lshlrev_b32_e32 v210, 16, v153
	v_and_b32_e32 v211, 0xffff0000, v153
	v_lshlrev_b32_e32 v212, 16, v154
	v_and_b32_e32 v213, 0xffff0000, v154
	v_lshlrev_b32_e32 v214, 16, v155
	v_and_b32_e32 v215, 0xffff0000, v155
	v_lshlrev_b32_e32 v216, 16, v156
	v_and_b32_e32 v217, 0xffff0000, v156
	v_lshlrev_b32_e32 v218, 16, v157
	v_and_b32_e32 v219, 0xffff0000, v157
	v_lshlrev_b32_e32 v220, 16, v158
	v_and_b32_e32 v221, 0xffff0000, v158
	v_lshlrev_b32_e32 v222, 16, v159
	v_and_b32_e32 v223, 0xffff0000, v159
	v_mul_f32_e32 v224, v208, v208
	v_fmac_f32_e32 v224, v209, v209
	v_fmac_f32_e32 v224, v210, v210
	v_fmac_f32_e32 v224, v211, v211
	v_fmac_f32_e32 v224, v212, v212
	v_fmac_f32_e32 v224, v213, v213
	v_fmac_f32_e32 v224, v214, v214
	v_fmac_f32_e32 v224, v215, v215
	v_fmac_f32_e32 v224, v216, v216
	v_fmac_f32_e32 v224, v217, v217
	v_fmac_f32_e32 v224, v218, v218
	v_fmac_f32_e32 v224, v219, v219
	v_fmac_f32_e32 v224, v220, v220
	v_fmac_f32_e32 v224, v221, v221
	v_fmac_f32_e32 v224, v222, v222
	v_fmac_f32_e32 v224, v223, v223
	s_nop 1
	v_add_f32_dpp v224, v224, v224 quad_perm:[1,0,3,2] row_mask:0xf bank_mask:0xf
	s_nop 1
	v_add_f32_dpp v224, v224, v224 quad_perm:[2,3,0,1] row_mask:0xf bank_mask:0xf
	s_nop 1
	v_add_f32_dpp v224, v224, v224 row_ror:4 row_mask:0xf bank_mask:0xf
	s_nop 1
	v_add_f32_dpp v224, v224, v224 row_ror:8 row_mask:0xf bank_mask:0xf
	s_nop 1
	v_readlane_b32 s20, v224, 0
	v_readlane_b32 s21, v224, 16
	v_readlane_b32 s22, v224, 32
	v_readlane_b32 s23, v224, 48
	s_nop 1
	v_mov_b32_e32 v225, s20
	v_add_f32_e32 v225, s21, v225
	v_add_f32_e32 v225, s22, v225
	v_add_f32_e32 v225, s23, v225
	v_mov_b32_e32 v226, 0x358637bd
	v_fmac_f32_e32 v226, 0x3a800000, v225
	v_rsq_f32_e32 v226, v226
	s_nop 0
	v_mul_f32_e32 v208, v208, v226
	v_mul_f32_e32 v209, v209, v226
	v_mul_f32_e32 v210, v210, v226
	v_mul_f32_e32 v211, v211, v226
	v_mul_f32_e32 v212, v212, v226
	v_mul_f32_e32 v213, v213, v226
	v_mul_f32_e32 v214, v214, v226
	v_mul_f32_e32 v215, v215, v226
	v_mul_f32_e32 v216, v216, v226
	v_mul_f32_e32 v217, v217, v226
	v_mul_f32_e32 v218, v218, v226
	v_mul_f32_e32 v219, v219, v226
	v_mul_f32_e32 v220, v220, v226
	v_mul_f32_e32 v221, v221, v226
	v_mul_f32_e32 v222, v222, v226
	v_mul_f32_e32 v223, v223, v226
	v_fmac_f32_e32 v128, v208, v56
	v_fmac_f32_e32 v129, v209, v57
	v_fmac_f32_e32 v130, v210, v58
	v_fmac_f32_e32 v131, v211, v59
	v_fmac_f32_e32 v132, v212, v60
	v_fmac_f32_e32 v133, v213, v61
	v_fmac_f32_e32 v134, v214, v62
	v_fmac_f32_e32 v135, v215, v63
	v_fmac_f32_e32 v136, v216, v64
	v_fmac_f32_e32 v137, v217, v65
	v_fmac_f32_e32 v138, v218, v66
	v_fmac_f32_e32 v139, v219, v67
	v_fmac_f32_e32 v140, v220, v68
	v_fmac_f32_e32 v141, v221, v69
	v_fmac_f32_e32 v142, v222, v70
	v_fmac_f32_e32 v143, v223, v71
; DI unsigned pk_bf16(float a, float b) { f32x2_t v = {a, b}; bf16x2_t r = __builtin_convertvector(v, bf16x2_t); return __builtin_bit_cast(unsigned, r); }
; DI float shx(float v, int mask) { const int l = olane(); return __builtin_bit_cast(float, __builtin_amdgcn_ds_bpermute(((l ^ mask) & 63) << 2, __builtin_bit_cast(int, v))); }
; DI void row_phase(const bf16_t* msrc, const float* xsrc, float* xdst, const float* g_post, const float* g_next, bf16_t* hdst, const int gw) {
;     ...
;                 for (int r = 0; r < RB; ++r) { const float r1 = rsqrtf(ss[r] * (1.f / DM) + EPS); xv[r][j] = xv[r][j] + mv[r][j] * r1 * g; *(f32x4*)(xdst + (size_t)(rowb + r) * DM + lane * 4 + 256 * j) = xv[r][j]; } }
;         }
;         if (hdst) {
;             float ss[RB];
; #pragma unroll
;             for (int r = 0; r < RB; ++r) { ss[r] = 0.f;
; #pragma unroll
;                 for (int j = 0; j < 4; ++j) ss[r] += xv[r][j][0] * xv[r][j][0] + xv[r][j][1] * xv[r][j][1] + xv[r][j][2] * xv[r][j][2] + xv[r][j][3] * xv[r][j][3]; }
; #pragma unroll
;             for (int o = 32; o >= 1; o >>= 1)
; #pragma unroll
;                 for (int r = 0; r < RB; ++r) ss[r] += shx(ss[r], o);
; #pragma unroll
;             for (int j = 0; j < 4; ++j) { const f32x4 g = *(const f32x4*)(g_next + lane * 4 + 256 * j);
; #pragma unroll
;                 for (int r = 0; r < RB; ++r) { const float r2 = rsqrtf(ss[r] * (1.f / DM) + EPS); const f32x4 hv = xv[r][j] * r2 * g;
;                     u32x2 o; o[0] = pk_bf16(hv[0], hv[1]); o[1] = pk_bf16(hv[2], hv[3]); *(u32x2*)(hdst + (size_t)(rowb + r) * DM + lane * 4 + 256 * j) = o; } }
	global_store_dwordx4 v1, v[128:131], s[8:9] offset:0
	global_store_dwordx4 v1, v[132:135], s[8:9] offset:16
	global_store_dwordx4 v1, v[136:139], s[8:9] offset:2048
	global_store_dwordx4 v1, v[140:143], s[8:9] offset:2064
	s_add_u32 s8, s8, 0x1000
	s_addc_u32 s9, s9, 0
	v_mul_f32_e32 v224, v128, v128
	v_fmac_f32_e32 v224, v129, v129
	v_fmac_f32_e32 v224, v130, v130
	v_fmac_f32_e32 v224, v131, v131
	v_fmac_f32_e32 v224, v132, v132
	v_fmac_f32_e32 v224, v133, v133
	v_fmac_f32_e32 v224, v134, v134
	v_fmac_f32_e32 v224, v135, v135
	v_fmac_f32_e32 v224, v136, v136
	v_fmac_f32_e32 v224, v137, v137
	v_fmac_f32_e32 v224, v138, v138
	v_fmac_f32_e32 v224, v139, v139
	v_fmac_f32_e32 v224, v140, v140
	v_fmac_f32_e32 v224, v141, v141
	v_fmac_f32_e32 v224, v142, v142
	v_fmac_f32_e32 v224, v143, v143
	s_nop 1
	v_add_f32_dpp v224, v224, v224 quad_perm:[1,0,3,2] row_mask:0xf bank_mask:0xf
	s_nop 1
	v_add_f32_dpp v224, v224, v224 quad_perm:[2,3,0,1] row_mask:0xf bank_mask:0xf
	s_nop 1
	v_add_f32_dpp v224, v224, v224 row_ror:4 row_mask:0xf bank_mask:0xf
	s_nop 1
	v_add_f32_dpp v224, v224, v224 row_ror:8 row_mask:0xf bank_mask:0xf
	s_nop 1
	v_readlane_b32 s20, v224, 0
	v_readlane_b32 s21, v224, 16
	v_readlane_b32 s22, v224, 32
	v_readlane_b32 s23, v224, 48
	s_nop 1
	v_mov_b32_e32 v225, s20
	v_add_f32_e32 v225, s21, v225
	v_add_f32_e32 v225, s22, v225
	v_add_f32_e32 v225, s23, v225
	v_mov_b32_e32 v226, 0x358637bd
	v_fmac_f32_e32 v226, 0x3a800000, v225
	v_rsq_f32_e32 v226, v226
	s_nop 0
	v_mul_f32_e32 v208, v128, v226
	v_mul_f32_e32 v209, v129, v226
	v_mul_f32_e32 v210, v130, v226
	v_mul_f32_e32 v211, v131, v226
	v_mul_f32_e32 v212, v132, v226
	v_mul_f32_e32 v213, v133, v226
	v_mul_f32_e32 v214, v134, v226
	v_mul_f32_e32 v215, v135, v226
	v_mul_f32_e32 v216, v136, v226
	v_mul_f32_e32 v217, v137, v226
	v_mul_f32_e32 v218, v138, v226
	v_mul_f32_e32 v219, v139, v226
	v_mul_f32_e32 v220, v140, v226
	v_mul_f32_e32 v221, v141, v226
	v_mul_f32_e32 v222, v142, v226
	v_mul_f32_e32 v223, v143, v226
	v_mul_f32_e32 v208, v208, v72
	v_mul_f32_e32 v209, v209, v73
	v_mul_f32_e32 v210, v210, v74
	v_mul_f32_e32 v211, v211, v75
	v_mul_f32_e32 v212, v212, v76
	v_mul_f32_e32 v213, v213, v77
	v_mul_f32_e32 v214, v214, v78
	v_mul_f32_e32 v215, v215, v79
	v_mul_f32_e32 v216, v216, v80
	v_mul_f32_e32 v217, v217, v81
	v_mul_f32_e32 v218, v218, v82
	v_mul_f32_e32 v219, v219, v83
	v_mul_f32_e32 v220, v220, v84
	v_mul_f32_e32 v221, v221, v85
	v_mul_f32_e32 v222, v222, v86
	v_mul_f32_e32 v223, v223, v87
	v_cvt_pk_bf16_f32 v144, v208, v209
	v_cvt_pk_bf16_f32 v145, v210, v211
	v_cvt_pk_bf16_f32 v146, v212, v213
	v_cvt_pk_bf16_f32 v147, v214, v215
	v_cvt_pk_bf16_f32 v148, v216, v217
	v_cvt_pk_bf16_f32 v149, v218, v219
	v_cvt_pk_bf16_f32 v150, v220, v221
	v_cvt_pk_bf16_f32 v151, v222, v223
	global_store_dwordx4 v2, v[144:147], s[14:15]
	global_store_dwordx4 v2, v[148:151], s[14:15] offset:1024
	s_add_u32 s14, s14, 0x800
	s_addc_u32 s15, s15, 0
	v_readlane_b32 s4, v3, 0
	v_readlane_b32 s5, v3, 1
	v_readlane_b32 s6, v3, 2
	v_readlane_b32 s7, v3, 3
	v_readlane_b32 s8, v3, 4
	v_readlane_b32 s9, v3, 5
	v_readlane_b32 s10, v3, 6
	v_readlane_b32 s11, v3, 7
	v_readlane_b32 s12, v3, 8
	v_readlane_b32 s13, v3, 9
	v_readlane_b32 s14, v3, 10
	v_readlane_b32 s15, v3, 11
	v_readlane_b32 s16, v3, 12
	v_readlane_b32 s17, v3, 13
	v_readlane_b32 s18, v3, 14
	v_readlane_b32 s19, v3, 15
	v_readlane_b32 s20, v3, 16
	v_readlane_b32 s21, v3, 17
	v_readlane_b32 s22, v3, 18
	v_readlane_b32 s23, v3, 19
	v_readlane_b32 s24, v3, 20
	v_readlane_b32 s25, v3, 21
	s_mov_b32 s6, 0x358637bd
	s_mov_b64 s[34:35], 0
	s_branch .LBB0_74
.Lrow_r2:
	v_writelane_b32 v3, s4, 0
	v_writelane_b32 v3, s5, 1
	v_writelane_b32 v3, s6, 2
	v_writelane_b32 v3, s7, 3
	v_writelane_b32 v3, s8, 4
	v_writelane_b32 v3, s9, 5
	v_writelane_b32 v3, s10, 6
	v_writelane_b32 v3, s11, 7
	v_writelane_b32 v3, s12, 8
	v_writelane_b32 v3, s13, 9
	v_writelane_b32 v3, s14, 10
	v_writelane_b32 v3, s15, 11
	v_writelane_b32 v3, s16, 12
	v_writelane_b32 v3, s17, 13
	v_writelane_b32 v3, s18, 14
	v_writelane_b32 v3, s19, 15
	v_writelane_b32 v3, s20, 16
	v_writelane_b32 v3, s21, 17
	v_writelane_b32 v3, s22, 18
	v_writelane_b32 v3, s23, 19
	v_writelane_b32 v3, s24, 20
	v_writelane_b32 v3, s25, 21
	s_waitcnt vmcnt(0) lgkmcnt(0)
; DI int obid() { int b = blockIdx.x; asm volatile("" : "+s"(b)); return b; }
; DI int ogrid() { int g = gridDim.x; asm volatile("" : "+s"(g)); return g; }
; DI int otid_w(int gw) { return (gw << 6) | olane(); }
; DI float shx(float v, int mask) { const int l = olane(); return __builtin_bit_cast(float, __builtin_amdgcn_ds_bpermute(((l ^ mask) & 63) << 2, __builtin_bit_cast(int, v))); }
; DI void row_phase(const bf16_t* msrc, const float* xsrc, float* xdst, const float* g_post, const float* g_next, bf16_t* hdst, const int gw) {
;     ...
;     const int tid = otid_w(gw); const int lane = tid & 63, w = tid >> 6;
;     const int wg = obid() * 8 + w, nw = ogrid() * 8;
;     for (int rowb = wg * RB; rowb < M_TOK; rowb += nw * RB) {
;         f32x4 xv[RB][4], mv[RB][4];
; #pragma unroll
;         for (int r = 0; r < RB; ++r)
; #pragma unroll
;             for (int j = 0; j < 4; ++j) xv[r][j] = *(const f32x4*)(xsrc + (size_t)(rowb + r) * DM + lane * 4 + 256 * j);
;         if (msrc) {
; #pragma unroll
;             for (int r = 0; r < RB; ++r)
; #pragma unroll
;                 for (int j = 0; j < 4; ++j) { const u32x2 mw = *(const u32x2*)(msrc + (size_t)(rowb + r) * DM + lane * 4 + 256 * j);
;                     mv[r][j] = (f32x4){__uint_as_float(mw[0] << 16), __uint_as_float(mw[0] & 0xffff0000u), __uint_as_float(mw[1] << 16), __uint_as_float(mw[1] & 0xffff0000u)}; }
;             float ss[RB];
; #pragma unroll
;             for (int r = 0; r < RB; ++r) { ss[r] = 0.f;
; #pragma unroll
;                 for (int j = 0; j < 4; ++j) ss[r] += mv[r][j][0] * mv[r][j][0] + mv[r][j][1] * mv[r][j][1] + mv[r][j][2] * mv[r][j][2] + mv[r][j][3] * mv[r][j][3]; }
; #pragma unroll
;             for (int o = 32; o >= 1; o >>= 1)
; #pragma unroll
;                 for (int r = 0; r < RB; ++r) ss[r] += shx(ss[r], o);
; #pragma unroll
;             for (int j = 0; j < 4; ++j) { const f32x4 g = *(const f32x4*)(g_post + lane * 4 + 256 * j);
; #pragma unroll
;                 for (int r = 0; r < RB; ++r) { const float r1 = rsqrtf(ss[r] * (1.f / DM) + EPS); xv[r][j] = xv[r][j] + mv[r][j] * r1 * g; *(f32x4*)(xdst + (size_t)(rowb + r) * DM + lane * 4 + 256 * j) = xv[r][j]; } }
	v_mbcnt_lo_u32_b32 v0, -1, 0
	v_mbcnt_hi_u32_b32 v0, -1, v0
	v_lshlrev_b32_e32 v1, 5, v0
	v_lshlrev_b32_e32 v2, 4, v0
	s_lshr_b32 s4, s71, 6
	s_lshl_b32 s5, s2, 3
	s_add_i32 s5, s5, s4
	s_lshl_b32 s24, s5, 15
	s_lshl_b32 s25, s5, 14
	v_readlane_b32 s8, v254, 62
	v_readlane_b32 s9, v254, 63
	v_readlane_b32 s6, v255, 2
	v_readlane_b32 s7, v255, 3
	v_readlane_b32 s4, v255, 6
	v_readlane_b32 s16, v255, 10
	v_readlane_b32 s17, v255, 11
	s_nop 1
	s_cmp_eq_u32 s4, 0
	s_cselect_b32 s6, s6, s8
	s_cselect_b32 s7, s7, s9
	s_add_u32 s6, s6, s24
	s_addc_u32 s7, s7, 0
	s_add_u32 s8, s8, s24
	s_addc_u32 s9, s9, 0
	s_add_u32 s10, s68, 0x10681000
	s_addc_u32 s11, s69, 0
	s_add_u32 s10, s10, s25
	s_addc_u32 s11, s11, 0
	s_add_u32 s12, s10, 0x2000000
	s_addc_u32 s13, s11, 0
	s_add_u32 s14, s82, s25
	s_addc_u32 s15, s83, 0
	s_add_u32 s18, s16, 0x1000
	s_addc_u32 s19, s17, 0
	global_load_dwordx4 v[40:43], v1, s[18:19] offset:0
	global_load_dwordx4 v[44:47], v1, s[18:19] offset:16
	global_load_dwordx4 v[48:51], v1, s[18:19] offset:2048
	global_load_dwordx4 v[52:55], v1, s[18:19] offset:2064
	s_add_u32 s18, s16, 0x3000
	s_addc_u32 s19, s17, 0
	global_load_dwordx4 v[56:59], v1, s[18:19] offset:0
	global_load_dwordx4 v[60:63], v1, s[18:19] offset:16
	global_load_dwordx4 v[64:67], v1, s[18:19] offset:2048
	global_load_dwordx4 v[68:71], v1, s[18:19] offset:2064
	global_load_dwordx4 v[96:99], v1, s[6:7] offset:0
	global_load_dwordx4 v[100:103], v1, s[6:7] offset:16
	global_load_dwordx4 v[104:107], v1, s[6:7] offset:2048
	global_load_dwordx4 v[108:111], v1, s[6:7] offset:2064
	global_load_dwordx4 v[112:115], v2, s[10:11]
	global_load_dwordx4 v[116:119], v2, s[10:11] offset:1024
	global_load_dwordx4 v[120:123], v2, s[12:13]
	global_load_dwordx4 v[124:127], v2, s[12:13] offset:1024
	s_add_u32 s6, s6, 0x1000
	s_addc_u32 s7, s7, 0
	s_add_u32 s10, s10, 0x800
	s_addc_u32 s11, s11, 0
	s_add_u32 s12, s12, 0x800
	s_addc_u32 s13, s13, 0
	global_load_dwordx4 v[128:131], v1, s[6:7] offset:0
	global_load_dwordx4 v[132:135], v1, s[6:7] offset:16
	global_load_dwordx4 v[136:139], v1, s[6:7] offset:2048
	global_load_dwordx4 v[140:143], v1, s[6:7] offset:2064
	global_load_dwordx4 v[144:147], v2, s[10:11]
	global_load_dwordx4 v[148:151], v2, s[10:11] offset:1024
	global_load_dwordx4 v[152:155], v2, s[12:13]
	global_load_dwordx4 v[156:159], v2, s[12:13] offset:1024
	s_add_u32 s6, s6, 0x1000
	s_addc_u32 s7, s7, 0
	s_add_u32 s10, s10, 0x800
	s_addc_u32 s11, s11, 0
	s_add_u32 s12, s12, 0x800
	s_addc_u32 s13, s13, 0
	global_load_dwordx4 v[160:163], v1, s[6:7] offset:0
	global_load_dwordx4 v[164:167], v1, s[6:7] offset:16
	global_load_dwordx4 v[168:171], v1, s[6:7] offset:2048
	global_load_dwordx4 v[172:175], v1, s[6:7] offset:2064
	global_load_dwordx4 v[176:179], v2, s[10:11]
	global_load_dwordx4 v[180:183], v2, s[10:11] offset:1024
	global_load_dwordx4 v[184:187], v2, s[12:13]
	global_load_dwordx4 v[188:191], v2, s[12:13] offset:1024
	s_add_u32 s6, s6, 0x1000
	s_addc_u32 s7, s7, 0
	s_add_u32 s10, s10, 0x800
	s_addc_u32 s11, s11, 0
	s_add_u32 s12, s12, 0x800
	s_addc_u32 s13, s13, 0
	s_waitcnt vmcnt(16)
	v_lshlrev_b32_e32 v208, 16, v112
	v_and_b32_e32 v209, 0xffff0000, v112
	v_lshlrev_b32_e32 v210, 16, v113
	v_and_b32_e32 v211, 0xffff0000, v113
	v_lshlrev_b32_e32 v212, 16, v114
	v_and_b32_e32 v213, 0xffff0000, v114
	v_lshlrev_b32_e32 v214, 16, v115
	v_and_b32_e32 v215, 0xffff0000, v115
	v_lshlrev_b32_e32 v216, 16, v116
	v_and_b32_e32 v217, 0xffff0000, v116
	v_lshlrev_b32_e32 v218, 16, v117
	v_and_b32_e32 v219, 0xffff0000, v117
	v_lshlrev_b32_e32 v220, 16, v118
	v_and_b32_e32 v221, 0xffff0000, v118
	v_lshlrev_b32_e32 v222, 16, v119
	v_and_b32_e32 v223, 0xffff0000, v119
	v_mul_f32_e32 v224, v208, v208
	v_fmac_f32_e32 v224, v209, v209
	v_fmac_f32_e32 v224, v210, v210
	v_fmac_f32_e32 v224, v211, v211
	v_fmac_f32_e32 v224, v212, v212
	v_fmac_f32_e32 v224, v213, v213
	v_fmac_f32_e32 v224, v214, v214
	v_fmac_f32_e32 v224, v215, v215
	v_fmac_f32_e32 v224, v216, v216
	v_fmac_f32_e32 v224, v217, v217
	v_fmac_f32_e32 v224, v218, v218
	v_fmac_f32_e32 v224, v219, v219
	v_fmac_f32_e32 v224, v220, v220
	v_fmac_f32_e32 v224, v221, v221
	v_fmac_f32_e32 v224, v222, v222
	v_fmac_f32_e32 v224, v223, v223
	s_nop 1
	v_add_f32_dpp v224, v224, v224 quad_perm:[1,0,3,2] row_mask:0xf bank_mask:0xf
	s_nop 1
	v_add_f32_dpp v224, v224, v224 quad_perm:[2,3,0,1] row_mask:0xf bank_mask:0xf
	s_nop 1
	v_add_f32_dpp v224, v224, v224 row_ror:4 row_mask:0xf bank_mask:0xf
	s_nop 1
	v_add_f32_dpp v224, v224, v224 row_ror:8 row_mask:0xf bank_mask:0xf
	s_nop 1
	v_readlane_b32 s20, v224, 0
	v_readlane_b32 s21, v224, 16
	v_readlane_b32 s22, v224, 32
	v_readlane_b32 s23, v224, 48
	s_nop 1
	v_mov_b32_e32 v225, s20
	v_add_f32_e32 v225, s21, v225
	v_add_f32_e32 v225, s22, v225
	v_add_f32_e32 v225, s23, v225
	v_mov_b32_e32 v226, 0x358637bd
	v_fmac_f32_e32 v226, 0x3a800000, v225
	v_rsq_f32_e32 v226, v226
	s_nop 0
	v_mul_f32_e32 v208, v208, v226
	v_mul_f32_e32 v209, v209, v226
	v_mul_f32_e32 v210, v210, v226
	v_mul_f32_e32 v211, v211, v226
	v_mul_f32_e32 v212, v212, v226
	v_mul_f32_e32 v213, v213, v226
	v_mul_f32_e32 v214, v214, v226
	v_mul_f32_e32 v215, v215, v226
	v_mul_f32_e32 v216, v216, v226
	v_mul_f32_e32 v217, v217, v226
	v_mul_f32_e32 v218, v218, v226
	v_mul_f32_e32 v219, v219, v226
	v_mul_f32_e32 v220, v220, v226
	v_mul_f32_e32 v221, v221, v226
	v_mul_f32_e32 v222, v222, v226
	v_mul_f32_e32 v223, v223, v226
	v_fmac_f32_e32 v96, v208, v40
	v_fmac_f32_e32 v97, v209, v41
	v_fmac_f32_e32 v98, v210, v42
	v_fmac_f32_e32 v99, v211, v43
	v_fmac_f32_e32 v100, v212, v44
	v_fmac_f32_e32 v101, v213, v45
	v_fmac_f32_e32 v102, v214, v46
; DI float shx(float v, int mask) { const int l = olane(); return __builtin_bit_cast(float, __builtin_amdgcn_ds_bpermute(((l ^ mask) & 63) << 2, __builtin_bit_cast(int, v))); }
; DI void row_phase(const bf16_t* msrc, const float* xsrc, float* xdst, const float* g_post, const float* g_next, bf16_t* hdst, const int gw) {
;     ...
;             for (int j = 0; j < 4; ++j) xv[r][j] = *(const f32x4*)(xsrc + (size_t)(rowb + r) * DM + lane * 4 + 256 * j);
;         if (msrc) {
; #pragma unroll
;             for (int r = 0; r < RB; ++r)
; #pragma unroll
;                 for (int j = 0; j < 4; ++j) { const u32x2 mw = *(const u32x2*)(msrc + (size_t)(rowb + r) * DM + lane * 4 + 256 * j);
;                     mv[r][j] = (f32x4){__uint_as_float(mw[0] << 16), __uint_as_float(mw[0] & 0xffff0000u), __uint_as_float(mw[1] << 16), __uint_as_float(mw[1] & 0xffff0000u)}; }
;             float ss[RB];
; #pragma unroll
;             for (int r = 0; r < RB; ++r) { ss[r] = 0.f;
; #pragma unroll
;                 for (int j = 0; j < 4; ++j) ss[r] += mv[r][j][0] * mv[r][j][0] + mv[r][j][1] * mv[r][j][1] + mv[r][j][2] * mv[r][j][2] + mv[r][j][3] * mv[r][j][3]; }
; #pragma unroll
;             for (int o = 32; o >= 1; o >>= 1)
; #pragma unroll
;                 for (int r = 0; r < RB; ++r) ss[r] += shx(ss[r], o);
; #pragma unroll
;             for (int j = 0; j < 4; ++j) { const f32x4 g = *(const f32x4*)(g_post + lane * 4 + 256 * j);
; #pragma unroll
;                 for (int r = 0; r < RB; ++r) { const float r1 = rsqrtf(ss[r] * (1.f / DM) + EPS); xv[r][j] = xv[r][j] + mv[r][j] * r1 * g; *(f32x4*)(xdst + (size_t)(rowb + r) * DM + lane * 4 + 256 * j) = xv[r][j]; } }
	v_fmac_f32_e32 v103, v215, v47
	v_fmac_f32_e32 v104, v216, v48
	v_fmac_f32_e32 v105, v217, v49
	v_fmac_f32_e32 v106, v218, v50
	v_fmac_f32_e32 v107, v219, v51
	v_fmac_f32_e32 v108, v220, v52
	v_fmac_f32_e32 v109, v221, v53
	v_fmac_f32_e32 v110, v222, v54
	v_fmac_f32_e32 v111, v223, v55
	v_lshlrev_b32_e32 v208, 16, v120
	v_and_b32_e32 v209, 0xffff0000, v120
	v_lshlrev_b32_e32 v210, 16, v121
	v_and_b32_e32 v211, 0xffff0000, v121
	v_lshlrev_b32_e32 v212, 16, v122
	v_and_b32_e32 v213, 0xffff0000, v122
	v_lshlrev_b32_e32 v214, 16, v123
	v_and_b32_e32 v215, 0xffff0000, v123
	v_lshlrev_b32_e32 v216, 16, v124
	v_and_b32_e32 v217, 0xffff0000, v124
	v_lshlrev_b32_e32 v218, 16, v125
	v_and_b32_e32 v219, 0xffff0000, v125
	v_lshlrev_b32_e32 v220, 16, v126
	v_and_b32_e32 v221, 0xffff0000, v126
	v_lshlrev_b32_e32 v222, 16, v127
	v_and_b32_e32 v223, 0xffff0000, v127
	v_mul_f32_e32 v224, v208, v208
	v_fmac_f32_e32 v224, v209, v209
	v_fmac_f32_e32 v224, v210, v210
	v_fmac_f32_e32 v224, v211, v211
	v_fmac_f32_e32 v224, v212, v212
	v_fmac_f32_e32 v224, v213, v213
	v_fmac_f32_e32 v224, v214, v214
	v_fmac_f32_e32 v224, v215, v215
	v_fmac_f32_e32 v224, v216, v216
	v_fmac_f32_e32 v224, v217, v217
	v_fmac_f32_e32 v224, v218, v218
	v_fmac_f32_e32 v224, v219, v219
	v_fmac_f32_e32 v224, v220, v220
	v_fmac_f32_e32 v224, v221, v221
	v_fmac_f32_e32 v224, v222, v222
	v_fmac_f32_e32 v224, v223, v223
	s_nop 1
	v_add_f32_dpp v224, v224, v224 quad_perm:[1,0,3,2] row_mask:0xf bank_mask:0xf
	s_nop 1
	v_add_f32_dpp v224, v224, v224 quad_perm:[2,3,0,1] row_mask:0xf bank_mask:0xf
	s_nop 1
	v_add_f32_dpp v224, v224, v224 row_ror:4 row_mask:0xf bank_mask:0xf
	s_nop 1
	v_add_f32_dpp v224, v224, v224 row_ror:8 row_mask:0xf bank_mask:0xf
	s_nop 1
	v_readlane_b32 s20, v224, 0
	v_readlane_b32 s21, v224, 16
	v_readlane_b32 s22, v224, 32
	v_readlane_b32 s23, v224, 48
	s_nop 1
	v_mov_b32_e32 v225, s20
	v_add_f32_e32 v225, s21, v225
	v_add_f32_e32 v225, s22, v225
	v_add_f32_e32 v225, s23, v225
	v_mov_b32_e32 v226, 0x358637bd
	v_fmac_f32_e32 v226, 0x3a800000, v225
	v_rsq_f32_e32 v226, v226
	s_nop 0
	v_mul_f32_e32 v208, v208, v226
	v_mul_f32_e32 v209, v209, v226
	v_mul_f32_e32 v210, v210, v226
	v_mul_f32_e32 v211, v211, v226
	v_mul_f32_e32 v212, v212, v226
	v_mul_f32_e32 v213, v213, v226
	v_mul_f32_e32 v214, v214, v226
	v_mul_f32_e32 v215, v215, v226
	v_mul_f32_e32 v216, v216, v226
	v_mul_f32_e32 v217, v217, v226
	v_mul_f32_e32 v218, v218, v226
	v_mul_f32_e32 v219, v219, v226
	v_mul_f32_e32 v220, v220, v226
	v_mul_f32_e32 v221, v221, v226
	v_mul_f32_e32 v222, v222, v226
	v_mul_f32_e32 v223, v223, v226
	v_fmac_f32_e32 v96, v208, v56
	v_fmac_f32_e32 v97, v209, v57
	v_fmac_f32_e32 v98, v210, v58
	v_fmac_f32_e32 v99, v211, v59
	v_fmac_f32_e32 v100, v212, v60
	v_fmac_f32_e32 v101, v213, v61
	v_fmac_f32_e32 v102, v214, v62
	v_fmac_f32_e32 v103, v215, v63
	v_fmac_f32_e32 v104, v216, v64
	v_fmac_f32_e32 v105, v217, v65
	v_fmac_f32_e32 v106, v218, v66
	v_fmac_f32_e32 v107, v219, v67
	v_fmac_f32_e32 v108, v220, v68
	v_fmac_f32_e32 v109, v221, v69
	v_fmac_f32_e32 v110, v222, v70
	v_fmac_f32_e32 v111, v223, v71
	global_store_dwordx4 v1, v[96:99], s[8:9] offset:0
	global_store_dwordx4 v1, v[100:103], s[8:9] offset:16
	global_store_dwordx4 v1, v[104:107], s[8:9] offset:2048
	global_store_dwordx4 v1, v[108:111], s[8:9] offset:2064
	s_add_u32 s8, s8, 0x1000
	s_addc_u32 s9, s9, 0
	global_load_dwordx4 v[96:99], v1, s[6:7] offset:0
	global_load_dwordx4 v[100:103], v1, s[6:7] offset:16
	global_load_dwordx4 v[104:107], v1, s[6:7] offset:2048
	global_load_dwordx4 v[108:111], v1, s[6:7] offset:2064
	global_load_dwordx4 v[112:115], v2, s[10:11]
	global_load_dwordx4 v[116:119], v2, s[10:11] offset:1024
	global_load_dwordx4 v[120:123], v2, s[12:13]
	global_load_dwordx4 v[124:127], v2, s[12:13] offset:1024
	s_add_u32 s6, s6, 0x1000
	s_addc_u32 s7, s7, 0
	s_add_u32 s10, s10, 0x800
	s_addc_u32 s11, s11, 0
	s_add_u32 s12, s12, 0x800
	s_addc_u32 s13, s13, 0
	s_waitcnt vmcnt(20)
	v_lshlrev_b32_e32 v208, 16, v144
	v_and_b32_e32 v209, 0xffff0000, v144
	v_lshlrev_b32_e32 v210, 16, v145
	v_and_b32_e32 v211, 0xffff0000, v145
	v_lshlrev_b32_e32 v212, 16, v146
	v_and_b32_e32 v213, 0xffff0000, v146
	v_lshlrev_b32_e32 v214, 16, v147
	v_and_b32_e32 v215, 0xffff0000, v147
	v_lshlrev_b32_e32 v216, 16, v148
	v_and_b32_e32 v217, 0xffff0000, v148
	v_lshlrev_b32_e32 v218, 16, v149
	v_and_b32_e32 v219, 0xffff0000, v149
	v_lshlrev_b32_e32 v220, 16, v150
	v_and_b32_e32 v221, 0xffff0000, v150
	v_lshlrev_b32_e32 v222, 16, v151
	v_and_b32_e32 v223, 0xffff0000, v151
	v_mul_f32_e32 v224, v208, v208
	v_fmac_f32_e32 v224, v209, v209
	v_fmac_f32_e32 v224, v210, v210
	v_fmac_f32_e32 v224, v211, v211
	v_fmac_f32_e32 v224, v212, v212
	v_fmac_f32_e32 v224, v213, v213
	v_fmac_f32_e32 v224, v214, v214
	v_fmac_f32_e32 v224, v215, v215
	v_fmac_f32_e32 v224, v216, v216
	v_fmac_f32_e32 v224, v217, v217
	v_fmac_f32_e32 v224, v218, v218
	v_fmac_f32_e32 v224, v219, v219
	v_fmac_f32_e32 v224, v220, v220
	v_fmac_f32_e32 v224, v221, v221
	v_fmac_f32_e32 v224, v222, v222
	v_fmac_f32_e32 v224, v223, v223
	s_nop 1
	v_add_f32_dpp v224, v224, v224 quad_perm:[1,0,3,2] row_mask:0xf bank_mask:0xf
	s_nop 1
	v_add_f32_dpp v224, v224, v224 quad_perm:[2,3,0,1] row_mask:0xf bank_mask:0xf
	s_nop 1
	v_add_f32_dpp v224, v224, v224 row_ror:4 row_mask:0xf bank_mask:0xf
	s_nop 1
	v_add_f32_dpp v224, v224, v224 row_ror:8 row_mask:0xf bank_mask:0xf
	s_nop 1
	v_readlane_b32 s20, v224, 0
	v_readlane_b32 s21, v224, 16
	v_readlane_b32 s22, v224, 32
	v_readlane_b32 s23, v224, 48
	s_nop 1
	v_mov_b32_e32 v225, s20
	v_add_f32_e32 v225, s21, v225
	v_add_f32_e32 v225, s22, v225
; DI float shx(float v, int mask) { const int l = olane(); return __builtin_bit_cast(float, __builtin_amdgcn_ds_bpermute(((l ^ mask) & 63) << 2, __builtin_bit_cast(int, v))); }
; DI void row_phase(const bf16_t* msrc, const float* xsrc, float* xdst, const float* g_post, const float* g_next, bf16_t* hdst, const int gw) {
;     ...
;             for (int j = 0; j < 4; ++j) xv[r][j] = *(const f32x4*)(xsrc + (size_t)(rowb + r) * DM + lane * 4 + 256 * j);
;         if (msrc) {
; #pragma unroll
;             for (int r = 0; r < RB; ++r)
; #pragma unroll
;                 for (int j = 0; j < 4; ++j) { const u32x2 mw = *(const u32x2*)(msrc + (size_t)(rowb + r) * DM + lane * 4 + 256 * j);
;                     mv[r][j] = (f32x4){__uint_as_float(mw[0] << 16), __uint_as_float(mw[0] & 0xffff0000u), __uint_as_float(mw[1] << 16), __uint_as_float(mw[1] & 0xffff0000u)}; }
;             float ss[RB];
; #pragma unroll
;             for (int r = 0; r < RB; ++r) { ss[r] = 0.f;
; #pragma unroll
;                 for (int j = 0; j < 4; ++j) ss[r] += mv[r][j][0] * mv[r][j][0] + mv[r][j][1] * mv[r][j][1] + mv[r][j][2] * mv[r][j][2] + mv[r][j][3] * mv[r][j][3]; }
; #pragma unroll
;             for (int o = 32; o >= 1; o >>= 1)
; #pragma unroll
;                 for (int r = 0; r < RB; ++r) ss[r] += shx(ss[r], o);
; #pragma unroll
;             for (int j = 0; j < 4; ++j) { const f32x4 g = *(const f32x4*)(g_post + lane * 4 + 256 * j);
; #pragma unroll
;                 for (int r = 0; r < RB; ++r) { const float r1 = rsqrtf(ss[r] * (1.f / DM) + EPS); xv[r][j] = xv[r][j] + mv[r][j] * r1 * g; *(f32x4*)(xdst + (size_t)(rowb + r) * DM + lane * 4 + 256 * j) = xv[r][j]; } }
	v_add_f32_e32 v225, s23, v225
	v_mov_b32_e32 v226, 0x358637bd
	v_fmac_f32_e32 v226, 0x3a800000, v225
	v_rsq_f32_e32 v226, v226
	s_nop 0
	v_mul_f32_e32 v208, v208, v226
	v_mul_f32_e32 v209, v209, v226
	v_mul_f32_e32 v210, v210, v226
	v_mul_f32_e32 v211, v211, v226
	v_mul_f32_e32 v212, v212, v226
	v_mul_f32_e32 v213, v213, v226
	v_mul_f32_e32 v214, v214, v226
	v_mul_f32_e32 v215, v215, v226
	v_mul_f32_e32 v216, v216, v226
	v_mul_f32_e32 v217, v217, v226
	v_mul_f32_e32 v218, v218, v226
	v_mul_f32_e32 v219, v219, v226
	v_mul_f32_e32 v220, v220, v226
	v_mul_f32_e32 v221, v221, v226
	v_mul_f32_e32 v222, v222, v226
	v_mul_f32_e32 v223, v223, v226
	v_fmac_f32_e32 v128, v208, v40
	v_fmac_f32_e32 v129, v209, v41
	v_fmac_f32_e32 v130, v210, v42
	v_fmac_f32_e32 v131, v211, v43
	v_fmac_f32_e32 v132, v212, v44
	v_fmac_f32_e32 v133, v213, v45
	v_fmac_f32_e32 v134, v214, v46
	v_fmac_f32_e32 v135, v215, v47
	v_fmac_f32_e32 v136, v216, v48
	v_fmac_f32_e32 v137, v217, v49
	v_fmac_f32_e32 v138, v218, v50
	v_fmac_f32_e32 v139, v219, v51
	v_fmac_f32_e32 v140, v220, v52
	v_fmac_f32_e32 v141, v221, v53
	v_fmac_f32_e32 v142, v222, v54
	v_fmac_f32_e32 v143, v223, v55
	v_lshlrev_b32_e32 v208, 16, v152
	v_and_b32_e32 v209, 0xffff0000, v152
	v_lshlrev_b32_e32 v210, 16, v153
	v_and_b32_e32 v211, 0xffff0000, v153
	v_lshlrev_b32_e32 v212, 16, v154
	v_and_b32_e32 v213, 0xffff0000, v154
	v_lshlrev_b32_e32 v214, 16, v155
	v_and_b32_e32 v215, 0xffff0000, v155
	v_lshlrev_b32_e32 v216, 16, v156
	v_and_b32_e32 v217, 0xffff0000, v156
	v_lshlrev_b32_e32 v218, 16, v157
	v_and_b32_e32 v219, 0xffff0000, v157
	v_lshlrev_b32_e32 v220, 16, v158
	v_and_b32_e32 v221, 0xffff0000, v158
	v_lshlrev_b32_e32 v222, 16, v159
	v_and_b32_e32 v223, 0xffff0000, v159
	v_mul_f32_e32 v224, v208, v208
	v_fmac_f32_e32 v224, v209, v209
	v_fmac_f32_e32 v224, v210, v210
	v_fmac_f32_e32 v224, v211, v211
	v_fmac_f32_e32 v224, v212, v212
	v_fmac_f32_e32 v224, v213, v213
	v_fmac_f32_e32 v224, v214, v214
	v_fmac_f32_e32 v224, v215, v215
	v_fmac_f32_e32 v224, v216, v216
	v_fmac_f32_e32 v224, v217, v217
	v_fmac_f32_e32 v224, v218, v218
	v_fmac_f32_e32 v224, v219, v219
	v_fmac_f32_e32 v224, v220, v220
	v_fmac_f32_e32 v224, v221, v221
	v_fmac_f32_e32 v224, v222, v222
	v_fmac_f32_e32 v224, v223, v223
	s_nop 1
	v_add_f32_dpp v224, v224, v224 quad_perm:[1,0,3,2] row_mask:0xf bank_mask:0xf
	s_nop 1
	v_add_f32_dpp v224, v224, v224 quad_perm:[2,3,0,1] row_mask:0xf bank_mask:0xf
	s_nop 1
	v_add_f32_dpp v224, v224, v224 row_ror:4 row_mask:0xf bank_mask:0xf
	s_nop 1
	v_add_f32_dpp v224, v224, v224 row_ror:8 row_mask:0xf bank_mask:0xf
	s_nop 1
	v_readlane_b32 s20, v224, 0
	v_readlane_b32 s21, v224, 16
	v_readlane_b32 s22, v224, 32
	v_readlane_b32 s23, v224, 48
	s_nop 1
	v_mov_b32_e32 v225, s20
	v_add_f32_e32 v225, s21, v225
	v_add_f32_e32 v225, s22, v225
	v_add_f32_e32 v225, s23, v225
	v_mov_b32_e32 v226, 0x358637bd
	v_fmac_f32_e32 v226, 0x3a800000, v225
	v_rsq_f32_e32 v226, v226
	s_nop 0
	v_mul_f32_e32 v208, v208, v226
	v_mul_f32_e32 v209, v209, v226
	v_mul_f32_e32 v210, v210, v226
	v_mul_f32_e32 v211, v211, v226
	v_mul_f32_e32 v212, v212, v226
	v_mul_f32_e32 v213, v213, v226
	v_mul_f32_e32 v214, v214, v226
	v_mul_f32_e32 v215, v215, v226
	v_mul_f32_e32 v216, v216, v226
	v_mul_f32_e32 v217, v217, v226
	v_mul_f32_e32 v218, v218, v226
	v_mul_f32_e32 v219, v219, v226
	v_mul_f32_e32 v220, v220, v226
	v_mul_f32_e32 v221, v221, v226
	v_mul_f32_e32 v222, v222, v226
	v_mul_f32_e32 v223, v223, v226
	v_fmac_f32_e32 v128, v208, v56
	v_fmac_f32_e32 v129, v209, v57
	v_fmac_f32_e32 v130, v210, v58
	v_fmac_f32_e32 v131, v211, v59
	v_fmac_f32_e32 v132, v212, v60
	v_fmac_f32_e32 v133, v213, v61
	v_fmac_f32_e32 v134, v214, v62
	v_fmac_f32_e32 v135, v215, v63
	v_fmac_f32_e32 v136, v216, v64
	v_fmac_f32_e32 v137, v217, v65
	v_fmac_f32_e32 v138, v218, v66
	v_fmac_f32_e32 v139, v219, v67
	v_fmac_f32_e32 v140, v220, v68
	v_fmac_f32_e32 v141, v221, v69
	v_fmac_f32_e32 v142, v222, v70
	v_fmac_f32_e32 v143, v223, v71
	global_store_dwordx4 v1, v[128:131], s[8:9] offset:0
	global_store_dwordx4 v1, v[132:135], s[8:9] offset:16
	global_store_dwordx4 v1, v[136:139], s[8:9] offset:2048
	global_store_dwordx4 v1, v[140:143], s[8:9] offset:2064
	s_add_u32 s8, s8, 0x1000
	s_addc_u32 s9, s9, 0
	global_load_dwordx4 v[128:131], v1, s[6:7] offset:0
	global_load_dwordx4 v[132:135], v1, s[6:7] offset:16
	global_load_dwordx4 v[136:139], v1, s[6:7] offset:2048
	global_load_dwordx4 v[140:143], v1, s[6:7] offset:2064
	global_load_dwordx4 v[144:147], v2, s[10:11]
	global_load_dwordx4 v[148:151], v2, s[10:11] offset:1024
	global_load_dwordx4 v[152:155], v2, s[12:13]
	global_load_dwordx4 v[156:159], v2, s[12:13] offset:1024
	s_add_u32 s6, s6, 0x1000
	s_addc_u32 s7, s7, 0
	s_add_u32 s10, s10, 0x800
	s_addc_u32 s11, s11, 0
	s_add_u32 s12, s12, 0x800
	s_addc_u32 s13, s13, 0
	s_waitcnt vmcnt(24)
; DI float shx(float v, int mask) { const int l = olane(); return __builtin_bit_cast(float, __builtin_amdgcn_ds_bpermute(((l ^ mask) & 63) << 2, __builtin_bit_cast(int, v))); }
; DI void row_phase(const bf16_t* msrc, const float* xsrc, float* xdst, const float* g_post, const float* g_next, bf16_t* hdst, const int gw) {
;     ...
;             for (int j = 0; j < 4; ++j) xv[r][j] = *(const f32x4*)(xsrc + (size_t)(rowb + r) * DM + lane * 4 + 256 * j);
;         if (msrc) {
; #pragma unroll
;             for (int r = 0; r < RB; ++r)
; #pragma unroll
;                 for (int j = 0; j < 4; ++j) { const u32x2 mw = *(const u32x2*)(msrc + (size_t)(rowb + r) * DM + lane * 4 + 256 * j);
;                     mv[r][j] = (f32x4){__uint_as_float(mw[0] << 16), __uint_as_float(mw[0] & 0xffff0000u), __uint_as_float(mw[1] << 16), __uint_as_float(mw[1] & 0xffff0000u)}; }
;             float ss[RB];
; #pragma unroll
;             for (int r = 0; r < RB; ++r) { ss[r] = 0.f;
; #pragma unroll
;                 for (int j = 0; j < 4; ++j) ss[r] += mv[r][j][0] * mv[r][j][0] + mv[r][j][1] * mv[r][j][1] + mv[r][j][2] * mv[r][j][2] + mv[r][j][3] * mv[r][j][3]; }
; #pragma unroll
;             for (int o = 32; o >= 1; o >>= 1)
; #pragma unroll
;                 for (int r = 0; r < RB; ++r) ss[r] += shx(ss[r], o);
; #pragma unroll
;             for (int j = 0; j < 4; ++j) { const f32x4 g = *(const f32x4*)(g_post + lane * 4 + 256 * j);
; #pragma unroll
;                 for (int r = 0; r < RB; ++r) { const float r1 = rsqrtf(ss[r] * (1.f / DM) + EPS); xv[r][j] = xv[r][j] + mv[r][j] * r1 * g; *(f32x4*)(xdst + (size_t)(rowb + r) * DM + lane * 4 + 256 * j) = xv[r][j]; } }
	v_lshlrev_b32_e32 v208, 16, v176
	v_and_b32_e32 v209, 0xffff0000, v176
	v_lshlrev_b32_e32 v210, 16, v177
	v_and_b32_e32 v211, 0xffff0000, v177
	v_lshlrev_b32_e32 v212, 16, v178
	v_and_b32_e32 v213, 0xffff0000, v178
	v_lshlrev_b32_e32 v214, 16, v179
	v_and_b32_e32 v215, 0xffff0000, v179
	v_lshlrev_b32_e32 v216, 16, v180
	v_and_b32_e32 v217, 0xffff0000, v180
	v_lshlrev_b32_e32 v218, 16, v181
	v_and_b32_e32 v219, 0xffff0000, v181
	v_lshlrev_b32_e32 v220, 16, v182
	v_and_b32_e32 v221, 0xffff0000, v182
	v_lshlrev_b32_e32 v222, 16, v183
	v_and_b32_e32 v223, 0xffff0000, v183
	v_mul_f32_e32 v224, v208, v208
	v_fmac_f32_e32 v224, v209, v209
	v_fmac_f32_e32 v224, v210, v210
	v_fmac_f32_e32 v224, v211, v211
	v_fmac_f32_e32 v224, v212, v212
	v_fmac_f32_e32 v224, v213, v213
	v_fmac_f32_e32 v224, v214, v214
	v_fmac_f32_e32 v224, v215, v215
	v_fmac_f32_e32 v224, v216, v216
	v_fmac_f32_e32 v224, v217, v217
	v_fmac_f32_e32 v224, v218, v218
	v_fmac_f32_e32 v224, v219, v219
	v_fmac_f32_e32 v224, v220, v220
	v_fmac_f32_e32 v224, v221, v221
	v_fmac_f32_e32 v224, v222, v222
	v_fmac_f32_e32 v224, v223, v223
	s_nop 1
	v_add_f32_dpp v224, v224, v224 quad_perm:[1,0,3,2] row_mask:0xf bank_mask:0xf
	s_nop 1
	v_add_f32_dpp v224, v224, v224 quad_perm:[2,3,0,1] row_mask:0xf bank_mask:0xf
	s_nop 1
	v_add_f32_dpp v224, v224, v224 row_ror:4 row_mask:0xf bank_mask:0xf
	s_nop 1
	v_add_f32_dpp v224, v224, v224 row_ror:8 row_mask:0xf bank_mask:0xf
	s_nop 1
	v_readlane_b32 s20, v224, 0
	v_readlane_b32 s21, v224, 16
	v_readlane_b32 s22, v224, 32
	v_readlane_b32 s23, v224, 48
	s_nop 1
	v_mov_b32_e32 v225, s20
	v_add_f32_e32 v225, s21, v225
	v_add_f32_e32 v225, s22, v225
	v_add_f32_e32 v225, s23, v225
	v_mov_b32_e32 v226, 0x358637bd
	v_fmac_f32_e32 v226, 0x3a800000, v225
	v_rsq_f32_e32 v226, v226
	s_nop 0
	v_mul_f32_e32 v208, v208, v226
	v_mul_f32_e32 v209, v209, v226
	v_mul_f32_e32 v210, v210, v226
	v_mul_f32_e32 v211, v211, v226
	v_mul_f32_e32 v212, v212, v226
	v_mul_f32_e32 v213, v213, v226
	v_mul_f32_e32 v214, v214, v226
	v_mul_f32_e32 v215, v215, v226
	v_mul_f32_e32 v216, v216, v226
	v_mul_f32_e32 v217, v217, v226
	v_mul_f32_e32 v218, v218, v226
	v_mul_f32_e32 v219, v219, v226
	v_mul_f32_e32 v220, v220, v226
	v_mul_f32_e32 v221, v221, v226
	v_mul_f32_e32 v222, v222, v226
	v_mul_f32_e32 v223, v223, v226
	v_fmac_f32_e32 v160, v208, v40
	v_fmac_f32_e32 v161, v209, v41
	v_fmac_f32_e32 v162, v210, v42
	v_fmac_f32_e32 v163, v211, v43
	v_fmac_f32_e32 v164, v212, v44
	v_fmac_f32_e32 v165, v213, v45
	v_fmac_f32_e32 v166, v214, v46
	v_fmac_f32_e32 v167, v215, v47
	v_fmac_f32_e32 v168, v216, v48
	v_fmac_f32_e32 v169, v217, v49
	v_fmac_f32_e32 v170, v218, v50
	v_fmac_f32_e32 v171, v219, v51
	v_fmac_f32_e32 v172, v220, v52
	v_fmac_f32_e32 v173, v221, v53
	v_fmac_f32_e32 v174, v222, v54
	v_fmac_f32_e32 v175, v223, v55
	v_lshlrev_b32_e32 v208, 16, v184
	v_and_b32_e32 v209, 0xffff0000, v184
	v_lshlrev_b32_e32 v210, 16, v185
	v_and_b32_e32 v211, 0xffff0000, v185
	v_lshlrev_b32_e32 v212, 16, v186
	v_and_b32_e32 v213, 0xffff0000, v186
	v_lshlrev_b32_e32 v214, 16, v187
	v_and_b32_e32 v215, 0xffff0000, v187
	v_lshlrev_b32_e32 v216, 16, v188
	v_and_b32_e32 v217, 0xffff0000, v188
	v_lshlrev_b32_e32 v218, 16, v189
	v_and_b32_e32 v219, 0xffff0000, v189
	v_lshlrev_b32_e32 v220, 16, v190
	v_and_b32_e32 v221, 0xffff0000, v190
	v_lshlrev_b32_e32 v222, 16, v191
	v_and_b32_e32 v223, 0xffff0000, v191
	v_mul_f32_e32 v224, v208, v208
	v_fmac_f32_e32 v224, v209, v209
	v_fmac_f32_e32 v224, v210, v210
	v_fmac_f32_e32 v224, v211, v211
	v_fmac_f32_e32 v224, v212, v212
	v_fmac_f32_e32 v224, v213, v213
	v_fmac_f32_e32 v224, v214, v214
	v_fmac_f32_e32 v224, v215, v215
	v_fmac_f32_e32 v224, v216, v216
	v_fmac_f32_e32 v224, v217, v217
	v_fmac_f32_e32 v224, v218, v218
	v_fmac_f32_e32 v224, v219, v219
	v_fmac_f32_e32 v224, v220, v220
	v_fmac_f32_e32 v224, v221, v221
	v_fmac_f32_e32 v224, v222, v222
	v_fmac_f32_e32 v224, v223, v223
	s_nop 1
	v_add_f32_dpp v224, v224, v224 quad_perm:[1,0,3,2] row_mask:0xf bank_mask:0xf
	s_nop 1
	v_add_f32_dpp v224, v224, v224 quad_perm:[2,3,0,1] row_mask:0xf bank_mask:0xf
	s_nop 1
	v_add_f32_dpp v224, v224, v224 row_ror:4 row_mask:0xf bank_mask:0xf
	s_nop 1
	v_add_f32_dpp v224, v224, v224 row_ror:8 row_mask:0xf bank_mask:0xf
	s_nop 1
	v_readlane_b32 s20, v224, 0
	v_readlane_b32 s21, v224, 16
	v_readlane_b32 s22, v224, 32
	v_readlane_b32 s23, v224, 48
	s_nop 1
	v_mov_b32_e32 v225, s20
	v_add_f32_e32 v225, s21, v225
	v_add_f32_e32 v225, s22, v225
	v_add_f32_e32 v225, s23, v225
	v_mov_b32_e32 v226, 0x358637bd
	v_fmac_f32_e32 v226, 0x3a800000, v225
	v_rsq_f32_e32 v226, v226
	s_nop 0
	v_mul_f32_e32 v208, v208, v226
	v_mul_f32_e32 v209, v209, v226
	v_mul_f32_e32 v210, v210, v226
	v_mul_f32_e32 v211, v211, v226
	v_mul_f32_e32 v212, v212, v226
	v_mul_f32_e32 v213, v213, v226
	v_mul_f32_e32 v214, v214, v226
	v_mul_f32_e32 v215, v215, v226
	v_mul_f32_e32 v216, v216, v226
	v_mul_f32_e32 v217, v217, v226
	v_mul_f32_e32 v218, v218, v226
	v_mul_f32_e32 v219, v219, v226
	v_mul_f32_e32 v220, v220, v226
	v_mul_f32_e32 v221, v221, v226
	v_mul_f32_e32 v222, v222, v226
	v_mul_f32_e32 v223, v223, v226
	v_fmac_f32_e32 v160, v208, v56
	v_fmac_f32_e32 v161, v209, v57
	v_fmac_f32_e32 v162, v210, v58
	v_fmac_f32_e32 v163, v211, v59
	v_fmac_f32_e32 v164, v212, v60
	v_fmac_f32_e32 v165, v213, v61
	v_fmac_f32_e32 v166, v214, v62
	v_fmac_f32_e32 v167, v215, v63
	v_fmac_f32_e32 v168, v216, v64
	v_fmac_f32_e32 v169, v217, v65
	v_fmac_f32_e32 v170, v218, v66
	v_fmac_f32_e32 v171, v219, v67
	v_fmac_f32_e32 v172, v220, v68
	v_fmac_f32_e32 v173, v221, v69
	v_fmac_f32_e32 v174, v222, v70
	v_fmac_f32_e32 v175, v223, v71
	global_store_dwordx4 v1, v[160:163], s[8:9] offset:0
	global_store_dwordx4 v1, v[164:167], s[8:9] offset:16
	global_store_dwordx4 v1, v[168:171], s[8:9] offset:2048
	global_store_dwordx4 v1, v[172:175], s[8:9] offset:2064
	s_add_u32 s8, s8, 0x1000
	s_addc_u32 s9, s9, 0
	global_load_dwordx4 v[160:163], v1, s[6:7] offset:0
	global_load_dwordx4 v[164:167], v1, s[6:7] offset:16
	global_load_dwordx4 v[168:171], v1, s[6:7] offset:2048
	global_load_dwordx4 v[172:175], v1, s[6:7] offset:2064
	global_load_dwordx4 v[176:179], v2, s[10:11]
	global_load_dwordx4 v[180:183], v2, s[10:11] offset:1024
	global_load_dwordx4 v[184:187], v2, s[12:13]
	global_load_dwordx4 v[188:191], v2, s[12:13] offset:1024
	s_add_u32 s6, s6, 0x1000
	s_addc_u32 s7, s7, 0
	s_add_u32 s10, s10, 0x800
	s_addc_u32 s11, s11, 0
	s_add_u32 s12, s12, 0x800
	s_addc_u32 s13, s13, 0
	s_waitcnt vmcnt(24)
; DI float shx(float v, int mask) { const int l = olane(); return __builtin_bit_cast(float, __builtin_amdgcn_ds_bpermute(((l ^ mask) & 63) << 2, __builtin_bit_cast(int, v))); }
; DI void row_phase(const bf16_t* msrc, const float* xsrc, float* xdst, const float* g_post, const float* g_next, bf16_t* hdst, const int gw) {
;     ...
;             for (int j = 0; j < 4; ++j) xv[r][j] = *(const f32x4*)(xsrc + (size_t)(rowb + r) * DM + lane * 4 + 256 * j);
;         if (msrc) {
; #pragma unroll
;             for (int r = 0; r < RB; ++r)
; #pragma unroll
;                 for (int j = 0; j < 4; ++j) { const u32x2 mw = *(const u32x2*)(msrc + (size_t)(rowb + r) * DM + lane * 4 + 256 * j);
;                     mv[r][j] = (f32x4){__uint_as_float(mw[0] << 16), __uint_as_float(mw[0] & 0xffff0000u), __uint_as_float(mw[1] << 16), __uint_as_float(mw[1] & 0xffff0000u)}; }
;             float ss[RB];
; #pragma unroll
;             for (int r = 0; r < RB; ++r) { ss[r] = 0.f;
; #pragma unroll
;                 for (int j = 0; j < 4; ++j) ss[r] += mv[r][j][0] * mv[r][j][0] + mv[r][j][1] * mv[r][j][1] + mv[r][j][2] * mv[r][j][2] + mv[r][j][3] * mv[r][j][3]; }
; #pragma unroll
;             for (int o = 32; o >= 1; o >>= 1)
; #pragma unroll
;                 for (int r = 0; r < RB; ++r) ss[r] += shx(ss[r], o);
; #pragma unroll
;             for (int j = 0; j < 4; ++j) { const f32x4 g = *(const f32x4*)(g_post + lane * 4 + 256 * j);
; #pragma unroll
;                 for (int r = 0; r < RB; ++r) { const float r1 = rsqrtf(ss[r] * (1.f / DM) + EPS); xv[r][j] = xv[r][j] + mv[r][j] * r1 * g; *(f32x4*)(xdst + (size_t)(rowb + r) * DM + lane * 4 + 256 * j) = xv[r][j]; } }
	v_lshlrev_b32_e32 v208, 16, v112
	v_and_b32_e32 v209, 0xffff0000, v112
	v_lshlrev_b32_e32 v210, 16, v113
	v_and_b32_e32 v211, 0xffff0000, v113
	v_lshlrev_b32_e32 v212, 16, v114
	v_and_b32_e32 v213, 0xffff0000, v114
	v_lshlrev_b32_e32 v214, 16, v115
	v_and_b32_e32 v215, 0xffff0000, v115
	v_lshlrev_b32_e32 v216, 16, v116
	v_and_b32_e32 v217, 0xffff0000, v116
	v_lshlrev_b32_e32 v218, 16, v117
	v_and_b32_e32 v219, 0xffff0000, v117
	v_lshlrev_b32_e32 v220, 16, v118
	v_and_b32_e32 v221, 0xffff0000, v118
	v_lshlrev_b32_e32 v222, 16, v119
	v_and_b32_e32 v223, 0xffff0000, v119
	v_mul_f32_e32 v224, v208, v208
	v_fmac_f32_e32 v224, v209, v209
	v_fmac_f32_e32 v224, v210, v210
	v_fmac_f32_e32 v224, v211, v211
	v_fmac_f32_e32 v224, v212, v212
	v_fmac_f32_e32 v224, v213, v213
	v_fmac_f32_e32 v224, v214, v214
	v_fmac_f32_e32 v224, v215, v215
	v_fmac_f32_e32 v224, v216, v216
	v_fmac_f32_e32 v224, v217, v217
	v_fmac_f32_e32 v224, v218, v218
	v_fmac_f32_e32 v224, v219, v219
	v_fmac_f32_e32 v224, v220, v220
	v_fmac_f32_e32 v224, v221, v221
	v_fmac_f32_e32 v224, v222, v222
	v_fmac_f32_e32 v224, v223, v223
	s_nop 1
	v_add_f32_dpp v224, v224, v224 quad_perm:[1,0,3,2] row_mask:0xf bank_mask:0xf
	s_nop 1
	v_add_f32_dpp v224, v224, v224 quad_perm:[2,3,0,1] row_mask:0xf bank_mask:0xf
	s_nop 1
	v_add_f32_dpp v224, v224, v224 row_ror:4 row_mask:0xf bank_mask:0xf
	s_nop 1
	v_add_f32_dpp v224, v224, v224 row_ror:8 row_mask:0xf bank_mask:0xf
	s_nop 1
	v_readlane_b32 s20, v224, 0
	v_readlane_b32 s21, v224, 16
	v_readlane_b32 s22, v224, 32
	v_readlane_b32 s23, v224, 48
	s_nop 1
	v_mov_b32_e32 v225, s20
	v_add_f32_e32 v225, s21, v225
	v_add_f32_e32 v225, s22, v225
	v_add_f32_e32 v225, s23, v225
	v_mov_b32_e32 v226, 0x358637bd
	v_fmac_f32_e32 v226, 0x3a800000, v225
	v_rsq_f32_e32 v226, v226
	s_nop 0
	v_mul_f32_e32 v208, v208, v226
	v_mul_f32_e32 v209, v209, v226
	v_mul_f32_e32 v210, v210, v226
	v_mul_f32_e32 v211, v211, v226
	v_mul_f32_e32 v212, v212, v226
	v_mul_f32_e32 v213, v213, v226
	v_mul_f32_e32 v214, v214, v226
	v_mul_f32_e32 v215, v215, v226
	v_mul_f32_e32 v216, v216, v226
	v_mul_f32_e32 v217, v217, v226
	v_mul_f32_e32 v218, v218, v226
	v_mul_f32_e32 v219, v219, v226
	v_mul_f32_e32 v220, v220, v226
	v_mul_f32_e32 v221, v221, v226
	v_mul_f32_e32 v222, v222, v226
	v_mul_f32_e32 v223, v223, v226
	v_fmac_f32_e32 v96, v208, v40
	v_fmac_f32_e32 v97, v209, v41
	v_fmac_f32_e32 v98, v210, v42
	v_fmac_f32_e32 v99, v211, v43
	v_fmac_f32_e32 v100, v212, v44
	v_fmac_f32_e32 v101, v213, v45
	v_fmac_f32_e32 v102, v214, v46
	v_fmac_f32_e32 v103, v215, v47
	v_fmac_f32_e32 v104, v216, v48
	v_fmac_f32_e32 v105, v217, v49
	v_fmac_f32_e32 v106, v218, v50
	v_fmac_f32_e32 v107, v219, v51
	v_fmac_f32_e32 v108, v220, v52
	v_fmac_f32_e32 v109, v221, v53
	v_fmac_f32_e32 v110, v222, v54
	v_fmac_f32_e32 v111, v223, v55
	v_lshlrev_b32_e32 v208, 16, v120
	v_and_b32_e32 v209, 0xffff0000, v120
	v_lshlrev_b32_e32 v210, 16, v121
	v_and_b32_e32 v211, 0xffff0000, v121
	v_lshlrev_b32_e32 v212, 16, v122
	v_and_b32_e32 v213, 0xffff0000, v122
	v_lshlrev_b32_e32 v214, 16, v123
	v_and_b32_e32 v215, 0xffff0000, v123
	v_lshlrev_b32_e32 v216, 16, v124
	v_and_b32_e32 v217, 0xffff0000, v124
	v_lshlrev_b32_e32 v218, 16, v125
	v_and_b32_e32 v219, 0xffff0000, v125
	v_lshlrev_b32_e32 v220, 16, v126
	v_and_b32_e32 v221, 0xffff0000, v126
	v_lshlrev_b32_e32 v222, 16, v127
	v_and_b32_e32 v223, 0xffff0000, v127
	v_mul_f32_e32 v224, v208, v208
	v_fmac_f32_e32 v224, v209, v209
	v_fmac_f32_e32 v224, v210, v210
	v_fmac_f32_e32 v224, v211, v211
	v_fmac_f32_e32 v224, v212, v212
	v_fmac_f32_e32 v224, v213, v213
	v_fmac_f32_e32 v224, v214, v214
	v_fmac_f32_e32 v224, v215, v215
	v_fmac_f32_e32 v224, v216, v216
	v_fmac_f32_e32 v224, v217, v217
	v_fmac_f32_e32 v224, v218, v218
	v_fmac_f32_e32 v224, v219, v219
	v_fmac_f32_e32 v224, v220, v220
	v_fmac_f32_e32 v224, v221, v221
	v_fmac_f32_e32 v224, v222, v222
	v_fmac_f32_e32 v224, v223, v223
	s_nop 1
	v_add_f32_dpp v224, v224, v224 quad_perm:[1,0,3,2] row_mask:0xf bank_mask:0xf
	s_nop 1
	v_add_f32_dpp v224, v224, v224 quad_perm:[2,3,0,1] row_mask:0xf bank_mask:0xf
	s_nop 1
	v_add_f32_dpp v224, v224, v224 row_ror:4 row_mask:0xf bank_mask:0xf
	s_nop 1
	v_add_f32_dpp v224, v224, v224 row_ror:8 row_mask:0xf bank_mask:0xf
	s_nop 1
	v_readlane_b32 s20, v224, 0
	v_readlane_b32 s21, v224, 16
	v_readlane_b32 s22, v224, 32
	v_readlane_b32 s23, v224, 48
	s_nop 1
	v_mov_b32_e32 v225, s20
	v_add_f32_e32 v225, s21, v225
	v_add_f32_e32 v225, s22, v225
	v_add_f32_e32 v225, s23, v225
	v_mov_b32_e32 v226, 0x358637bd
	v_fmac_f32_e32 v226, 0x3a800000, v225
	v_rsq_f32_e32 v226, v226
	s_nop 0
	v_mul_f32_e32 v208, v208, v226
	v_mul_f32_e32 v209, v209, v226
	v_mul_f32_e32 v210, v210, v226
	v_mul_f32_e32 v211, v211, v226
	v_mul_f32_e32 v212, v212, v226
	v_mul_f32_e32 v213, v213, v226
	v_mul_f32_e32 v214, v214, v226
	v_mul_f32_e32 v215, v215, v226
	v_mul_f32_e32 v216, v216, v226
	v_mul_f32_e32 v217, v217, v226
	v_mul_f32_e32 v218, v218, v226
	v_mul_f32_e32 v219, v219, v226
	v_mul_f32_e32 v220, v220, v226
	v_mul_f32_e32 v221, v221, v226
	v_mul_f32_e32 v222, v222, v226
	v_mul_f32_e32 v223, v223, v226
	v_fmac_f32_e32 v96, v208, v56
	v_fmac_f32_e32 v97, v209, v57
	v_fmac_f32_e32 v98, v210, v58
	v_fmac_f32_e32 v99, v211, v59
	v_fmac_f32_e32 v100, v212, v60
	v_fmac_f32_e32 v101, v213, v61
	v_fmac_f32_e32 v102, v214, v62
	v_fmac_f32_e32 v103, v215, v63
	v_fmac_f32_e32 v104, v216, v64
	v_fmac_f32_e32 v105, v217, v65
	v_fmac_f32_e32 v106, v218, v66
	v_fmac_f32_e32 v107, v219, v67
	v_fmac_f32_e32 v108, v220, v68
	v_fmac_f32_e32 v109, v221, v69
	v_fmac_f32_e32 v110, v222, v70
	v_fmac_f32_e32 v111, v223, v71
	global_store_dwordx4 v1, v[96:99], s[8:9] offset:0
	global_store_dwordx4 v1, v[100:103], s[8:9] offset:16
	global_store_dwordx4 v1, v[104:107], s[8:9] offset:2048
	global_store_dwordx4 v1, v[108:111], s[8:9] offset:2064
	s_add_u32 s8, s8, 0x1000
	s_addc_u32 s9, s9, 0
	global_load_dwordx4 v[96:99], v1, s[6:7] offset:0
	global_load_dwordx4 v[100:103], v1, s[6:7] offset:16
	global_load_dwordx4 v[104:107], v1, s[6:7] offset:2048
	global_load_dwordx4 v[108:111], v1, s[6:7] offset:2064
	global_load_dwordx4 v[112:115], v2, s[10:11]
	global_load_dwordx4 v[116:119], v2, s[10:11] offset:1024
	global_load_dwordx4 v[120:123], v2, s[12:13]
	global_load_dwordx4 v[124:127], v2, s[12:13] offset:1024
	s_add_u32 s6, s6, 0x1000
	s_addc_u32 s7, s7, 0
	s_add_u32 s10, s10, 0x800
	s_addc_u32 s11, s11, 0
	s_add_u32 s12, s12, 0x800
	s_addc_u32 s13, s13, 0
	s_waitcnt vmcnt(24)
; DI float shx(float v, int mask) { const int l = olane(); return __builtin_bit_cast(float, __builtin_amdgcn_ds_bpermute(((l ^ mask) & 63) << 2, __builtin_bit_cast(int, v))); }
; DI void row_phase(const bf16_t* msrc, const float* xsrc, float* xdst, const float* g_post, const float* g_next, bf16_t* hdst, const int gw) {
;     ...
;             for (int j = 0; j < 4; ++j) xv[r][j] = *(const f32x4*)(xsrc + (size_t)(rowb + r) * DM + lane * 4 + 256 * j);
;         if (msrc) {
; #pragma unroll
;             for (int r = 0; r < RB; ++r)
; #pragma unroll
;                 for (int j = 0; j < 4; ++j) { const u32x2 mw = *(const u32x2*)(msrc + (size_t)(rowb + r) * DM + lane * 4 + 256 * j);
;                     mv[r][j] = (f32x4){__uint_as_float(mw[0] << 16), __uint_as_float(mw[0] & 0xffff0000u), __uint_as_float(mw[1] << 16), __uint_as_float(mw[1] & 0xffff0000u)}; }
;             float ss[RB];
; #pragma unroll
;             for (int r = 0; r < RB; ++r) { ss[r] = 0.f;
; #pragma unroll
;                 for (int j = 0; j < 4; ++j) ss[r] += mv[r][j][0] * mv[r][j][0] + mv[r][j][1] * mv[r][j][1] + mv[r][j][2] * mv[r][j][2] + mv[r][j][3] * mv[r][j][3]; }
; #pragma unroll
;             for (int o = 32; o >= 1; o >>= 1)
; #pragma unroll
;                 for (int r = 0; r < RB; ++r) ss[r] += shx(ss[r], o);
; #pragma unroll
;             for (int j = 0; j < 4; ++j) { const f32x4 g = *(const f32x4*)(g_post + lane * 4 + 256 * j);
; #pragma unroll
;                 for (int r = 0; r < RB; ++r) { const float r1 = rsqrtf(ss[r] * (1.f / DM) + EPS); xv[r][j] = xv[r][j] + mv[r][j] * r1 * g; *(f32x4*)(xdst + (size_t)(rowb + r) * DM + lane * 4 + 256 * j) = xv[r][j]; } }
	v_lshlrev_b32_e32 v208, 16, v144
	v_and_b32_e32 v209, 0xffff0000, v144
	v_lshlrev_b32_e32 v210, 16, v145
	v_and_b32_e32 v211, 0xffff0000, v145
	v_lshlrev_b32_e32 v212, 16, v146
	v_and_b32_e32 v213, 0xffff0000, v146
	v_lshlrev_b32_e32 v214, 16, v147
	v_and_b32_e32 v215, 0xffff0000, v147
	v_lshlrev_b32_e32 v216, 16, v148
	v_and_b32_e32 v217, 0xffff0000, v148
	v_lshlrev_b32_e32 v218, 16, v149
	v_and_b32_e32 v219, 0xffff0000, v149
	v_lshlrev_b32_e32 v220, 16, v150
	v_and_b32_e32 v221, 0xffff0000, v150
	v_lshlrev_b32_e32 v222, 16, v151
	v_and_b32_e32 v223, 0xffff0000, v151
	v_mul_f32_e32 v224, v208, v208
	v_fmac_f32_e32 v224, v209, v209
	v_fmac_f32_e32 v224, v210, v210
	v_fmac_f32_e32 v224, v211, v211
	v_fmac_f32_e32 v224, v212, v212
	v_fmac_f32_e32 v224, v213, v213
	v_fmac_f32_e32 v224, v214, v214
	v_fmac_f32_e32 v224, v215, v215
	v_fmac_f32_e32 v224, v216, v216
	v_fmac_f32_e32 v224, v217, v217
	v_fmac_f32_e32 v224, v218, v218
	v_fmac_f32_e32 v224, v219, v219
	v_fmac_f32_e32 v224, v220, v220
	v_fmac_f32_e32 v224, v221, v221
	v_fmac_f32_e32 v224, v222, v222
	v_fmac_f32_e32 v224, v223, v223
	s_nop 1
	v_add_f32_dpp v224, v224, v224 quad_perm:[1,0,3,2] row_mask:0xf bank_mask:0xf
	s_nop 1
	v_add_f32_dpp v224, v224, v224 quad_perm:[2,3,0,1] row_mask:0xf bank_mask:0xf
	s_nop 1
	v_add_f32_dpp v224, v224, v224 row_ror:4 row_mask:0xf bank_mask:0xf
	s_nop 1
	v_add_f32_dpp v224, v224, v224 row_ror:8 row_mask:0xf bank_mask:0xf
	s_nop 1
	v_readlane_b32 s20, v224, 0
	v_readlane_b32 s21, v224, 16
	v_readlane_b32 s22, v224, 32
	v_readlane_b32 s23, v224, 48
	s_nop 1
	v_mov_b32_e32 v225, s20
	v_add_f32_e32 v225, s21, v225
	v_add_f32_e32 v225, s22, v225
	v_add_f32_e32 v225, s23, v225
	v_mov_b32_e32 v226, 0x358637bd
	v_fmac_f32_e32 v226, 0x3a800000, v225
	v_rsq_f32_e32 v226, v226
	s_nop 0
	v_mul_f32_e32 v208, v208, v226
	v_mul_f32_e32 v209, v209, v226
	v_mul_f32_e32 v210, v210, v226
	v_mul_f32_e32 v211, v211, v226
	v_mul_f32_e32 v212, v212, v226
	v_mul_f32_e32 v213, v213, v226
	v_mul_f32_e32 v214, v214, v226
	v_mul_f32_e32 v215, v215, v226
	v_mul_f32_e32 v216, v216, v226
	v_mul_f32_e32 v217, v217, v226
	v_mul_f32_e32 v218, v218, v226
	v_mul_f32_e32 v219, v219, v226
	v_mul_f32_e32 v220, v220, v226
	v_mul_f32_e32 v221, v221, v226
	v_mul_f32_e32 v222, v222, v226
	v_mul_f32_e32 v223, v223, v226
	v_fmac_f32_e32 v128, v208, v40
	v_fmac_f32_e32 v129, v209, v41
	v_fmac_f32_e32 v130, v210, v42
	v_fmac_f32_e32 v131, v211, v43
	v_fmac_f32_e32 v132, v212, v44
	v_fmac_f32_e32 v133, v213, v45
	v_fmac_f32_e32 v134, v214, v46
	v_fmac_f32_e32 v135, v215, v47
	v_fmac_f32_e32 v136, v216, v48
	v_fmac_f32_e32 v137, v217, v49
	v_fmac_f32_e32 v138, v218, v50
	v_fmac_f32_e32 v139, v219, v51
	v_fmac_f32_e32 v140, v220, v52
	v_fmac_f32_e32 v141, v221, v53
	v_fmac_f32_e32 v142, v222, v54
	v_fmac_f32_e32 v143, v223, v55
	v_lshlrev_b32_e32 v208, 16, v152
	v_and_b32_e32 v209, 0xffff0000, v152
	v_lshlrev_b32_e32 v210, 16, v153
	v_and_b32_e32 v211, 0xffff0000, v153
	v_lshlrev_b32_e32 v212, 16, v154
	v_and_b32_e32 v213, 0xffff0000, v154
	v_lshlrev_b32_e32 v214, 16, v155
	v_and_b32_e32 v215, 0xffff0000, v155
	v_lshlrev_b32_e32 v216, 16, v156
	v_and_b32_e32 v217, 0xffff0000, v156
	v_lshlrev_b32_e32 v218, 16, v157
	v_and_b32_e32 v219, 0xffff0000, v157
	v_lshlrev_b32_e32 v220, 16, v158
	v_and_b32_e32 v221, 0xffff0000, v158
	v_lshlrev_b32_e32 v222, 16, v159
	v_and_b32_e32 v223, 0xffff0000, v159
	v_mul_f32_e32 v224, v208, v208
	v_fmac_f32_e32 v224, v209, v209
	v_fmac_f32_e32 v224, v210, v210
	v_fmac_f32_e32 v224, v211, v211
	v_fmac_f32_e32 v224, v212, v212
	v_fmac_f32_e32 v224, v213, v213
	v_fmac_f32_e32 v224, v214, v214
	v_fmac_f32_e32 v224, v215, v215
	v_fmac_f32_e32 v224, v216, v216
	v_fmac_f32_e32 v224, v217, v217
	v_fmac_f32_e32 v224, v218, v218
	v_fmac_f32_e32 v224, v219, v219
	v_fmac_f32_e32 v224, v220, v220
	v_fmac_f32_e32 v224, v221, v221
	v_fmac_f32_e32 v224, v222, v222
	v_fmac_f32_e32 v224, v223, v223
	s_nop 1
	v_add_f32_dpp v224, v224, v224 quad_perm:[1,0,3,2] row_mask:0xf bank_mask:0xf
	s_nop 1
	v_add_f32_dpp v224, v224, v224 quad_perm:[2,3,0,1] row_mask:0xf bank_mask:0xf
	s_nop 1
	v_add_f32_dpp v224, v224, v224 row_ror:4 row_mask:0xf bank_mask:0xf
	s_nop 1
	v_add_f32_dpp v224, v224, v224 row_ror:8 row_mask:0xf bank_mask:0xf
	s_nop 1
	v_readlane_b32 s20, v224, 0
	v_readlane_b32 s21, v224, 16
	v_readlane_b32 s22, v224, 32
	v_readlane_b32 s23, v224, 48
	s_nop 1
	v_mov_b32_e32 v225, s20
	v_add_f32_e32 v225, s21, v225
	v_add_f32_e32 v225, s22, v225
	v_add_f32_e32 v225, s23, v225
	v_mov_b32_e32 v226, 0x358637bd
	v_fmac_f32_e32 v226, 0x3a800000, v225
	v_rsq_f32_e32 v226, v226
	s_nop 0
	v_mul_f32_e32 v208, v208, v226
	v_mul_f32_e32 v209, v209, v226
	v_mul_f32_e32 v210, v210, v226
	v_mul_f32_e32 v211, v211, v226
	v_mul_f32_e32 v212, v212, v226
	v_mul_f32_e32 v213, v213, v226
	v_mul_f32_e32 v214, v214, v226
	v_mul_f32_e32 v215, v215, v226
	v_mul_f32_e32 v216, v216, v226
	v_mul_f32_e32 v217, v217, v226
	v_mul_f32_e32 v218, v218, v226
	v_mul_f32_e32 v219, v219, v226
	v_mul_f32_e32 v220, v220, v226
	v_mul_f32_e32 v221, v221, v226
	v_mul_f32_e32 v222, v222, v226
	v_mul_f32_e32 v223, v223, v226
	v_fmac_f32_e32 v128, v208, v56
	v_fmac_f32_e32 v129, v209, v57
	v_fmac_f32_e32 v130, v210, v58
	v_fmac_f32_e32 v131, v211, v59
	v_fmac_f32_e32 v132, v212, v60
	v_fmac_f32_e32 v133, v213, v61
	v_fmac_f32_e32 v134, v214, v62
	v_fmac_f32_e32 v135, v215, v63
	v_fmac_f32_e32 v136, v216, v64
	v_fmac_f32_e32 v137, v217, v65
	v_fmac_f32_e32 v138, v218, v66
	v_fmac_f32_e32 v139, v219, v67
	v_fmac_f32_e32 v140, v220, v68
	v_fmac_f32_e32 v141, v221, v69
	v_fmac_f32_e32 v142, v222, v70
	v_fmac_f32_e32 v143, v223, v71
	global_store_dwordx4 v1, v[128:131], s[8:9] offset:0
	global_store_dwordx4 v1, v[132:135], s[8:9] offset:16
	global_store_dwordx4 v1, v[136:139], s[8:9] offset:2048
	global_store_dwordx4 v1, v[140:143], s[8:9] offset:2064
	s_add_u32 s8, s8, 0x1000
	s_addc_u32 s9, s9, 0
	global_load_dwordx4 v[128:131], v1, s[6:7] offset:0
	global_load_dwordx4 v[132:135], v1, s[6:7] offset:16
	global_load_dwordx4 v[136:139], v1, s[6:7] offset:2048
	global_load_dwordx4 v[140:143], v1, s[6:7] offset:2064
	global_load_dwordx4 v[144:147], v2, s[10:11]
	global_load_dwordx4 v[148:151], v2, s[10:11] offset:1024
	global_load_dwordx4 v[152:155], v2, s[12:13]
	global_load_dwordx4 v[156:159], v2, s[12:13] offset:1024
	s_add_u32 s6, s6, 0x1000
	s_addc_u32 s7, s7, 0
	s_add_u32 s10, s10, 0x800
	s_addc_u32 s11, s11, 0
	s_add_u32 s12, s12, 0x800
	s_addc_u32 s13, s13, 0
	s_waitcnt vmcnt(24)
; DI float shx(float v, int mask) { const int l = olane(); return __builtin_bit_cast(float, __builtin_amdgcn_ds_bpermute(((l ^ mask) & 63) << 2, __builtin_bit_cast(int, v))); }
; DI void row_phase(const bf16_t* msrc, const float* xsrc, float* xdst, const float* g_post, const float* g_next, bf16_t* hdst, const int gw) {
;     ...
;             for (int j = 0; j < 4; ++j) xv[r][j] = *(const f32x4*)(xsrc + (size_t)(rowb + r) * DM + lane * 4 + 256 * j);
;         if (msrc) {
; #pragma unroll
;             for (int r = 0; r < RB; ++r)
; #pragma unroll
;                 for (int j = 0; j < 4; ++j) { const u32x2 mw = *(const u32x2*)(msrc + (size_t)(rowb + r) * DM + lane * 4 + 256 * j);
;                     mv[r][j] = (f32x4){__uint_as_float(mw[0] << 16), __uint_as_float(mw[0] & 0xffff0000u), __uint_as_float(mw[1] << 16), __uint_as_float(mw[1] & 0xffff0000u)}; }
;             float ss[RB];
; #pragma unroll
;             for (int r = 0; r < RB; ++r) { ss[r] = 0.f;
; #pragma unroll
;                 for (int j = 0; j < 4; ++j) ss[r] += mv[r][j][0] * mv[r][j][0] + mv[r][j][1] * mv[r][j][1] + mv[r][j][2] * mv[r][j][2] + mv[r][j][3] * mv[r][j][3]; }
; #pragma unroll
;             for (int o = 32; o >= 1; o >>= 1)
; #pragma unroll
;                 for (int r = 0; r < RB; ++r) ss[r] += shx(ss[r], o);
; #pragma unroll
;             for (int j = 0; j < 4; ++j) { const f32x4 g = *(const f32x4*)(g_post + lane * 4 + 256 * j);
; #pragma unroll
;                 for (int r = 0; r < RB; ++r) { const float r1 = rsqrtf(ss[r] * (1.f / DM) + EPS); xv[r][j] = xv[r][j] + mv[r][j] * r1 * g; *(f32x4*)(xdst + (size_t)(rowb + r) * DM + lane * 4 + 256 * j) = xv[r][j]; } }
	v_lshlrev_b32_e32 v208, 16, v176
	v_and_b32_e32 v209, 0xffff0000, v176
	v_lshlrev_b32_e32 v210, 16, v177
	v_and_b32_e32 v211, 0xffff0000, v177
	v_lshlrev_b32_e32 v212, 16, v178
	v_and_b32_e32 v213, 0xffff0000, v178
	v_lshlrev_b32_e32 v214, 16, v179
	v_and_b32_e32 v215, 0xffff0000, v179
	v_lshlrev_b32_e32 v216, 16, v180
	v_and_b32_e32 v217, 0xffff0000, v180
	v_lshlrev_b32_e32 v218, 16, v181
	v_and_b32_e32 v219, 0xffff0000, v181
	v_lshlrev_b32_e32 v220, 16, v182
	v_and_b32_e32 v221, 0xffff0000, v182
	v_lshlrev_b32_e32 v222, 16, v183
	v_and_b32_e32 v223, 0xffff0000, v183
	v_mul_f32_e32 v224, v208, v208
	v_fmac_f32_e32 v224, v209, v209
	v_fmac_f32_e32 v224, v210, v210
	v_fmac_f32_e32 v224, v211, v211
	v_fmac_f32_e32 v224, v212, v212
	v_fmac_f32_e32 v224, v213, v213
	v_fmac_f32_e32 v224, v214, v214
	v_fmac_f32_e32 v224, v215, v215
	v_fmac_f32_e32 v224, v216, v216
	v_fmac_f32_e32 v224, v217, v217
	v_fmac_f32_e32 v224, v218, v218
	v_fmac_f32_e32 v224, v219, v219
	v_fmac_f32_e32 v224, v220, v220
	v_fmac_f32_e32 v224, v221, v221
	v_fmac_f32_e32 v224, v222, v222
	v_fmac_f32_e32 v224, v223, v223
	s_nop 1
	v_add_f32_dpp v224, v224, v224 quad_perm:[1,0,3,2] row_mask:0xf bank_mask:0xf
	s_nop 1
	v_add_f32_dpp v224, v224, v224 quad_perm:[2,3,0,1] row_mask:0xf bank_mask:0xf
	s_nop 1
	v_add_f32_dpp v224, v224, v224 row_ror:4 row_mask:0xf bank_mask:0xf
	s_nop 1
	v_add_f32_dpp v224, v224, v224 row_ror:8 row_mask:0xf bank_mask:0xf
	s_nop 1
	v_readlane_b32 s20, v224, 0
	v_readlane_b32 s21, v224, 16
	v_readlane_b32 s22, v224, 32
	v_readlane_b32 s23, v224, 48
	s_nop 1
	v_mov_b32_e32 v225, s20
	v_add_f32_e32 v225, s21, v225
	v_add_f32_e32 v225, s22, v225
	v_add_f32_e32 v225, s23, v225
	v_mov_b32_e32 v226, 0x358637bd
	v_fmac_f32_e32 v226, 0x3a800000, v225
	v_rsq_f32_e32 v226, v226
	s_nop 0
	v_mul_f32_e32 v208, v208, v226
	v_mul_f32_e32 v209, v209, v226
	v_mul_f32_e32 v210, v210, v226
	v_mul_f32_e32 v211, v211, v226
	v_mul_f32_e32 v212, v212, v226
	v_mul_f32_e32 v213, v213, v226
	v_mul_f32_e32 v214, v214, v226
	v_mul_f32_e32 v215, v215, v226
	v_mul_f32_e32 v216, v216, v226
	v_mul_f32_e32 v217, v217, v226
	v_mul_f32_e32 v218, v218, v226
	v_mul_f32_e32 v219, v219, v226
	v_mul_f32_e32 v220, v220, v226
	v_mul_f32_e32 v221, v221, v226
	v_mul_f32_e32 v222, v222, v226
	v_mul_f32_e32 v223, v223, v226
	v_fmac_f32_e32 v160, v208, v40
	v_fmac_f32_e32 v161, v209, v41
	v_fmac_f32_e32 v162, v210, v42
	v_fmac_f32_e32 v163, v211, v43
	v_fmac_f32_e32 v164, v212, v44
	v_fmac_f32_e32 v165, v213, v45
	v_fmac_f32_e32 v166, v214, v46
	v_fmac_f32_e32 v167, v215, v47
	v_fmac_f32_e32 v168, v216, v48
	v_fmac_f32_e32 v169, v217, v49
	v_fmac_f32_e32 v170, v218, v50
	v_fmac_f32_e32 v171, v219, v51
	v_fmac_f32_e32 v172, v220, v52
	v_fmac_f32_e32 v173, v221, v53
	v_fmac_f32_e32 v174, v222, v54
	v_fmac_f32_e32 v175, v223, v55
	v_lshlrev_b32_e32 v208, 16, v184
	v_and_b32_e32 v209, 0xffff0000, v184
	v_lshlrev_b32_e32 v210, 16, v185
	v_and_b32_e32 v211, 0xffff0000, v185
	v_lshlrev_b32_e32 v212, 16, v186
	v_and_b32_e32 v213, 0xffff0000, v186
	v_lshlrev_b32_e32 v214, 16, v187
	v_and_b32_e32 v215, 0xffff0000, v187
	v_lshlrev_b32_e32 v216, 16, v188
	v_and_b32_e32 v217, 0xffff0000, v188
	v_lshlrev_b32_e32 v218, 16, v189
	v_and_b32_e32 v219, 0xffff0000, v189
	v_lshlrev_b32_e32 v220, 16, v190
	v_and_b32_e32 v221, 0xffff0000, v190
	v_lshlrev_b32_e32 v222, 16, v191
	v_and_b32_e32 v223, 0xffff0000, v191
	v_mul_f32_e32 v224, v208, v208
	v_fmac_f32_e32 v224, v209, v209
	v_fmac_f32_e32 v224, v210, v210
	v_fmac_f32_e32 v224, v211, v211
	v_fmac_f32_e32 v224, v212, v212
	v_fmac_f32_e32 v224, v213, v213
	v_fmac_f32_e32 v224, v214, v214
	v_fmac_f32_e32 v224, v215, v215
	v_fmac_f32_e32 v224, v216, v216
	v_fmac_f32_e32 v224, v217, v217
	v_fmac_f32_e32 v224, v218, v218
	v_fmac_f32_e32 v224, v219, v219
	v_fmac_f32_e32 v224, v220, v220
	v_fmac_f32_e32 v224, v221, v221
	v_fmac_f32_e32 v224, v222, v222
	v_fmac_f32_e32 v224, v223, v223
	s_nop 1
	v_add_f32_dpp v224, v224, v224 quad_perm:[1,0,3,2] row_mask:0xf bank_mask:0xf
	s_nop 1
	v_add_f32_dpp v224, v224, v224 quad_perm:[2,3,0,1] row_mask:0xf bank_mask:0xf
	s_nop 1
	v_add_f32_dpp v224, v224, v224 row_ror:4 row_mask:0xf bank_mask:0xf
	s_nop 1
	v_add_f32_dpp v224, v224, v224 row_ror:8 row_mask:0xf bank_mask:0xf
	s_nop 1
	v_readlane_b32 s20, v224, 0
	v_readlane_b32 s21, v224, 16
	v_readlane_b32 s22, v224, 32
	v_readlane_b32 s23, v224, 48
	s_nop 1
	v_mov_b32_e32 v225, s20
	v_add_f32_e32 v225, s21, v225
	v_add_f32_e32 v225, s22, v225
	v_add_f32_e32 v225, s23, v225
	v_mov_b32_e32 v226, 0x358637bd
	v_fmac_f32_e32 v226, 0x3a800000, v225
	v_rsq_f32_e32 v226, v226
	s_nop 0
	v_mul_f32_e32 v208, v208, v226
	v_mul_f32_e32 v209, v209, v226
	v_mul_f32_e32 v210, v210, v226
	v_mul_f32_e32 v211, v211, v226
	v_mul_f32_e32 v212, v212, v226
	v_mul_f32_e32 v213, v213, v226
	v_mul_f32_e32 v214, v214, v226
	v_mul_f32_e32 v215, v215, v226
	v_mul_f32_e32 v216, v216, v226
	v_mul_f32_e32 v217, v217, v226
	v_mul_f32_e32 v218, v218, v226
	v_mul_f32_e32 v219, v219, v226
	v_mul_f32_e32 v220, v220, v226
	v_mul_f32_e32 v221, v221, v226
	v_mul_f32_e32 v222, v222, v226
	v_mul_f32_e32 v223, v223, v226
	v_fmac_f32_e32 v160, v208, v56
	v_fmac_f32_e32 v161, v209, v57
	v_fmac_f32_e32 v162, v210, v58
	v_fmac_f32_e32 v163, v211, v59
	v_fmac_f32_e32 v164, v212, v60
	v_fmac_f32_e32 v165, v213, v61
	v_fmac_f32_e32 v166, v214, v62
	v_fmac_f32_e32 v167, v215, v63
	v_fmac_f32_e32 v168, v216, v64
	v_fmac_f32_e32 v169, v217, v65
	v_fmac_f32_e32 v170, v218, v66
	v_fmac_f32_e32 v171, v219, v67
	v_fmac_f32_e32 v172, v220, v68
	v_fmac_f32_e32 v173, v221, v69
	v_fmac_f32_e32 v174, v222, v70
	v_fmac_f32_e32 v175, v223, v71
	global_store_dwordx4 v1, v[160:163], s[8:9] offset:0
	global_store_dwordx4 v1, v[164:167], s[8:9] offset:16
	global_store_dwordx4 v1, v[168:171], s[8:9] offset:2048
	global_store_dwordx4 v1, v[172:175], s[8:9] offset:2064
	s_add_u32 s8, s8, 0x1000
	s_addc_u32 s9, s9, 0
	s_waitcnt vmcnt(16)
; DI float shx(float v, int mask) { const int l = olane(); return __builtin_bit_cast(float, __builtin_amdgcn_ds_bpermute(((l ^ mask) & 63) << 2, __builtin_bit_cast(int, v))); }
; DI void row_phase(const bf16_t* msrc, const float* xsrc, float* xdst, const float* g_post, const float* g_next, bf16_t* hdst, const int gw) {
;     ...
;             for (int j = 0; j < 4; ++j) xv[r][j] = *(const f32x4*)(xsrc + (size_t)(rowb + r) * DM + lane * 4 + 256 * j);
;         if (msrc) {
; #pragma unroll
;             for (int r = 0; r < RB; ++r)
; #pragma unroll
;                 for (int j = 0; j < 4; ++j) { const u32x2 mw = *(const u32x2*)(msrc + (size_t)(rowb + r) * DM + lane * 4 + 256 * j);
;                     mv[r][j] = (f32x4){__uint_as_float(mw[0] << 16), __uint_as_float(mw[0] & 0xffff0000u), __uint_as_float(mw[1] << 16), __uint_as_float(mw[1] & 0xffff0000u)}; }
;             float ss[RB];
; #pragma unroll
;             for (int r = 0; r < RB; ++r) { ss[r] = 0.f;
; #pragma unroll
;                 for (int j = 0; j < 4; ++j) ss[r] += mv[r][j][0] * mv[r][j][0] + mv[r][j][1] * mv[r][j][1] + mv[r][j][2] * mv[r][j][2] + mv[r][j][3] * mv[r][j][3]; }
; #pragma unroll
;             for (int o = 32; o >= 1; o >>= 1)
; #pragma unroll
;                 for (int r = 0; r < RB; ++r) ss[r] += shx(ss[r], o);
; #pragma unroll
;             for (int j = 0; j < 4; ++j) { const f32x4 g = *(const f32x4*)(g_post + lane * 4 + 256 * j);
; #pragma unroll
;                 for (int r = 0; r < RB; ++r) { const float r1 = rsqrtf(ss[r] * (1.f / DM) + EPS); xv[r][j] = xv[r][j] + mv[r][j] * r1 * g; *(f32x4*)(xdst + (size_t)(rowb + r) * DM + lane * 4 + 256 * j) = xv[r][j]; } }
	v_lshlrev_b32_e32 v208, 16, v112
	v_and_b32_e32 v209, 0xffff0000, v112
	v_lshlrev_b32_e32 v210, 16, v113
	v_and_b32_e32 v211, 0xffff0000, v113
	v_lshlrev_b32_e32 v212, 16, v114
	v_and_b32_e32 v213, 0xffff0000, v114
	v_lshlrev_b32_e32 v214, 16, v115
	v_and_b32_e32 v215, 0xffff0000, v115
	v_lshlrev_b32_e32 v216, 16, v116
	v_and_b32_e32 v217, 0xffff0000, v116
	v_lshlrev_b32_e32 v218, 16, v117
	v_and_b32_e32 v219, 0xffff0000, v117
	v_lshlrev_b32_e32 v220, 16, v118
	v_and_b32_e32 v221, 0xffff0000, v118
	v_lshlrev_b32_e32 v222, 16, v119
	v_and_b32_e32 v223, 0xffff0000, v119
	v_mul_f32_e32 v224, v208, v208
	v_fmac_f32_e32 v224, v209, v209
	v_fmac_f32_e32 v224, v210, v210
	v_fmac_f32_e32 v224, v211, v211
	v_fmac_f32_e32 v224, v212, v212
	v_fmac_f32_e32 v224, v213, v213
	v_fmac_f32_e32 v224, v214, v214
	v_fmac_f32_e32 v224, v215, v215
	v_fmac_f32_e32 v224, v216, v216
	v_fmac_f32_e32 v224, v217, v217
	v_fmac_f32_e32 v224, v218, v218
	v_fmac_f32_e32 v224, v219, v219
	v_fmac_f32_e32 v224, v220, v220
	v_fmac_f32_e32 v224, v221, v221
	v_fmac_f32_e32 v224, v222, v222
	v_fmac_f32_e32 v224, v223, v223
	s_nop 1
	v_add_f32_dpp v224, v224, v224 quad_perm:[1,0,3,2] row_mask:0xf bank_mask:0xf
	s_nop 1
	v_add_f32_dpp v224, v224, v224 quad_perm:[2,3,0,1] row_mask:0xf bank_mask:0xf
	s_nop 1
	v_add_f32_dpp v224, v224, v224 row_ror:4 row_mask:0xf bank_mask:0xf
	s_nop 1
	v_add_f32_dpp v224, v224, v224 row_ror:8 row_mask:0xf bank_mask:0xf
	s_nop 1
	v_readlane_b32 s20, v224, 0
	v_readlane_b32 s21, v224, 16
	v_readlane_b32 s22, v224, 32
	v_readlane_b32 s23, v224, 48
	s_nop 1
	v_mov_b32_e32 v225, s20
	v_add_f32_e32 v225, s21, v225
	v_add_f32_e32 v225, s22, v225
	v_add_f32_e32 v225, s23, v225
	v_mov_b32_e32 v226, 0x358637bd
	v_fmac_f32_e32 v226, 0x3a800000, v225
	v_rsq_f32_e32 v226, v226
	s_nop 0
	v_mul_f32_e32 v208, v208, v226
	v_mul_f32_e32 v209, v209, v226
	v_mul_f32_e32 v210, v210, v226
	v_mul_f32_e32 v211, v211, v226
	v_mul_f32_e32 v212, v212, v226
	v_mul_f32_e32 v213, v213, v226
	v_mul_f32_e32 v214, v214, v226
	v_mul_f32_e32 v215, v215, v226
	v_mul_f32_e32 v216, v216, v226
	v_mul_f32_e32 v217, v217, v226
	v_mul_f32_e32 v218, v218, v226
	v_mul_f32_e32 v219, v219, v226
	v_mul_f32_e32 v220, v220, v226
	v_mul_f32_e32 v221, v221, v226
	v_mul_f32_e32 v222, v222, v226
	v_mul_f32_e32 v223, v223, v226
	v_fmac_f32_e32 v96, v208, v40
	v_fmac_f32_e32 v97, v209, v41
	v_fmac_f32_e32 v98, v210, v42
	v_fmac_f32_e32 v99, v211, v43
	v_fmac_f32_e32 v100, v212, v44
	v_fmac_f32_e32 v101, v213, v45
	v_fmac_f32_e32 v102, v214, v46
	v_fmac_f32_e32 v103, v215, v47
	v_fmac_f32_e32 v104, v216, v48
	v_fmac_f32_e32 v105, v217, v49
	v_fmac_f32_e32 v106, v218, v50
	v_fmac_f32_e32 v107, v219, v51
	v_fmac_f32_e32 v108, v220, v52
	v_fmac_f32_e32 v109, v221, v53
	v_fmac_f32_e32 v110, v222, v54
	v_fmac_f32_e32 v111, v223, v55
	v_lshlrev_b32_e32 v208, 16, v120
	v_and_b32_e32 v209, 0xffff0000, v120
	v_lshlrev_b32_e32 v210, 16, v121
	v_and_b32_e32 v211, 0xffff0000, v121
	v_lshlrev_b32_e32 v212, 16, v122
	v_and_b32_e32 v213, 0xffff0000, v122
	v_lshlrev_b32_e32 v214, 16, v123
	v_and_b32_e32 v215, 0xffff0000, v123
	v_lshlrev_b32_e32 v216, 16, v124
	v_and_b32_e32 v217, 0xffff0000, v124
	v_lshlrev_b32_e32 v218, 16, v125
	v_and_b32_e32 v219, 0xffff0000, v125
	v_lshlrev_b32_e32 v220, 16, v126
	v_and_b32_e32 v221, 0xffff0000, v126
	v_lshlrev_b32_e32 v222, 16, v127
	v_and_b32_e32 v223, 0xffff0000, v127
	v_mul_f32_e32 v224, v208, v208
	v_fmac_f32_e32 v224, v209, v209
	v_fmac_f32_e32 v224, v210, v210
	v_fmac_f32_e32 v224, v211, v211
	v_fmac_f32_e32 v224, v212, v212
	v_fmac_f32_e32 v224, v213, v213
	v_fmac_f32_e32 v224, v214, v214
	v_fmac_f32_e32 v224, v215, v215
	v_fmac_f32_e32 v224, v216, v216
	v_fmac_f32_e32 v224, v217, v217
	v_fmac_f32_e32 v224, v218, v218
	v_fmac_f32_e32 v224, v219, v219
	v_fmac_f32_e32 v224, v220, v220
	v_fmac_f32_e32 v224, v221, v221
	v_fmac_f32_e32 v224, v222, v222
	v_fmac_f32_e32 v224, v223, v223
	s_nop 1
	v_add_f32_dpp v224, v224, v224 quad_perm:[1,0,3,2] row_mask:0xf bank_mask:0xf
	s_nop 1
	v_add_f32_dpp v224, v224, v224 quad_perm:[2,3,0,1] row_mask:0xf bank_mask:0xf
	s_nop 1
	v_add_f32_dpp v224, v224, v224 row_ror:4 row_mask:0xf bank_mask:0xf
	s_nop 1
	v_add_f32_dpp v224, v224, v224 row_ror:8 row_mask:0xf bank_mask:0xf
	s_nop 1
	v_readlane_b32 s20, v224, 0
	v_readlane_b32 s21, v224, 16
	v_readlane_b32 s22, v224, 32
	v_readlane_b32 s23, v224, 48
	s_nop 1
	v_mov_b32_e32 v225, s20
	v_add_f32_e32 v225, s21, v225
	v_add_f32_e32 v225, s22, v225
	v_add_f32_e32 v225, s23, v225
	v_mov_b32_e32 v226, 0x358637bd
	v_fmac_f32_e32 v226, 0x3a800000, v225
	v_rsq_f32_e32 v226, v226
	s_nop 0
	v_mul_f32_e32 v208, v208, v226
	v_mul_f32_e32 v209, v209, v226
	v_mul_f32_e32 v210, v210, v226
	v_mul_f32_e32 v211, v211, v226
	v_mul_f32_e32 v212, v212, v226
	v_mul_f32_e32 v213, v213, v226
	v_mul_f32_e32 v214, v214, v226
	v_mul_f32_e32 v215, v215, v226
	v_mul_f32_e32 v216, v216, v226
	v_mul_f32_e32 v217, v217, v226
	v_mul_f32_e32 v218, v218, v226
	v_mul_f32_e32 v219, v219, v226
	v_mul_f32_e32 v220, v220, v226
	v_mul_f32_e32 v221, v221, v226
	v_mul_f32_e32 v222, v222, v226
	v_mul_f32_e32 v223, v223, v226
	v_fmac_f32_e32 v96, v208, v56
	v_fmac_f32_e32 v97, v209, v57
	v_fmac_f32_e32 v98, v210, v58
	v_fmac_f32_e32 v99, v211, v59
	v_fmac_f32_e32 v100, v212, v60
	v_fmac_f32_e32 v101, v213, v61
	v_fmac_f32_e32 v102, v214, v62
	v_fmac_f32_e32 v103, v215, v63
	v_fmac_f32_e32 v104, v216, v64
	v_fmac_f32_e32 v105, v217, v65
	v_fmac_f32_e32 v106, v218, v66
	v_fmac_f32_e32 v107, v219, v67
	v_fmac_f32_e32 v108, v220, v68
	v_fmac_f32_e32 v109, v221, v69
	v_fmac_f32_e32 v110, v222, v70
	v_fmac_f32_e32 v111, v223, v71
	global_store_dwordx4 v1, v[96:99], s[8:9] offset:0
	global_store_dwordx4 v1, v[100:103], s[8:9] offset:16
	global_store_dwordx4 v1, v[104:107], s[8:9] offset:2048
	global_store_dwordx4 v1, v[108:111], s[8:9] offset:2064
	s_add_u32 s8, s8, 0x1000
	s_addc_u32 s9, s9, 0
	s_waitcnt vmcnt(8)
; DI float shx(float v, int mask) { const int l = olane(); return __builtin_bit_cast(float, __builtin_amdgcn_ds_bpermute(((l ^ mask) & 63) << 2, __builtin_bit_cast(int, v))); }
; DI void row_phase(const bf16_t* msrc, const float* xsrc, float* xdst, const float* g_post, const float* g_next, bf16_t* hdst, const int gw) {
;     ...
;         if (msrc) {
; #pragma unroll
;             for (int r = 0; r < RB; ++r)
; #pragma unroll
;                 for (int j = 0; j < 4; ++j) { const u32x2 mw = *(const u32x2*)(msrc + (size_t)(rowb + r) * DM + lane * 4 + 256 * j);
;                     mv[r][j] = (f32x4){__uint_as_float(mw[0] << 16), __uint_as_float(mw[0] & 0xffff0000u), __uint_as_float(mw[1] << 16), __uint_as_float(mw[1] & 0xffff0000u)}; }
;             float ss[RB];
; #pragma unroll
;             for (int r = 0; r < RB; ++r) { ss[r] = 0.f;
; #pragma unroll
;                 for (int j = 0; j < 4; ++j) ss[r] += mv[r][j][0] * mv[r][j][0] + mv[r][j][1] * mv[r][j][1] + mv[r][j][2] * mv[r][j][2] + mv[r][j][3] * mv[r][j][3]; }
; #pragma unroll
;             for (int o = 32; o >= 1; o >>= 1)
; #pragma unroll
;                 for (int r = 0; r < RB; ++r) ss[r] += shx(ss[r], o);
; #pragma unroll
;             for (int j = 0; j < 4; ++j) { const f32x4 g = *(const f32x4*)(g_post + lane * 4 + 256 * j);
; #pragma unroll
;                 for (int r = 0; r < RB; ++r) { const float r1 = rsqrtf(ss[r] * (1.f / DM) + EPS); xv[r][j] = xv[r][j] + mv[r][j] * r1 * g; *(f32x4*)(xdst + (size_t)(rowb + r) * DM + lane * 4 + 256 * j) = xv[r][j]; } }
	v_lshlrev_b32_e32 v208, 16, v144
	v_and_b32_e32 v209, 0xffff0000, v144
	v_lshlrev_b32_e32 v210, 16, v145
	v_and_b32_e32 v211, 0xffff0000, v145
	v_lshlrev_b32_e32 v212, 16, v146
	v_and_b32_e32 v213, 0xffff0000, v146
	v_lshlrev_b32_e32 v214, 16, v147
	v_and_b32_e32 v215, 0xffff0000, v147
	v_lshlrev_b32_e32 v216, 16, v148
	v_and_b32_e32 v217, 0xffff0000, v148
	v_lshlrev_b32_e32 v218, 16, v149
	v_and_b32_e32 v219, 0xffff0000, v149
	v_lshlrev_b32_e32 v220, 16, v150
	v_and_b32_e32 v221, 0xffff0000, v150
	v_lshlrev_b32_e32 v222, 16, v151
	v_and_b32_e32 v223, 0xffff0000, v151
	v_mul_f32_e32 v224, v208, v208
	v_fmac_f32_e32 v224, v209, v209
	v_fmac_f32_e32 v224, v210, v210
	v_fmac_f32_e32 v224, v211, v211
	v_fmac_f32_e32 v224, v212, v212
	v_fmac_f32_e32 v224, v213, v213
	v_fmac_f32_e32 v224, v214, v214
	v_fmac_f32_e32 v224, v215, v215
	v_fmac_f32_e32 v224, v216, v216
	v_fmac_f32_e32 v224, v217, v217
	v_fmac_f32_e32 v224, v218, v218
	v_fmac_f32_e32 v224, v219, v219
	v_fmac_f32_e32 v224, v220, v220
	v_fmac_f32_e32 v224, v221, v221
	v_fmac_f32_e32 v224, v222, v222
	v_fmac_f32_e32 v224, v223, v223
	s_nop 1
	v_add_f32_dpp v224, v224, v224 quad_perm:[1,0,3,2] row_mask:0xf bank_mask:0xf
	s_nop 1
	v_add_f32_dpp v224, v224, v224 quad_perm:[2,3,0,1] row_mask:0xf bank_mask:0xf
	s_nop 1
	v_add_f32_dpp v224, v224, v224 row_ror:4 row_mask:0xf bank_mask:0xf
	s_nop 1
	v_add_f32_dpp v224, v224, v224 row_ror:8 row_mask:0xf bank_mask:0xf
	s_nop 1
	v_readlane_b32 s20, v224, 0
	v_readlane_b32 s21, v224, 16
	v_readlane_b32 s22, v224, 32
	v_readlane_b32 s23, v224, 48
	s_nop 1
	v_mov_b32_e32 v225, s20
	v_add_f32_e32 v225, s21, v225
	v_add_f32_e32 v225, s22, v225
	v_add_f32_e32 v225, s23, v225
	v_mov_b32_e32 v226, 0x358637bd
	v_fmac_f32_e32 v226, 0x3a800000, v225
	v_rsq_f32_e32 v226, v226
	s_nop 0
	v_mul_f32_e32 v208, v208, v226
	v_mul_f32_e32 v209, v209, v226
	v_mul_f32_e32 v210, v210, v226
	v_mul_f32_e32 v211, v211, v226
	v_mul_f32_e32 v212, v212, v226
	v_mul_f32_e32 v213, v213, v226
	v_mul_f32_e32 v214, v214, v226
	v_mul_f32_e32 v215, v215, v226
	v_mul_f32_e32 v216, v216, v226
	v_mul_f32_e32 v217, v217, v226
	v_mul_f32_e32 v218, v218, v226
	v_mul_f32_e32 v219, v219, v226
	v_mul_f32_e32 v220, v220, v226
	v_mul_f32_e32 v221, v221, v226
	v_mul_f32_e32 v222, v222, v226
	v_mul_f32_e32 v223, v223, v226
	v_fmac_f32_e32 v128, v208, v40
	v_fmac_f32_e32 v129, v209, v41
	v_fmac_f32_e32 v130, v210, v42
	v_fmac_f32_e32 v131, v211, v43
	v_fmac_f32_e32 v132, v212, v44
	v_fmac_f32_e32 v133, v213, v45
	v_fmac_f32_e32 v134, v214, v46
	v_fmac_f32_e32 v135, v215, v47
	v_fmac_f32_e32 v136, v216, v48
	v_fmac_f32_e32 v137, v217, v49
	v_fmac_f32_e32 v138, v218, v50
	v_fmac_f32_e32 v139, v219, v51
	v_fmac_f32_e32 v140, v220, v52
	v_fmac_f32_e32 v141, v221, v53
	v_fmac_f32_e32 v142, v222, v54
	v_fmac_f32_e32 v143, v223, v55
	v_lshlrev_b32_e32 v208, 16, v152
	v_and_b32_e32 v209, 0xffff0000, v152
	v_lshlrev_b32_e32 v210, 16, v153
	v_and_b32_e32 v211, 0xffff0000, v153
	v_lshlrev_b32_e32 v212, 16, v154
	v_and_b32_e32 v213, 0xffff0000, v154
	v_lshlrev_b32_e32 v214, 16, v155
	v_and_b32_e32 v215, 0xffff0000, v155
	v_lshlrev_b32_e32 v216, 16, v156
	v_and_b32_e32 v217, 0xffff0000, v156
	v_lshlrev_b32_e32 v218, 16, v157
	v_and_b32_e32 v219, 0xffff0000, v157
	v_lshlrev_b32_e32 v220, 16, v158
	v_and_b32_e32 v221, 0xffff0000, v158
	v_lshlrev_b32_e32 v222, 16, v159
	v_and_b32_e32 v223, 0xffff0000, v159
	v_mul_f32_e32 v224, v208, v208
	v_fmac_f32_e32 v224, v209, v209
	v_fmac_f32_e32 v224, v210, v210
	v_fmac_f32_e32 v224, v211, v211
	v_fmac_f32_e32 v224, v212, v212
	v_fmac_f32_e32 v224, v213, v213
	v_fmac_f32_e32 v224, v214, v214
	v_fmac_f32_e32 v224, v215, v215
	v_fmac_f32_e32 v224, v216, v216
	v_fmac_f32_e32 v224, v217, v217
	v_fmac_f32_e32 v224, v218, v218
	v_fmac_f32_e32 v224, v219, v219
	v_fmac_f32_e32 v224, v220, v220
	v_fmac_f32_e32 v224, v221, v221
	v_fmac_f32_e32 v224, v222, v222
	v_fmac_f32_e32 v224, v223, v223
	s_nop 1
	v_add_f32_dpp v224, v224, v224 quad_perm:[1,0,3,2] row_mask:0xf bank_mask:0xf
	s_nop 1
	v_add_f32_dpp v224, v224, v224 quad_perm:[2,3,0,1] row_mask:0xf bank_mask:0xf
	s_nop 1
	v_add_f32_dpp v224, v224, v224 row_ror:4 row_mask:0xf bank_mask:0xf
	s_nop 1
	v_add_f32_dpp v224, v224, v224 row_ror:8 row_mask:0xf bank_mask:0xf
	s_nop 1
	v_readlane_b32 s20, v224, 0
	v_readlane_b32 s21, v224, 16
	v_readlane_b32 s22, v224, 32
	v_readlane_b32 s23, v224, 48
	s_nop 1
	v_mov_b32_e32 v225, s20
	v_add_f32_e32 v225, s21, v225
	v_add_f32_e32 v225, s22, v225
	v_add_f32_e32 v225, s23, v225
	v_mov_b32_e32 v226, 0x358637bd
	v_fmac_f32_e32 v226, 0x3a800000, v225
	v_rsq_f32_e32 v226, v226
	s_nop 0
	v_mul_f32_e32 v208, v208, v226
	v_mul_f32_e32 v209, v209, v226
	v_mul_f32_e32 v210, v210, v226
	v_mul_f32_e32 v211, v211, v226
	v_mul_f32_e32 v212, v212, v226
	v_mul_f32_e32 v213, v213, v226
	v_mul_f32_e32 v214, v214, v226
	v_mul_f32_e32 v215, v215, v226
	v_mul_f32_e32 v216, v216, v226
	v_mul_f32_e32 v217, v217, v226
	v_mul_f32_e32 v218, v218, v226
	v_mul_f32_e32 v219, v219, v226
	v_mul_f32_e32 v220, v220, v226
	v_mul_f32_e32 v221, v221, v226
	v_mul_f32_e32 v222, v222, v226
	v_mul_f32_e32 v223, v223, v226
	v_fmac_f32_e32 v128, v208, v56
	v_fmac_f32_e32 v129, v209, v57
	v_fmac_f32_e32 v130, v210, v58
	v_fmac_f32_e32 v131, v211, v59
	v_fmac_f32_e32 v132, v212, v60
	v_fmac_f32_e32 v133, v213, v61
	v_fmac_f32_e32 v134, v214, v62
	v_fmac_f32_e32 v135, v215, v63
	v_fmac_f32_e32 v136, v216, v64
	v_fmac_f32_e32 v137, v217, v65
	v_fmac_f32_e32 v138, v218, v66
	v_fmac_f32_e32 v139, v219, v67
	v_fmac_f32_e32 v140, v220, v68
	v_fmac_f32_e32 v141, v221, v69
	v_fmac_f32_e32 v142, v222, v70
	v_fmac_f32_e32 v143, v223, v71
	global_store_dwordx4 v1, v[128:131], s[8:9] offset:0
	global_store_dwordx4 v1, v[132:135], s[8:9] offset:16
	global_store_dwordx4 v1, v[136:139], s[8:9] offset:2048
	global_store_dwordx4 v1, v[140:143], s[8:9] offset:2064
	s_add_u32 s8, s8, 0x1000
	s_addc_u32 s9, s9, 0
	v_readlane_b32 s4, v3, 0
	v_readlane_b32 s5, v3, 1
	v_readlane_b32 s6, v3, 2
	v_readlane_b32 s7, v3, 3
	v_readlane_b32 s8, v3, 4
	v_readlane_b32 s9, v3, 5
	v_readlane_b32 s10, v3, 6
	v_readlane_b32 s11, v3, 7
	v_readlane_b32 s12, v3, 8
	v_readlane_b32 s13, v3, 9
	v_readlane_b32 s14, v3, 10
	v_readlane_b32 s15, v3, 11
	v_readlane_b32 s16, v3, 12
	v_readlane_b32 s17, v3, 13
	v_readlane_b32 s18, v3, 14
	v_readlane_b32 s19, v3, 15
	v_readlane_b32 s20, v3, 16
	v_readlane_b32 s21, v3, 17
	v_readlane_b32 s22, v3, 18
	v_readlane_b32 s23, v3, 19
	v_readlane_b32 s24, v3, 20
	v_readlane_b32 s25, v3, 21
	s_mov_b32 s6, 0x358637bd
	s_mov_b64 s[34:35], 0
	s_branch .LBB0_74
.LBB0_74:
	s_branch .LBB0_26
.LBB0_75:
	s_branch .Lrow_r1
.LBB0_79:
	s_mov_b64 s[4:5], 0

; DI bf16_t f2bf(float a) { return (bf16_t)(pk_bf16(a, 0.f) & 0xffffu); }
; template <int EPI>
; DI void gemm_phase(const bf16_t* __restrict__ A, const bf16_t* __restrict__ Bt, const int K, const int N, const Params& p, const int layer_j, char* lds) {
;     ...
;         if (EPI == EPI_F32) {
;             bf16_t* T = (bf16_t*)(ws + OFF_T) + (size_t)row0 * DM + col0 + fr;
; #pragma unroll
;             for (int ai = 0; ai < 2; ++ai)
; #pragma unroll
;                 for (int m = 0; m < 4; ++m)
; #pragma unroll
;                     for (int j = 0; j < 4; ++j)
; #pragma unroll
;                         for (int bj = 0; bj < 2; ++bj)
; #pragma unroll
;                             for (int n = 0; n < 2; ++n) T[(size_t)(ai * 128 + m * 16 + j) * DM + bj * 32 + n * 16] = f2bf(acc[ai][bj][m][n][j]);
.LBB0_109:
	v_mbcnt_lo_u32_b32 v152, -1, 0
	v_mbcnt_hi_u32_b32 v152, -1, v152
	s_mul_i32 s16, s71, 34
	s_add_i32 s16, s16, 0x20100
	v_and_b32_e32 v153, 15, v152
	v_lshrrev_b32_e32 v154, 4, v152
	v_mul_u32_u24_e32 v153, 136, v153
	v_lshl_add_u32 v153, v154, 3, v153
	v_add_u32_e32 v153, s16, v153
	v_lshrrev_b32_e32 v155, 3, v152
	v_and_b32_e32 v156, 7, v152
	v_mul_u32_u24_e32 v154, 136, v155
	v_lshl_add_u32 v154, v156, 4, v154
	v_add_u32_e32 v154, s16, v154
	v_readlane_b32 s16, v254, 7
	v_readlane_b32 s17, v254, 14
	v_lshlrev_b32_e32 v156, 4, v156
	v_add_u32_e32 v155, s16, v155
	v_lshl_add_u32 v155, v155, 11, v156
	s_lshl_b32 s17, s17, 1
	v_add_u32_e32 v155, s17, v155
	v_add_u32_e32 v156, 0x4000, v155
	s_lshl_b32 s16, s34, 19
	s_lshl_b32 s17, s31, 9
	s_add_u32 s16, s16, s17
	s_add_u32 s16, s8, s16
	s_addc_u32 s17, s9, 0
	s_cmp_eq_u32 s24, 44
	s_cselect_b32 vcc_lo, 0x2000000, 0
	s_add_u32 s16, s16, vcc_lo
	s_addc_u32 s17, s17, 0
	v_cvt_pk_bf16_f32 v160, v126, v127
	v_cvt_pk_bf16_f32 v161, v128, v129
	v_cvt_pk_bf16_f32 v162, v122, v123
	v_cvt_pk_bf16_f32 v163, v124, v125
	v_cvt_pk_bf16_f32 v164, v118, v119
	v_cvt_pk_bf16_f32 v165, v120, v121
	v_cvt_pk_bf16_f32 v166, v114, v115
	v_cvt_pk_bf16_f32 v167, v116, v117
	ds_write_b64 v153, v[160:161]
	ds_write_b64 v153, v[162:163] offset:32
	ds_write_b64 v153, v[164:165] offset:64
	ds_write_b64 v153, v[166:167] offset:96
	ds_read2_b64 v[168:171], v154 offset1:1
	ds_read2_b64 v[172:175], v154 offset0:136 offset1:137
	s_waitcnt lgkmcnt(0)
	global_store_dwordx4 v155, v[168:171], s[16:17]
	global_store_dwordx4 v156, v[172:175], s[16:17]
	v_cvt_pk_bf16_f32 v160, v110, v111
	v_cvt_pk_bf16_f32 v161, v112, v113
	v_cvt_pk_bf16_f32 v162, v106, v107
	v_cvt_pk_bf16_f32 v163, v108, v109
	v_cvt_pk_bf16_f32 v164, v102, v103
	v_cvt_pk_bf16_f32 v165, v104, v105
	v_cvt_pk_bf16_f32 v166, v98, v99
	v_cvt_pk_bf16_f32 v167, v100, v101
	ds_write_b64 v153, v[160:161]
	ds_write_b64 v153, v[162:163] offset:32
	ds_write_b64 v153, v[164:165] offset:64
	ds_write_b64 v153, v[166:167] offset:96
	ds_read2_b64 v[168:171], v154 offset1:1
	ds_read2_b64 v[172:175], v154 offset0:136 offset1:137
	v_add_u32_e32 v157, 0x8000, v155
	v_add_u32_e32 v158, 0x8000, v156
	s_waitcnt lgkmcnt(0)
	global_store_dwordx4 v157, v[168:171], s[16:17]
	global_store_dwordx4 v158, v[172:175], s[16:17]
	v_cvt_pk_bf16_f32 v160, v94, v95
	v_cvt_pk_bf16_f32 v161, v96, v97
	v_cvt_pk_bf16_f32 v162, v90, v91
	v_cvt_pk_bf16_f32 v163, v92, v93
	v_cvt_pk_bf16_f32 v164, v86, v87
	v_cvt_pk_bf16_f32 v165, v88, v89
	v_cvt_pk_bf16_f32 v166, v82, v83
	v_cvt_pk_bf16_f32 v167, v84, v85
	ds_write_b64 v153, v[160:161]
	ds_write_b64 v153, v[162:163] offset:32
	ds_write_b64 v153, v[164:165] offset:64
	ds_write_b64 v153, v[166:167] offset:96
	ds_read2_b64 v[168:171], v154 offset1:1
	ds_read2_b64 v[172:175], v154 offset0:136 offset1:137
	v_add_u32_e32 v157, 0x10000, v155
	v_add_u32_e32 v158, 0x10000, v156
	s_waitcnt lgkmcnt(0)
	global_store_dwordx4 v157, v[168:171], s[16:17]
	global_store_dwordx4 v158, v[172:175], s[16:17]
	v_cvt_pk_bf16_f32 v160, v78, v79
	v_cvt_pk_bf16_f32 v161, v80, v81
	v_cvt_pk_bf16_f32 v162, v74, v75
	v_cvt_pk_bf16_f32 v163, v76, v77
	v_cvt_pk_bf16_f32 v164, v70, v71
	v_cvt_pk_bf16_f32 v165, v72, v73
	v_cvt_pk_bf16_f32 v166, v66, v67
	v_cvt_pk_bf16_f32 v167, v68, v69
	ds_write_b64 v153, v[160:161]
	ds_write_b64 v153, v[162:163] offset:32
	ds_write_b64 v153, v[164:165] offset:64
	ds_write_b64 v153, v[166:167] offset:96
	ds_read2_b64 v[168:171], v154 offset1:1
	ds_read2_b64 v[172:175], v154 offset0:136 offset1:137
	v_add_u32_e32 v157, 0x18000, v155
	v_add_u32_e32 v158, 0x18000, v156
	s_waitcnt lgkmcnt(0)
	global_store_dwordx4 v157, v[168:171], s[16:17]
	global_store_dwordx4 v158, v[172:175], s[16:17]
	v_cvt_pk_bf16_f32 v160, v62, v63
	v_cvt_pk_bf16_f32 v161, v64, v65
	v_cvt_pk_bf16_f32 v162, v58, v59
	v_cvt_pk_bf16_f32 v163, v60, v61
	v_cvt_pk_bf16_f32 v164, v46, v47
	v_cvt_pk_bf16_f32 v165, v48, v49
	v_cvt_pk_bf16_f32 v166, v42, v43
	v_cvt_pk_bf16_f32 v167, v44, v45
	ds_write_b64 v153, v[160:161]
	ds_write_b64 v153, v[162:163] offset:32
	ds_write_b64 v153, v[164:165] offset:64
	ds_write_b64 v153, v[166:167] offset:96
	ds_read2_b64 v[168:171], v154 offset1:1
	ds_read2_b64 v[172:175], v154 offset0:136 offset1:137
	v_add_u32_e32 v157, 0x40000, v155
	v_add_u32_e32 v158, 0x40000, v156
	s_waitcnt lgkmcnt(0)
	global_store_dwordx4 v157, v[168:171], s[16:17]
	global_store_dwordx4 v158, v[172:175], s[16:17]
	v_cvt_pk_bf16_f32 v160, v38, v39
	v_cvt_pk_bf16_f32 v161, v40, v41
	v_cvt_pk_bf16_f32 v162, v24, v25
	v_cvt_pk_bf16_f32 v163, v26, v27
	v_cvt_pk_bf16_f32 v164, v20, v21
	v_cvt_pk_bf16_f32 v165, v22, v23
	v_cvt_pk_bf16_f32 v166, v16, v17
	v_cvt_pk_bf16_f32 v167, v18, v19
	ds_write_b64 v153, v[160:161]
	ds_write_b64 v153, v[162:163] offset:32
	ds_write_b64 v153, v[164:165] offset:64
	ds_write_b64 v153, v[166:167] offset:96
	ds_read2_b64 v[168:171], v154 offset1:1
	ds_read2_b64 v[172:175], v154 offset0:136 offset1:137
	v_add_u32_e32 v157, 0x48000, v155
	v_add_u32_e32 v158, 0x48000, v156
	s_waitcnt lgkmcnt(0)
	global_store_dwordx4 v157, v[168:171], s[16:17]
	global_store_dwordx4 v158, v[172:175], s[16:17]
	v_cvt_pk_bf16_f32 v160, v12, v13
	v_cvt_pk_bf16_f32 v161, v14, v15
	v_cvt_pk_bf16_f32 v162, v8, v9
	v_cvt_pk_bf16_f32 v163, v10, v11
	v_cvt_pk_bf16_f32 v164, v50, v51
	v_cvt_pk_bf16_f32 v165, v52, v53
	v_cvt_pk_bf16_f32 v166, v54, v55
	v_cvt_pk_bf16_f32 v167, v56, v57
	ds_write_b64 v153, v[160:161]
	ds_write_b64 v153, v[162:163] offset:32
	ds_write_b64 v153, v[164:165] offset:64
	ds_write_b64 v153, v[166:167] offset:96
	ds_read2_b64 v[168:171], v154 offset1:1
	ds_read2_b64 v[172:175], v154 offset0:136 offset1:137
	v_add_u32_e32 v157, 0x50000, v155
	v_add_u32_e32 v158, 0x50000, v156
	s_waitcnt lgkmcnt(0)
	global_store_dwordx4 v157, v[168:171], s[16:17]
	global_store_dwordx4 v158, v[172:175], s[16:17]
	v_cvt_pk_bf16_f32 v160, v4, v5
	v_cvt_pk_bf16_f32 v161, v6, v7
	v_cvt_pk_bf16_f32 v162, v0, v1
	v_cvt_pk_bf16_f32 v163, v2, v3
	v_cvt_pk_bf16_f32 v164, v28, v29
	v_cvt_pk_bf16_f32 v165, v30, v31
	v_cvt_pk_bf16_f32 v166, v34, v35
	v_cvt_pk_bf16_f32 v167, v36, v37
	ds_write_b64 v153, v[160:161]
	ds_write_b64 v153, v[162:163] offset:32
	ds_write_b64 v153, v[164:165] offset:64
	ds_write_b64 v153, v[166:167] offset:96
	ds_read2_b64 v[168:171], v154 offset1:1
	ds_read2_b64 v[172:175], v154 offset0:136 offset1:137
	v_add_u32_e32 v157, 0x58000, v155
	v_add_u32_e32 v158, 0x58000, v156
	s_waitcnt lgkmcnt(0)
	global_store_dwordx4 v157, v[168:171], s[16:17]
	global_store_dwordx4 v158, v[172:175], s[16:17]
	s_andn2_b64 vcc, exec, s[10:11]
	s_mov_b64 s[10:11], -1
	s_mov_b32 s39, 0x2e8ba2e9
	s_cbranch_vccnz .LBB0_98
	s_and_b64 vcc, exec, s[4:5]
	s_cbranch_vccnz .LBB0_97
	s_barrier
	s_branch .LBB0_97

; DI bf16_t f2bf(float a) { return (bf16_t)(pk_bf16(a, 0.f) & 0xffffu); }
; DI float silu_f(float x) { return x * __builtin_amdgcn_rcpf(1.f + __expf(-x)); }
; template <int EPI>
; DI void gemm_phase(const bf16_t* __restrict__ A, const bf16_t* __restrict__ Bt, const int K, const int N, const Params& p, const int layer_j, char* lds) {
;     ...
;             } else if (region == 1) {
;                 float* lf = (float*)(ws + OFF_T) + (size_t)row0 * DM + (col0 - 1024) + fr;
;                 bf16_t* dst = PROJ + (size_t)row0 * ATT_IN + col0 + fr;
; #pragma unroll
;                 for (int bj = 0; bj < 2; ++bj)
; #pragma unroll
;                     for (int n = 0; n < 2; ++n) {
;                         float lb = 0.f;
;                         if (layer_j == 1) { const float a0 = p.rec_lb[col0 - 1024 + bj * 32 + n * 16 + fr], a1 = p.rec_lb[DM + col0 - 1024 + bj * 32 + n * 16 + fr]; lb = 1.f / (1.f + __expf(a0 - a1)); }
; #pragma unroll
;                         for (int ai = 0; ai < 2; ++ai)
; #pragma unroll
;                             for (int m = 0; m < 4; ++m)
; #pragma unroll
;                                 for (int j = 0; j < 4; ++j) {
;                                     const float sg = __builtin_amdgcn_rcpf(1.f + __expf(-acc[ai][bj][m][n][j])); const float fg = lb + (1.f - lb) * sg;
;                                     lf[(size_t)(ai * 128 + m * 16 + j) * DM + bj * 32 + n * 16] = __logf(fg);
;                                     dst[(size_t)(ai * 128 + m * 16 + j) * ATT_IN + bj * 32 + n * 16] = f2bf(1.f - fg);
;                                     if (j == 3) __builtin_amdgcn_sched_barrier(0); } }
;             } else {
;                 const int dc0 = (region == 0) ? col0 : (col0 - 3072 + 2048);
;                 const float sc = (region == 0) ? 0.08838834764831845f : 1.0f;
;                 bf16_t* dst = PROJ + (size_t)row0 * ATT_IN + dc0 + fr;
; #pragma unroll
;                 for (int ai = 0; ai < 2; ++ai)
; #pragma unroll
;                     for (int m = 0; m < 4; ++m)
; #pragma unroll
;                         for (int j = 0; j < 4; ++j)
; #pragma unroll
;                             for (int bj = 0; bj < 2; ++bj)
; #pragma unroll
;                                 for (int n = 0; n < 2; ++n) dst[(size_t)(ai * 128 + m * 16 + j) * ATT_IN + bj * 32 + n * 16] = f2bf(silu_f(acc[ai][bj][m][n][j]) * sc);
;             }
.LBB0_349:
	s_andn2_b64 vcc, exec, s[18:19]
	s_mov_b64 s[4:5], -1
	s_cbranch_vccnz .LBB0_330
	s_branch .LBB0_360
.LBB0_351:
	v_cndmask_b32_e64 v16, 0, 1, s[14:15]
	v_or_b32_e32 v74, s28, v130
	v_mov_b32_e32 v18, 0
	v_cmp_ne_u32_e64 s[4:5], 1, v16
	s_andn2_b64 vcc, exec, s[14:15]
	v_mov_b32_e32 v40, 0
	s_cbranch_vccnz .LBB0_353
	v_mov_b32_e32 v131, v33
	s_ashr_i32 s29, s28, 31
	v_lshl_add_u64 v[16:17], v[130:131], 0, s[28:29]
	v_lshl_add_u64 v[16:17], v[16:17], 2, s[54:55]
	v_mov_b32_e32 v75, v33
	v_lshl_add_u64 v[38:39], v[74:75], 2, s[54:55]
	global_load_dword v16, v[16:17], off offset:-4096
	s_nop 0
	global_load_dword v17, v[38:39], off
	s_waitcnt vmcnt(0)
	v_sub_f32_e32 v16, v16, v17
	v_mul_f32_e32 v16, 0x3fb8aa3b, v16
	v_exp_f32_e32 v16, v16
	s_nop 0
	v_add_f32_e32 v16, 1.0, v16
	v_div_scale_f32 v17, s[8:9], v16, v16, 1.0
	v_rcp_f32_e32 v32, v17
	v_div_scale_f32 v38, vcc, 1.0, v16, 1.0
	v_fma_f32 v39, -v17, v32, 1.0
	v_fmac_f32_e32 v32, v39, v32
	v_mul_f32_e32 v39, v38, v32
	v_fma_f32 v40, -v17, v39, v38
	v_fmac_f32_e32 v39, v40, v32
	v_fma_f32 v17, -v17, v39, v38
	v_div_fmas_f32 v17, v17, v32, v39
	v_div_fixup_f32 v40, v17, v16, 1.0

; DI bf16_t f2bf(float a) { return (bf16_t)(pk_bf16(a, 0.f) & 0xffffu); }
; template <int EPI>
; DI void gemm_phase(const bf16_t* __restrict__ A, const bf16_t* __restrict__ Bt, const int K, const int N, const Params& p, const int layer_j, char* lds) {
;     ...
;         } else if (EPI == EPI_ATT_IN) {
;             bf16_t* PROJ = (bf16_t*)(ws + OFF_P);
;             bf16_t* VT = PROJ + (size_t)M_TOK * ATT_IN;
;             const int region = col0 >> 9;
;             if (region == 2 || region == 5) {
;                 const int vc0 = (region == 2 ? col0 - 1024 : 512 + col0 - 2560);
;                 const int b = row0 >> 11, t0 = row0 & 2047;
;                 bf16_t* dst = VT + ((size_t)(b * 1024 + vc0 + fr)) * SEQ + t0;
; #pragma unroll
;                 for (int bj = 0; bj < 2; ++bj)
; #pragma unroll
;                     for (int n = 0; n < 2; ++n)
; #pragma unroll
;                         for (int ai = 0; ai < 2; ++ai)
; #pragma unroll
;                             for (int m = 0; m < 4; ++m) { u32x2 o; o[0] = pk_bf16(acc[ai][bj][m][n][0], acc[ai][bj][m][n][1]); o[1] = pk_bf16(acc[ai][bj][m][n][2], acc[ai][bj][m][n][3]);
;                                 *(u32x2*)(dst + (size_t)(bj * 32 + n * 16) * SEQ + ai * 128 + m * 16) = o; }
;             } else {
;                 const float sc = (region == 0 || region == 3) ? 0.125f * LOG2E : 1.0f;
;                 const float* cb = (const float*)(ws + OFF_ROPE) + (row0 & 2047) * 32 + fr;
;                 bf16_t* dst = PROJ + (size_t)row0 * ATT_IN + col0 + fr;
; #pragma unroll
;                 for (int ai = 0; ai < 2; ++ai)
; #pragma unroll
;                     for (int m = 0; m < 4; ++m)
; #pragma unroll
;                         for (int j = 0; j < 4; ++j)
; #pragma unroll
;                             for (int n = 0; n < 2; ++n) {
;                                 const int ro = ai * 128 + m * 16 + j;
;                                 const float c = cb[ro * 32 + n * 16], sn = cb[2048 * 32 + ro * 32 + n * 16];
;                                 const float x1 = acc[ai][0][m][n][j], x2 = acc[ai][1][m][n][j];
;                                 dst[(size_t)ro * ATT_IN + n * 16] = f2bf((x1 * c - x2 * sn) * sc); dst[(size_t)ro * ATT_IN + 32 + n * 16] = f2bf((x2 * c + x1 * sn) * sc);
;                                 if (n == 1 && (j & 1)) __builtin_amdgcn_sched_barrier(0); }
;             }
.LBB0_377:
	s_ashr_i32 s15, s24, 1
	s_mov_b32 s86, 0x3a800000
	s_movk_i32 s67, 0x1000
	s_movk_i32 s87, 0x3fff
	s_cmp_eq_u32 s15, 2
	s_cbranch_scc1 .Latt_epi_tr
	s_cmp_eq_u32 s15, 5
	s_cbranch_scc1 .Latt_epi_tr
	s_branch .Latt_epi_rope
.LBB0_385:
	s_andn2_b64 vcc, exec, s[16:17]
	s_mov_b64 s[16:17], -1
	s_cbranch_vccnz .LBB0_370
	s_branch .LBB0_388
.LBB0_388:
	s_and_b64 vcc, exec, s[4:5]
	s_cbranch_vccnz .LBB0_369
	s_barrier
	s_branch .LBB0_369
